# added: residual-add GEMM epilogues issue both halves of the residual tile loads up front (second half no longer queued behind the first half's stores)
# speedup vs baseline: 1.0059x; 1.0059x over previous
; #define PG8_STAGE(bufoff, gbase, voff) do { _Pragma("unroll") for (int _i = 0; _i < 2; ++_i) \
;         __builtin_amdgcn_global_load_lds((const unsigned*)((const char*)(gbase) + (voff)[_i]), (LAS unsigned*)(lds + (bufoff) + ldsw + _i * 8192), 16, 0, 0); } while (0)
; #define PG8_LDA(dst, b, h) do { _Pragma("unroll") for (int m = 0; m < 4; ++m) _Pragma("unroll") for (int k = 0; k < 2; ++k) dst[m][k] = *(const LAS bf16x8*)(lds + PG8_SA(b, h) + aoff + m * 2048 + k * 1024); } while (0)
; #define PG8_LDB(dst, b, h) do { _Pragma("unroll") for (int n = 0; n < 2; ++n) _Pragma("unroll") for (int k = 0; k < 2; ++k) dst[n][k] = *(const LAS bf16x8*)(lds + PG8_SB(b, h) + boff + n * 2048 + k * 1024); } while (0)
; #define PG8_MMA(ai, bj, At, Bt) do { __builtin_amdgcn_s_setprio(1); _Pragma("unroll") for (int m = 0; m < 4; ++m) _Pragma("unroll") for (int n = 0; n < 2; ++n) _Pragma("unroll") for (int k = 0; k < 2; ++k) \
;         acc[ai][bj][m][n] = __builtin_amdgcn_mfma_f32_16x16x32_bf16(Bt[n][k], At[m][k], acc[ai][bj][m][n], 0, 0, 0); __builtin_amdgcn_s_setprio(0); } while (0)
; #define PG8_WAIT_L(n) asm volatile("s_waitcnt lgkmcnt(" #n ")" ::: "memory")
; #define PG8_BAR __builtin_amdgcn_s_barrier()
; #define PG8_SCHED __builtin_amdgcn_sched_barrier(0)
; template <class Epi>
; __device__ __forceinline__ void gemm_phase(LAS unsigned char* lds, const Gemm g, const StaticOrder& S, const Epi& E) {
;     ...
;             PG8_LDB(B0, 0, 0); PG8_SCHED; PG8_LDA(At, 0, 0); PG8_STAGE(PG8_SA(1, 1), a1 + hstepA, voffA);
;             PG8_WAIT_L(8); PG8_BAR; PG8_WAIT_L(0); PG8_MMA(0, 0, At, B0); PG8_BAR; PG8_SCHED;
;             PG8_LDB(B1, 0, 1); PG8_STAGE(PG8_SB(0, 0), b2, voffB);
;             PG8_BAR; PG8_WAIT_L(0); PG8_MMA(0, 1, At, B1); PG8_BAR;
;             PG8_LDA(At, 0, 1); PG8_STAGE(PG8_SA(0, 0), a2, voffA);
;             PG8_BAR; PG8_WAIT_L(0); PG8_MMA(1, 0, At, B0); PG8_BAR; PG8_SCHED;
.LBB0_684:
	ds_read_b128 v[128:131], v191
	ds_read_b128 v[132:135], v191 offset:1024
	ds_read_b128 v[136:139], v191 offset:2048
	ds_read_b128 v[140:143], v191 offset:3072
	s_add_u32 s22, s4, 0xffec0080
	s_addc_u32 s23, s5, -1
	s_cmp_eq_u32 s48, 28
	s_cselect_b32 s25, s19, s23
	s_cselect_b32 s24, s18, s22
	s_cselect_b32 s23, s17, s47
	s_cselect_b32 s22, s45, s46
	v_lshl_add_u64 v[186:187], s[4:5], 0, v[162:163]
	s_add_i32 m0, s11, 0xc000
	ds_read_b128 v[144:147], v192
	ds_read_b128 v[148:151], v192 offset:1024
	ds_read_b128 v[170:173], v192 offset:2048
	ds_read_b128 v[174:177], v192 offset:3072
	ds_read_b128 v[178:181], v192 offset:4096
	ds_read_b128 v[182:185], v192 offset:5120
	ds_read_b128 v[196:199], v192 offset:6144
	ds_read_b128 v[200:203], v192 offset:7168
	global_load_lds_dwordx4 v[186:187], off
	v_lshl_add_u64 v[186:187], s[4:5], 0, v[164:165]
	s_add_i32 m0, s11, 0xe000
	s_nop 0
	global_load_lds_dwordx4 v[186:187], off
	s_waitcnt lgkmcnt(8)
	s_barrier
	s_waitcnt lgkmcnt(0)
	s_setprio 1
	s_waitcnt lgkmcnt(0)
	v_mfma_f32_16x16x32_bf16 v[124:127], v[128:131], v[144:147], v[124:127]
	v_mfma_f32_16x16x32_bf16 v[120:123], v[136:139], v[144:147], v[120:123]
	v_mfma_f32_16x16x32_bf16 v[108:111], v[128:131], v[170:173], v[108:111]
	v_mfma_f32_16x16x32_bf16 v[104:107], v[136:139], v[170:173], v[104:107]
	v_mfma_f32_16x16x32_bf16 v[92:95], v[128:131], v[178:181], v[92:95]
	v_mfma_f32_16x16x32_bf16 v[88:91], v[136:139], v[178:181], v[88:91]
	v_mfma_f32_16x16x32_bf16 v[76:79], v[128:131], v[196:199], v[76:79]
	v_mfma_f32_16x16x32_bf16 v[72:75], v[136:139], v[196:199], v[72:75]
	v_mfma_f32_16x16x32_bf16 v[124:127], v[132:135], v[148:151], v[124:127]
	v_mfma_f32_16x16x32_bf16 v[120:123], v[140:143], v[148:151], v[120:123]
	v_mfma_f32_16x16x32_bf16 v[108:111], v[132:135], v[174:177], v[108:111]
	v_mfma_f32_16x16x32_bf16 v[104:107], v[140:143], v[174:177], v[104:107]
	v_mfma_f32_16x16x32_bf16 v[92:95], v[132:135], v[182:185], v[92:95]
	v_mfma_f32_16x16x32_bf16 v[88:91], v[140:143], v[182:185], v[88:91]
	v_mfma_f32_16x16x32_bf16 v[76:79], v[132:135], v[200:203], v[76:79]
	v_mfma_f32_16x16x32_bf16 v[72:75], v[140:143], v[200:203], v[72:75]
	s_setprio 0
	s_barrier
	s_add_i32 s49, s42, s31
	v_lshl_add_u64 v[186:187], s[22:23], 0, v[156:157]
	s_mov_b32 m0, s49
	ds_read_b128 v[204:207], v193
	ds_read_b128 v[208:211], v193 offset:1024
	ds_read_b128 v[212:215], v193 offset:2048
	ds_read_b128 v[216:219], v193 offset:3072
	global_load_lds_dwordx4 v[186:187], off
	v_lshl_add_u64 v[220:221], s[22:23], 0, v[160:161]
	s_add_i32 m0, s49, 0x2000
	s_nop 0
	global_load_lds_dwordx4 v[220:221], off
	s_barrier
	s_waitcnt lgkmcnt(0)
	s_setprio 1
	s_waitcnt lgkmcnt(0)
	v_mfma_f32_16x16x32_bf16 v[116:119], v[204:207], v[144:147], v[116:119]
	v_mfma_f32_16x16x32_bf16 v[112:115], v[212:215], v[144:147], v[112:115]
	v_mfma_f32_16x16x32_bf16 v[100:103], v[204:207], v[170:173], v[100:103]
	v_mfma_f32_16x16x32_bf16 v[96:99], v[212:215], v[170:173], v[96:99]
	v_mfma_f32_16x16x32_bf16 v[84:87], v[204:207], v[178:181], v[84:87]
	v_mfma_f32_16x16x32_bf16 v[80:83], v[212:215], v[178:181], v[80:83]
	v_mfma_f32_16x16x32_bf16 v[68:71], v[204:207], v[196:199], v[68:71]
	v_mfma_f32_16x16x32_bf16 v[64:67], v[212:215], v[196:199], v[64:67]
	v_mfma_f32_16x16x32_bf16 v[116:119], v[208:211], v[148:151], v[116:119]
	v_mfma_f32_16x16x32_bf16 v[112:115], v[216:219], v[148:151], v[112:115]
	v_mfma_f32_16x16x32_bf16 v[100:103], v[208:211], v[174:177], v[100:103]
	v_mfma_f32_16x16x32_bf16 v[96:99], v[216:219], v[174:177], v[96:99]
	v_mfma_f32_16x16x32_bf16 v[84:87], v[208:211], v[182:185], v[84:87]
	v_mfma_f32_16x16x32_bf16 v[80:83], v[216:219], v[182:185], v[80:83]
	v_mfma_f32_16x16x32_bf16 v[68:71], v[208:211], v[200:203], v[68:71]
	v_mfma_f32_16x16x32_bf16 v[64:67], v[216:219], v[200:203], v[64:67]
	s_setprio 0
	s_mov_b32 m0, s11
	v_lshl_add_u64 v[222:223], s[24:25], 0, v[154:155]
	s_barrier
	ds_read_b128 v[144:147], v192 offset:16384
	ds_read_b128 v[148:151], v192 offset:17408
	ds_read_b128 v[170:173], v192 offset:18432
	ds_read_b128 v[174:177], v192 offset:19456
	ds_read_b128 v[178:181], v192 offset:20480
	ds_read_b128 v[182:185], v192 offset:21504
	ds_read_b128 v[196:199], v192 offset:22528
	ds_read_b128 v[200:203], v192 offset:23552
	global_load_lds_dwordx4 v[222:223], off
	v_lshl_add_u64 v[224:225], s[24:25], 0, v[158:159]
	s_mov_b32 m0, s34
	s_nop 0
	global_load_lds_dwordx4 v[224:225], off
	s_barrier
	s_waitcnt lgkmcnt(0)
	s_setprio 1
	s_waitcnt lgkmcnt(0)
	v_mfma_f32_16x16x32_bf16 v[60:63], v[128:131], v[144:147], v[60:63]
	v_mfma_f32_16x16x32_bf16 v[56:59], v[136:139], v[144:147], v[56:59]
	v_mfma_f32_16x16x32_bf16 v[44:47], v[128:131], v[170:173], v[44:47]
	v_mfma_f32_16x16x32_bf16 v[40:43], v[136:139], v[170:173], v[40:43]
	v_mfma_f32_16x16x32_bf16 v[28:31], v[128:131], v[178:181], v[28:31]
	v_mfma_f32_16x16x32_bf16 v[24:27], v[136:139], v[178:181], v[24:27]
	v_mfma_f32_16x16x32_bf16 v[12:15], v[128:131], v[196:199], v[12:15]
	v_mfma_f32_16x16x32_bf16 v[8:11], v[136:139], v[196:199], v[8:11]
	v_mfma_f32_16x16x32_bf16 v[60:63], v[132:135], v[148:151], v[60:63]
	v_mfma_f32_16x16x32_bf16 v[56:59], v[140:143], v[148:151], v[56:59]
	v_mfma_f32_16x16x32_bf16 v[44:47], v[132:135], v[174:177], v[44:47]
	v_mfma_f32_16x16x32_bf16 v[40:43], v[140:143], v[174:177], v[40:43]
	v_mfma_f32_16x16x32_bf16 v[28:31], v[132:135], v[182:185], v[28:31]
	v_mfma_f32_16x16x32_bf16 v[24:27], v[140:143], v[182:185], v[24:27]
	v_mfma_f32_16x16x32_bf16 v[12:15], v[132:135], v[200:203], v[12:15]
	v_mfma_f32_16x16x32_bf16 v[8:11], v[140:143], v[200:203], v[8:11]
	s_setprio 0
	s_barrier
; #define PG8_STAGE(bufoff, gbase, voff) do { _Pragma("unroll") for (int _i = 0; _i < 2; ++_i) \
;         __builtin_amdgcn_global_load_lds((const unsigned*)((const char*)(gbase) + (voff)[_i]), (LAS unsigned*)(lds + (bufoff) + ldsw + _i * 8192), 16, 0, 0); } while (0)
; #define PG8_LDA(dst, b, h) do { _Pragma("unroll") for (int m = 0; m < 4; ++m) _Pragma("unroll") for (int k = 0; k < 2; ++k) dst[m][k] = *(const LAS bf16x8*)(lds + PG8_SA(b, h) + aoff + m * 2048 + k * 1024); } while (0)
; #define PG8_LDB(dst, b, h) do { _Pragma("unroll") for (int n = 0; n < 2; ++n) _Pragma("unroll") for (int k = 0; k < 2; ++k) dst[n][k] = *(const LAS bf16x8*)(lds + PG8_SB(b, h) + boff + n * 2048 + k * 1024); } while (0)
; #define PG8_MMA(ai, bj, At, Bt) do { __builtin_amdgcn_s_setprio(1); _Pragma("unroll") for (int m = 0; m < 4; ++m) _Pragma("unroll") for (int n = 0; n < 2; ++n) _Pragma("unroll") for (int k = 0; k < 2; ++k) \
;         acc[ai][bj][m][n] = __builtin_amdgcn_mfma_f32_16x16x32_bf16(Bt[n][k], At[m][k], acc[ai][bj][m][n], 0, 0, 0); __builtin_amdgcn_s_setprio(0); } while (0)
; #define PG8_WAIT_V(n) asm volatile("s_waitcnt vmcnt(" #n ")" ::: "memory")
; #define PG8_WAIT_L(n) asm volatile("s_waitcnt lgkmcnt(" #n ")" ::: "memory")
; #define PG8_BAR __builtin_amdgcn_s_barrier()
; #define PG8_SCHED __builtin_amdgcn_sched_barrier(0)
; template <class Epi>
; __device__ __forceinline__ void gemm_phase(LAS unsigned char* lds, const Gemm g, const StaticOrder& S, const Epi& E) {
;     ...
;             PG8_STAGE(PG8_SB(0, 1), b2 + hstepB, voffB);
;             PG8_WAIT_V(6); PG8_BAR; PG8_MMA(1, 1, At, B1); PG8_BAR;
;             PG8_LDB(B0, 1, 0); PG8_SCHED; PG8_LDA(At, 1, 0); PG8_STAGE(PG8_SA(0, 1), a2 + hstepA, voffA);
;             PG8_WAIT_L(8); PG8_BAR; PG8_WAIT_L(0); PG8_MMA(0, 0, At, B0); PG8_BAR; PG8_SCHED;
;             PG8_LDB(B1, 1, 1); PG8_STAGE(PG8_SB(1, 0), b3, voffB);
;             PG8_BAR; PG8_WAIT_L(0); PG8_MMA(0, 1, At, B1); PG8_BAR;
;             PG8_LDA(At, 1, 1); PG8_STAGE(PG8_SA(1, 0), a3, voffA);
	s_add_u32 s50, s22, 0x80000
	s_addc_u32 s51, s23, 0
	s_add_i32 s49, s43, s31
	v_lshl_add_u64 v[128:129], s[50:51], 0, v[156:157]
	s_mov_b32 m0, s49
	s_nop 0
	global_load_lds_dwordx4 v[128:129], off
	v_lshl_add_u64 v[128:129], s[50:51], 0, v[160:161]
	s_add_i32 m0, s49, 0x2000
	s_nop 0
	global_load_lds_dwordx4 v[128:129], off
	s_waitcnt vmcnt(6)
	s_barrier
	s_setprio 1
	v_mfma_f32_16x16x32_bf16 v[52:55], v[204:207], v[144:147], v[52:55]
	v_mfma_f32_16x16x32_bf16 v[48:51], v[212:215], v[144:147], v[48:51]
	v_mfma_f32_16x16x32_bf16 v[36:39], v[204:207], v[170:173], v[36:39]
	v_mfma_f32_16x16x32_bf16 v[32:35], v[212:215], v[170:173], v[32:35]
	v_mfma_f32_16x16x32_bf16 v[20:23], v[204:207], v[178:181], v[20:23]
	v_mfma_f32_16x16x32_bf16 v[16:19], v[212:215], v[178:181], v[16:19]
	v_mfma_f32_16x16x32_bf16 v[4:7], v[204:207], v[196:199], v[4:7]
	v_mfma_f32_16x16x32_bf16 v[0:3], v[212:215], v[196:199], v[0:3]
	v_mfma_f32_16x16x32_bf16 v[52:55], v[208:211], v[148:151], v[52:55]
	v_mfma_f32_16x16x32_bf16 v[48:51], v[216:219], v[148:151], v[48:51]
	v_mfma_f32_16x16x32_bf16 v[36:39], v[208:211], v[174:177], v[36:39]
	v_mfma_f32_16x16x32_bf16 v[32:35], v[216:219], v[174:177], v[32:35]
	v_mfma_f32_16x16x32_bf16 v[20:23], v[208:211], v[182:185], v[20:23]
	v_mfma_f32_16x16x32_bf16 v[16:19], v[216:219], v[182:185], v[16:19]
	v_mfma_f32_16x16x32_bf16 v[4:7], v[208:211], v[200:203], v[4:7]
	v_mfma_f32_16x16x32_bf16 v[0:3], v[216:219], v[200:203], v[0:3]
	s_setprio 0
	s_add_i32 s49, 0, 0x18000
	v_add_u32_e32 v140, s49, v189
	s_barrier
	ds_read_b128 v[128:131], v140
	ds_read_b128 v[132:135], v140 offset:1024
	ds_read_b128 v[136:139], v140 offset:2048
	ds_read_b128 v[140:143], v140 offset:3072
	s_add_u32 s24, s24, 0x140000
	s_addc_u32 s25, s25, 0
	s_mov_b32 m0, s35
	v_lshl_add_u64 v[204:205], s[24:25], 0, v[154:155]
	ds_read_b128 v[144:147], v192 offset:32768
	ds_read_b128 v[148:151], v192 offset:33792
	ds_read_b128 v[170:173], v192 offset:34816
	ds_read_b128 v[174:177], v192 offset:35840
	ds_read_b128 v[178:181], v192 offset:36864
	ds_read_b128 v[182:185], v192 offset:37888
	ds_read_b128 v[196:199], v192 offset:38912
	ds_read_b128 v[200:203], v192 offset:39936
	global_load_lds_dwordx4 v[204:205], off
	v_lshl_add_u64 v[204:205], s[24:25], 0, v[158:159]
	s_mov_b32 m0, s36
	s_nop 0
	global_load_lds_dwordx4 v[204:205], off
	s_waitcnt lgkmcnt(8)
	s_barrier
	s_waitcnt lgkmcnt(0)
	s_setprio 1
	s_waitcnt lgkmcnt(0)
	v_mfma_f32_16x16x32_bf16 v[124:127], v[128:131], v[144:147], v[124:127]
	v_mfma_f32_16x16x32_bf16 v[120:123], v[136:139], v[144:147], v[120:123]
	v_mfma_f32_16x16x32_bf16 v[108:111], v[128:131], v[170:173], v[108:111]
	v_mfma_f32_16x16x32_bf16 v[104:107], v[136:139], v[170:173], v[104:107]
	v_mfma_f32_16x16x32_bf16 v[92:95], v[128:131], v[178:181], v[92:95]
	v_mfma_f32_16x16x32_bf16 v[88:91], v[136:139], v[178:181], v[88:91]
	v_mfma_f32_16x16x32_bf16 v[76:79], v[128:131], v[196:199], v[76:79]
	v_mfma_f32_16x16x32_bf16 v[72:75], v[136:139], v[196:199], v[72:75]
	v_mfma_f32_16x16x32_bf16 v[124:127], v[132:135], v[148:151], v[124:127]
	v_mfma_f32_16x16x32_bf16 v[120:123], v[140:143], v[148:151], v[120:123]
	v_mfma_f32_16x16x32_bf16 v[108:111], v[132:135], v[174:177], v[108:111]
	v_mfma_f32_16x16x32_bf16 v[104:107], v[140:143], v[174:177], v[104:107]
	v_mfma_f32_16x16x32_bf16 v[92:95], v[132:135], v[182:185], v[92:95]
	v_mfma_f32_16x16x32_bf16 v[88:91], v[140:143], v[182:185], v[88:91]
	v_mfma_f32_16x16x32_bf16 v[76:79], v[132:135], v[200:203], v[76:79]
	v_mfma_f32_16x16x32_bf16 v[72:75], v[140:143], v[200:203], v[72:75]
	s_setprio 0
	s_barrier
	s_add_i32 s24, 0, 0x1c000
	s_add_i32 s25, s49, s31
	v_add_u32_e32 v195, s24, v189
	v_lshl_add_u64 v[186:187], v[186:187], 0, s[14:15]
	s_mov_b32 m0, s25
	ds_read_b128 v[204:207], v195
	ds_read_b128 v[208:211], v195 offset:1024
	ds_read_b128 v[212:215], v195 offset:2048
	ds_read_b128 v[216:219], v195 offset:3072
	global_load_lds_dwordx4 v[186:187], off
	v_lshl_add_u64 v[186:187], v[220:221], 0, s[14:15]
	s_add_i32 m0, s25, 0x2000
	s_nop 0
	global_load_lds_dwordx4 v[186:187], off
	s_barrier
	s_waitcnt lgkmcnt(0)
	s_setprio 1
	s_waitcnt lgkmcnt(0)
	v_mfma_f32_16x16x32_bf16 v[116:119], v[204:207], v[144:147], v[116:119]
	v_mfma_f32_16x16x32_bf16 v[112:115], v[212:215], v[144:147], v[112:115]
	v_mfma_f32_16x16x32_bf16 v[100:103], v[204:207], v[170:173], v[100:103]
	v_mfma_f32_16x16x32_bf16 v[96:99], v[212:215], v[170:173], v[96:99]
	v_mfma_f32_16x16x32_bf16 v[84:87], v[204:207], v[178:181], v[84:87]
	v_mfma_f32_16x16x32_bf16 v[80:83], v[212:215], v[178:181], v[80:83]
	v_mfma_f32_16x16x32_bf16 v[68:71], v[204:207], v[196:199], v[68:71]
	v_mfma_f32_16x16x32_bf16 v[64:67], v[212:215], v[196:199], v[64:67]
	v_mfma_f32_16x16x32_bf16 v[116:119], v[208:211], v[148:151], v[116:119]
	v_mfma_f32_16x16x32_bf16 v[112:115], v[216:219], v[148:151], v[112:115]
	v_mfma_f32_16x16x32_bf16 v[100:103], v[208:211], v[174:177], v[100:103]
	v_mfma_f32_16x16x32_bf16 v[96:99], v[216:219], v[174:177], v[96:99]
	v_mfma_f32_16x16x32_bf16 v[84:87], v[208:211], v[182:185], v[84:87]
	v_mfma_f32_16x16x32_bf16 v[80:83], v[216:219], v[182:185], v[80:83]
	v_mfma_f32_16x16x32_bf16 v[68:71], v[208:211], v[200:203], v[68:71]
	v_mfma_f32_16x16x32_bf16 v[64:67], v[216:219], v[200:203], v[64:67]
	s_setprio 0
	s_mov_b32 m0, s38
	v_lshl_add_u64 v[186:187], v[222:223], 0, s[14:15]
	s_barrier
	ds_read_b128 v[144:147], v192 offset:49152
	ds_read_b128 v[148:151], v192 offset:50176
	ds_read_b128 v[170:173], v192 offset:51200
	ds_read_b128 v[174:177], v192 offset:52224
	ds_read_b128 v[178:181], v192 offset:53248
	ds_read_b128 v[182:185], v192 offset:54272
	ds_read_b128 v[196:199], v192 offset:55296
	ds_read_b128 v[200:203], v192 offset:56320
	global_load_lds_dwordx4 v[186:187], off
	v_lshl_add_u64 v[186:187], v[224:225], 0, s[14:15]
	s_mov_b32 m0, s39
	s_nop 0
	global_load_lds_dwordx4 v[186:187], off
	s_barrier
; #define PG8_STAGE(bufoff, gbase, voff) do { _Pragma("unroll") for (int _i = 0; _i < 2; ++_i) \
;         __builtin_amdgcn_global_load_lds((const unsigned*)((const char*)(gbase) + (voff)[_i]), (LAS unsigned*)(lds + (bufoff) + ldsw + _i * 8192), 16, 0, 0); } while (0)
; #define PG8_MMA(ai, bj, At, Bt) do { __builtin_amdgcn_s_setprio(1); _Pragma("unroll") for (int m = 0; m < 4; ++m) _Pragma("unroll") for (int n = 0; n < 2; ++n) _Pragma("unroll") for (int k = 0; k < 2; ++k) \
;         acc[ai][bj][m][n] = __builtin_amdgcn_mfma_f32_16x16x32_bf16(Bt[n][k], At[m][k], acc[ai][bj][m][n], 0, 0, 0); __builtin_amdgcn_s_setprio(0); } while (0)
; #define PG8_WAIT_V(n) asm volatile("s_waitcnt vmcnt(" #n ")" ::: "memory")
; #define PG8_WAIT_L(n) asm volatile("s_waitcnt lgkmcnt(" #n ")" ::: "memory")
; #define PG8_BAR __builtin_amdgcn_s_barrier()
; #define PG8_SCHED __builtin_amdgcn_sched_barrier(0)
; template <class Epi>
; __device__ __forceinline__ void gemm_phase(LAS unsigned char* lds, const Gemm g, const StaticOrder& S, const Epi& E) {
;     ...
;             PG8_BAR; PG8_WAIT_L(0); PG8_MMA(1, 0, At, B0); PG8_BAR; PG8_SCHED;
;             PG8_STAGE(PG8_SB(1, 1), b3 + hstepB, voffB);
;             PG8_WAIT_V(6); PG8_BAR; PG8_MMA(1, 1, At, B1); PG8_BAR;
;         }
	s_waitcnt lgkmcnt(0)
	s_setprio 1
	s_waitcnt lgkmcnt(0)
	v_mfma_f32_16x16x32_bf16 v[60:63], v[128:131], v[144:147], v[60:63]
	v_mfma_f32_16x16x32_bf16 v[56:59], v[136:139], v[144:147], v[56:59]
	v_mfma_f32_16x16x32_bf16 v[44:47], v[128:131], v[170:173], v[44:47]
	v_mfma_f32_16x16x32_bf16 v[40:43], v[136:139], v[170:173], v[40:43]
	v_mfma_f32_16x16x32_bf16 v[28:31], v[128:131], v[178:181], v[28:31]
	v_mfma_f32_16x16x32_bf16 v[24:27], v[136:139], v[178:181], v[24:27]
	v_mfma_f32_16x16x32_bf16 v[12:15], v[128:131], v[196:199], v[12:15]
	v_mfma_f32_16x16x32_bf16 v[8:11], v[136:139], v[196:199], v[8:11]
	v_mfma_f32_16x16x32_bf16 v[60:63], v[132:135], v[148:151], v[60:63]
	v_mfma_f32_16x16x32_bf16 v[56:59], v[140:143], v[148:151], v[56:59]
	v_mfma_f32_16x16x32_bf16 v[44:47], v[132:135], v[174:177], v[44:47]
	v_mfma_f32_16x16x32_bf16 v[40:43], v[140:143], v[174:177], v[40:43]
	v_mfma_f32_16x16x32_bf16 v[28:31], v[132:135], v[182:185], v[28:31]
	v_mfma_f32_16x16x32_bf16 v[24:27], v[140:143], v[182:185], v[24:27]
	v_mfma_f32_16x16x32_bf16 v[12:15], v[132:135], v[200:203], v[12:15]
	v_mfma_f32_16x16x32_bf16 v[8:11], v[140:143], v[200:203], v[8:11]
	s_setprio 0
	s_barrier
	s_add_u32 s22, s22, 0x80080
	s_addc_u32 s23, s23, 0
	s_add_i32 s24, s24, s31
	v_lshl_add_u64 v[128:129], s[22:23], 0, v[156:157]
	s_mov_b32 m0, s24
	s_nop 0
	global_load_lds_dwordx4 v[128:129], off
	v_lshl_add_u64 v[128:129], s[22:23], 0, v[160:161]
	s_add_i32 m0, s24, 0x2000
	s_nop 0
	global_load_lds_dwordx4 v[128:129], off
	s_waitcnt vmcnt(6)
	s_barrier
	s_setprio 1
	v_mfma_f32_16x16x32_bf16 v[52:55], v[204:207], v[144:147], v[52:55]
	v_mfma_f32_16x16x32_bf16 v[48:51], v[212:215], v[144:147], v[48:51]
	v_mfma_f32_16x16x32_bf16 v[36:39], v[204:207], v[170:173], v[36:39]
	v_mfma_f32_16x16x32_bf16 v[32:35], v[212:215], v[170:173], v[32:35]
	v_mfma_f32_16x16x32_bf16 v[20:23], v[204:207], v[178:181], v[20:23]
	v_mfma_f32_16x16x32_bf16 v[16:19], v[212:215], v[178:181], v[16:19]
	v_mfma_f32_16x16x32_bf16 v[4:7], v[204:207], v[196:199], v[4:7]
	v_mfma_f32_16x16x32_bf16 v[0:3], v[212:215], v[196:199], v[0:3]
	v_mfma_f32_16x16x32_bf16 v[52:55], v[208:211], v[148:151], v[52:55]
	v_mfma_f32_16x16x32_bf16 v[48:51], v[216:219], v[148:151], v[48:51]
	v_mfma_f32_16x16x32_bf16 v[36:39], v[208:211], v[174:177], v[36:39]
	v_mfma_f32_16x16x32_bf16 v[32:35], v[216:219], v[174:177], v[32:35]
	v_mfma_f32_16x16x32_bf16 v[20:23], v[208:211], v[182:185], v[20:23]
	v_mfma_f32_16x16x32_bf16 v[16:19], v[216:219], v[182:185], v[16:19]
	v_mfma_f32_16x16x32_bf16 v[4:7], v[208:211], v[200:203], v[4:7]
	v_mfma_f32_16x16x32_bf16 v[0:3], v[216:219], v[200:203], v[0:3]
	s_setprio 0
	s_add_i32 s48, s48, 2
	s_add_u32 s4, s4, 0x100
	s_addc_u32 s5, s5, 0
	s_add_u32 s46, s46, 0x100
	s_addc_u32 s47, s47, 0
	s_cmp_gt_u32 s48, 29
	s_barrier
	s_cbranch_scc0 .LBB0_684
; __device__ __forceinline__ unsigned pk2(float lo, float hi) { const f32x2 v = (f32x2){lo, hi}; const bf16x2_t b = __builtin_convertvector(v, bf16x2_t); return __builtin_bit_cast(unsigned, b); }
; __device__ __forceinline__ void unpack8(const u32x4 v, float* f) { f[0] = bf_lo(v.x); f[1] = bf_hi(v.x); f[2] = bf_lo(v.y); f[3] = bf_hi(v.y); f[4] = bf_lo(v.z); f[5] = bf_hi(v.z); f[6] = bf_lo(v.w); f[7] = bf_hi(v.w); }
;     __device__ __forceinline__ void operator()(const f32x4 (&acc)[2][2][4][2], const Unit& u, int wr, int wc, int fr, int fq, const float (&)[8]) const {
;     ...
;         for (int ai = 0; ai < 2; ++ai) {
;             u32x4 bv[4][2];
; #pragma unroll
;             for (int m = 0; m < 4; ++m)
; #pragma unroll
;                 for (int bj = 0; bj < 2; ++bj) bv[m][bj] = *(const u32x4*)(xb + (size_t)(row0 + ai * HALF + m * 16) * DM + col0 + bj * HALF);
; #pragma unroll
;             for (int m = 0; m < 4; ++m) { const int row = row0 + ai * HALF + m * 16; const size_t ro = (size_t)row * DM + col0; float s = 0.f;
; #pragma unroll
;                 for (int bj = 0; bj < 2; ++bj) { float b8[8]; unpack8(bv[m][bj], b8);
;                     const f32x4 v0 = (f32x4){b8[0], b8[1], b8[2], b8[3]} + acc[ai][bj][m][0], v1 = (f32x4){b8[4], b8[5], b8[6], b8[7]} + acc[ai][bj][m][1];
;                     s += v0[0] * v0[0] + v0[1] * v0[1] + v0[2] * v0[2] + v0[3] * v0[3] + v1[0] * v1[0] + v1[1] * v1[1] + v1[2] * v1[2] + v1[3] * v1[3];
;                     if (LAST) { *(f32x4*)(out + ro + bj * HALF) = v0; *(f32x4*)(out + ro + bj * HALF + 4) = v1; }
;                     else { u32x4 w; w.x = pk2(v0[0], v0[1]); w.y = pk2(v0[2], v0[3]); w.z = pk2(v1[0], v1[1]); w.w = pk2(v1[2], v1[3]); *(u32x4*)(xb + ro + bj * HALF) = w; } }
;                 s += __shfl_xor(s, 16); s += __shfl_xor(s, 32);
;                 if (fq == 0) ss[(size_t)row * 16 + u.pn * 4 + wc] = s; }
	v_lshl_or_b32 v170, s10, 8, v190
	v_lshl_add_u32 v172, s12, 8, v188
	v_ashrrev_i32_e32 v171, 31, v170
	v_lshlrev_b64 v[206:207], 1, v[170:171]
	v_ashrrev_i32_e32 v173, 31, v172
	v_lshl_add_u64 v[174:175], s[76:77], 0, v[206:207]
	v_lshlrev_b64 v[208:209], 11, v[172:173]
	v_lshl_add_u64 v[128:129], v[174:175], 0, v[208:209]
	global_load_dwordx4 v[198:201], v[128:129], off
	global_load_dwordx4 v[202:205], v[128:129], off offset:256
	v_or_b32_e32 v184, 16, v172
	v_or_b32_e32 v180, 32, v172
	v_or_b32_e32 v176, 48, v172
	v_ashrrev_i32_e32 v185, 31, v184
	v_ashrrev_i32_e32 v181, 31, v180
	v_ashrrev_i32_e32 v177, 31, v176
	v_lshlrev_b64 v[186:187], 11, v[184:185]
	v_lshlrev_b64 v[182:183], 11, v[180:181]
	v_lshlrev_b64 v[178:179], 11, v[176:177]
	v_lshl_add_u64 v[128:129], v[174:175], 0, v[186:187]
	v_lshl_add_u64 v[130:131], v[174:175], 0, v[182:183]
	v_lshl_add_u64 v[196:197], v[174:175], 0, v[178:179]
	global_load_dwordx4 v[148:151], v[128:129], off
	global_load_dwordx4 v[144:147], v[128:129], off offset:256
	global_load_dwordx4 v[140:143], v[130:131], off
	global_load_dwordx4 v[136:139], v[130:131], off offset:256
	global_load_dwordx4 v[132:135], v[196:197], off
	s_nop 0
	global_load_dwordx4 v[128:131], v[196:197], off offset:256
	v_add_u32_e32 v218, 0x80, v172
	v_ashrrev_i32_e32 v219, 31, v218
	v_lshlrev_b64 v[218:219], 11, v[218:219]
	v_lshl_add_u64 v[218:219], v[174:175], 0, v[218:219]
	global_load_dwordx4 v[220:223], v[218:219], off
	global_load_dwordx4 v[224:227], v[218:219], off offset:256
	v_add_u32_e32 v218, 0x90, v172
	v_ashrrev_i32_e32 v219, 31, v218
	v_lshlrev_b64 v[218:219], 11, v[218:219]
	v_lshl_add_u64 v[218:219], v[174:175], 0, v[218:219]
	global_load_dwordx4 v[228:231], v[218:219], off
	global_load_dwordx4 v[232:235], v[218:219], off offset:256
	v_add_u32_e32 v218, 0xa0, v172
	v_ashrrev_i32_e32 v219, 31, v218
	v_lshlrev_b64 v[218:219], 11, v[218:219]
	v_lshl_add_u64 v[218:219], v[174:175], 0, v[218:219]
	global_load_dwordx4 v[236:239], v[218:219], off
	global_load_dwordx4 v[240:243], v[218:219], off offset:256
	v_add_u32_e32 v218, 0xb0, v172
	v_ashrrev_i32_e32 v219, 31, v218
	v_lshlrev_b64 v[218:219], 11, v[218:219]
	v_lshl_add_u64 v[218:219], v[174:175], 0, v[218:219]
	global_load_dwordx4 v[244:247], v[218:219], off
	global_load_dwordx4 v[252:255], v[218:219], off offset:256
	v_and_b32_e32 v196, 64, v194
	v_xor_b32_e32 v195, 16, v194
	v_add_u32_e32 v196, 64, v196
	v_xor_b32_e32 v197, 32, v194
	v_cmp_lt_i32_e32 vcc, v195, v196
	s_waitcnt vmcnt(0)
	v_lshlrev_b32_e32 v210, 16, v198
	v_cndmask_b32_e32 v195, v194, v195, vcc
	v_cmp_lt_i32_e32 vcc, v197, v196
	v_and_b32_e32 v211, 0xffff0000, v198
	v_lshlrev_b32_e32 v214, 16, v202
	v_and_b32_e32 v215, 0xffff0000, v202
	v_cndmask_b32_e32 v197, v194, v197, vcc
	v_lshlrev_b32_e32 v212, 16, v200
	v_and_b32_e32 v213, 0xffff0000, v200
	v_lshlrev_b32_e32 v200, 16, v201
	v_and_b32_e32 v201, 0xffff0000, v201
	v_lshlrev_b32_e32 v216, 16, v204
	v_and_b32_e32 v217, 0xffff0000, v204
	v_pk_add_f32 v[124:125], v[124:125], v[210:211]
	v_pk_add_f32 v[116:117], v[116:117], v[214:215]
	v_lshlrev_b32_e32 v196, 2, v195
	v_lshlrev_b32_e32 v195, 2, v197
	v_lshlrev_b32_e32 v198, 16, v199
	v_and_b32_e32 v199, 0xffff0000, v199
	v_lshlrev_b32_e32 v202, 16, v203
	v_and_b32_e32 v203, 0xffff0000, v203
	v_pk_add_f32 v[122:123], v[122:123], v[200:201]
	v_pk_add_f32 v[200:201], v[112:113], v[216:217]
	v_mul_f32_e32 v197, v125, v125
	v_cvt_pk_bf16_f32 v112, v124, v125
	v_mul_f32_e32 v125, v117, v117
	v_pk_add_f32 v[126:127], v[126:127], v[198:199]
	v_pk_add_f32 v[118:119], v[118:119], v[202:203]
	v_fmac_f32_e32 v197, v124, v124
	v_fmac_f32_e32 v125, v116, v116
	v_fmac_f32_e32 v197, v126, v126
	v_fmac_f32_e32 v125, v118, v118
	v_pk_add_f32 v[120:121], v[120:121], v[212:213]
	v_fmac_f32_e32 v197, v127, v127
	v_fmac_f32_e32 v125, v119, v119
	v_lshlrev_b32_e32 v204, 16, v205
	v_and_b32_e32 v205, 0xffff0000, v205
	v_fmac_f32_e32 v197, v120, v120
	v_fmac_f32_e32 v125, v200, v200
	v_pk_add_f32 v[198:199], v[114:115], v[204:205]
	v_fmac_f32_e32 v197, v121, v121
	v_fmac_f32_e32 v125, v201, v201
	v_fmac_f32_e32 v197, v122, v122
	v_fmac_f32_e32 v125, v198, v198
	v_fmac_f32_e32 v197, v123, v123
	v_fmac_f32_e32 v125, v199, v199
	v_cvt_pk_bf16_f32 v115, v122, v123
	v_add_f32_e32 v122, v197, v125
	ds_bpermute_b32 v123, v196, v122
	v_cvt_pk_bf16_f32 v114, v120, v121
	v_lshl_add_u64 v[120:121], s[76:77], 0, v[208:209]
	v_cvt_pk_bf16_f32 v113, v126, v127
	v_lshl_add_u64 v[120:121], v[120:121], 0, v[206:207]
	global_store_dwordx4 v[120:121], v[112:115], off
	s_waitcnt lgkmcnt(0)
	s_nop 0
	v_add_f32_e32 v112, v122, v123
	ds_bpermute_b32 v113, v195, v112
	v_cvt_pk_bf16_f32 v114, v116, v117
	v_cvt_pk_bf16_f32 v115, v118, v119
	v_cvt_pk_bf16_f32 v116, v200, v201
	v_cvt_pk_bf16_f32 v117, v198, v199
	global_store_dwordx4 v[120:121], v[114:117], off offset:256
	s_and_saveexec_b64 s[4:5], s[0:1]
	s_cbranch_execz .LBB0_687
	s_waitcnt lgkmcnt(0)
	v_add_f32_e32 v114, v112, v113
	s_lshl_b32 s22, s10, 2
	v_lshlrev_b64 v[112:113], 6, v[172:173]
	s_ashr_i32 s23, s22, 31
	v_lshl_add_u64 v[112:113], s[6:7], 0, v[112:113]
	v_lshl_add_u64 v[112:113], s[22:23], 2, v[112:113]
	s_lshl_b32 s12, s37, 2
	v_lshl_add_u64 v[112:113], v[112:113], 0, s[12:13]
	global_store_dword v[112:113], v114, off

; __device__ __forceinline__ unsigned pk2(float lo, float hi) { const f32x2 v = (f32x2){lo, hi}; const bf16x2_t b = __builtin_convertvector(v, bf16x2_t); return __builtin_bit_cast(unsigned, b); }
; __device__ __forceinline__ void unpack8(const u32x4 v, float* f) { f[0] = bf_lo(v.x); f[1] = bf_hi(v.x); f[2] = bf_lo(v.y); f[3] = bf_hi(v.y); f[4] = bf_lo(v.z); f[5] = bf_hi(v.z); f[6] = bf_lo(v.w); f[7] = bf_hi(v.w); }
;     __device__ __forceinline__ void operator()(const f32x4 (&acc)[2][2][4][2], const Unit& u, int wr, int wc, int fr, int fq, const float (&)[8]) const {
;     ...
;         for (int ai = 0; ai < 2; ++ai) {
;             u32x4 bv[4][2];
; #pragma unroll
;             for (int m = 0; m < 4; ++m)
; #pragma unroll
;                 for (int bj = 0; bj < 2; ++bj) bv[m][bj] = *(const u32x4*)(xb + (size_t)(row0 + ai * HALF + m * 16) * DM + col0 + bj * HALF);
; #pragma unroll
;             for (int m = 0; m < 4; ++m) { const int row = row0 + ai * HALF + m * 16; const size_t ro = (size_t)row * DM + col0; float s = 0.f;
; #pragma unroll
;                 for (int bj = 0; bj < 2; ++bj) { float b8[8]; unpack8(bv[m][bj], b8);
;                     const f32x4 v0 = (f32x4){b8[0], b8[1], b8[2], b8[3]} + acc[ai][bj][m][0], v1 = (f32x4){b8[4], b8[5], b8[6], b8[7]} + acc[ai][bj][m][1];
;                     s += v0[0] * v0[0] + v0[1] * v0[1] + v0[2] * v0[2] + v0[3] * v0[3] + v1[0] * v1[0] + v1[1] * v1[1] + v1[2] * v1[2] + v1[3] * v1[3];
;                     if (LAST) { *(f32x4*)(out + ro + bj * HALF) = v0; *(f32x4*)(out + ro + bj * HALF + 4) = v1; }
;                     else { u32x4 w; w.x = pk2(v0[0], v0[1]); w.y = pk2(v0[2], v0[3]); w.z = pk2(v1[0], v1[1]); w.w = pk2(v1[2], v1[3]); *(u32x4*)(xb + ro + bj * HALF) = w; } }
;                 s += __shfl_xor(s, 16); s += __shfl_xor(s, 32);
;                 if (fq == 0) ss[(size_t)row * 16 + u.pn * 4 + wc] = s; }
.LBB0_693:
	s_or_b64 exec, exec, s[4:5]
	v_add_u32_e32 v100, 0x80, v172
	v_ashrrev_i32_e32 v101, 31, v100
	v_lshlrev_b64 v[110:111], 11, v[100:101]
	s_waitcnt lgkmcnt(0)
	v_lshl_add_u64 v[64:65], v[174:175], 0, v[110:111]
	v_mov_b32_e32 v102, v220
	v_mov_b32_e32 v103, v221
	v_mov_b32_e32 v104, v222
	v_mov_b32_e32 v105, v223
	v_mov_b32_e32 v106, v224
	v_mov_b32_e32 v107, v225
	v_mov_b32_e32 v108, v226
	v_mov_b32_e32 v109, v227
	v_add_u32_e32 v96, 0x90, v172
	v_add_u32_e32 v92, 0xa0, v172
	v_add_u32_e32 v88, 0xb0, v172
	v_ashrrev_i32_e32 v97, 31, v96
	v_ashrrev_i32_e32 v93, 31, v92
	v_ashrrev_i32_e32 v89, 31, v88
	v_lshlrev_b64 v[98:99], 11, v[96:97]
	v_lshlrev_b64 v[94:95], 11, v[92:93]
	v_lshlrev_b64 v[90:91], 11, v[88:89]
	v_lshl_add_u64 v[64:65], v[174:175], 0, v[98:99]
	v_lshl_add_u64 v[66:67], v[174:175], 0, v[94:95]
	v_lshl_add_u64 v[112:113], v[174:175], 0, v[90:91]
	v_mov_b32_e32 v84, v228
	v_mov_b32_e32 v85, v229
	v_mov_b32_e32 v86, v230
	v_mov_b32_e32 v87, v231
	v_mov_b32_e32 v80, v232
	v_mov_b32_e32 v81, v233
	v_mov_b32_e32 v82, v234
	v_mov_b32_e32 v83, v235
	v_mov_b32_e32 v76, v236
	v_mov_b32_e32 v77, v237
	v_mov_b32_e32 v78, v238
	v_mov_b32_e32 v79, v239
	v_mov_b32_e32 v72, v240
	v_mov_b32_e32 v73, v241
	v_mov_b32_e32 v74, v242
	v_mov_b32_e32 v75, v243
	v_mov_b32_e32 v68, v244
	v_mov_b32_e32 v69, v245
	v_mov_b32_e32 v70, v246
	v_mov_b32_e32 v71, v247
	s_nop 0
	v_mov_b32_e32 v64, v252
	v_mov_b32_e32 v65, v253
	v_mov_b32_e32 v66, v254
	v_mov_b32_e32 v67, v255
	s_nop 0
	v_lshlrev_b32_e32 v112, 16, v102
	v_and_b32_e32 v113, 0xffff0000, v102
	s_nop 0
	v_lshlrev_b32_e32 v116, 16, v106
	v_and_b32_e32 v117, 0xffff0000, v106
	v_lshlrev_b32_e32 v114, 16, v104
	v_and_b32_e32 v115, 0xffff0000, v104
	v_lshlrev_b32_e32 v104, 16, v105
	v_and_b32_e32 v105, 0xffff0000, v105
	v_lshlrev_b32_e32 v106, 16, v107
	v_and_b32_e32 v107, 0xffff0000, v107
	v_lshlrev_b32_e32 v118, 16, v108
	v_and_b32_e32 v119, 0xffff0000, v108
	v_pk_add_f32 v[60:61], v[60:61], v[112:113]
	v_pk_add_f32 v[52:53], v[52:53], v[116:117]
	v_lshlrev_b32_e32 v102, 16, v103
	v_and_b32_e32 v103, 0xffff0000, v103
	v_pk_add_f32 v[58:59], v[58:59], v[104:105]
	v_pk_add_f32 v[54:55], v[54:55], v[106:107]
	v_pk_add_f32 v[104:105], v[48:49], v[118:119]
	v_mul_f32_e32 v106, v61, v61
	v_cvt_pk_bf16_f32 v48, v60, v61
	v_mul_f32_e32 v61, v53, v53
	v_pk_add_f32 v[62:63], v[62:63], v[102:103]
	v_fmac_f32_e32 v106, v60, v60
	v_fmac_f32_e32 v61, v52, v52
	v_fmac_f32_e32 v106, v62, v62
	v_fmac_f32_e32 v61, v54, v54
	v_pk_add_f32 v[56:57], v[56:57], v[114:115]
	v_fmac_f32_e32 v106, v63, v63
	v_fmac_f32_e32 v61, v55, v55
	v_lshlrev_b32_e32 v108, 16, v109
	v_and_b32_e32 v109, 0xffff0000, v109
	v_fmac_f32_e32 v106, v56, v56
	v_fmac_f32_e32 v61, v104, v104
	v_pk_add_f32 v[102:103], v[50:51], v[108:109]
	v_fmac_f32_e32 v106, v57, v57
	v_fmac_f32_e32 v61, v105, v105
	v_fmac_f32_e32 v106, v58, v58
	v_fmac_f32_e32 v61, v102, v102
	v_fmac_f32_e32 v106, v59, v59
	v_fmac_f32_e32 v61, v103, v103
	v_cvt_pk_bf16_f32 v51, v58, v59
	v_add_f32_e32 v58, v106, v61
	ds_bpermute_b32 v59, v196, v58
	v_cvt_pk_bf16_f32 v50, v56, v57
	v_lshl_add_u64 v[56:57], s[76:77], 0, v[110:111]
	v_cvt_pk_bf16_f32 v49, v62, v63
	v_lshl_add_u64 v[56:57], v[170:171], 1, v[56:57]
	global_store_dwordx4 v[56:57], v[48:51], off
	s_waitcnt lgkmcnt(0)
	s_nop 0
	v_add_f32_e32 v48, v58, v59
	ds_bpermute_b32 v49, v195, v48
	v_cvt_pk_bf16_f32 v50, v52, v53
	v_cvt_pk_bf16_f32 v51, v54, v55
	v_cvt_pk_bf16_f32 v52, v104, v105
	v_cvt_pk_bf16_f32 v53, v102, v103
	global_store_dwordx4 v[56:57], v[50:53], off offset:256
	s_and_saveexec_b64 s[4:5], s[0:1]
	s_cbranch_execz .LBB0_695
	s_waitcnt lgkmcnt(0)
	v_add_f32_e32 v50, v48, v49
	s_lshl_b32 s22, s10, 2
	v_lshlrev_b64 v[48:49], 6, v[100:101]
	s_ashr_i32 s23, s22, 31
	v_lshl_add_u64 v[48:49], s[6:7], 0, v[48:49]
	v_lshl_add_u64 v[48:49], s[22:23], 2, v[48:49]
	s_lshl_b32 s12, s37, 2
	v_lshl_add_u64 v[48:49], v[48:49], 0, s[12:13]
	global_store_dword v[48:49], v50, off
.LBB0_695:
	s_or_b64 exec, exec, s[4:5]
	s_nop 0
	v_lshlrev_b32_e32 v48, 16, v84
	s_waitcnt lgkmcnt(0)
	v_and_b32_e32 v49, 0xffff0000, v84
	v_lshlrev_b32_e32 v52, 16, v86
	v_and_b32_e32 v53, 0xffff0000, v86
	v_lshlrev_b32_e32 v54, 16, v87
	v_and_b32_e32 v55, 0xffff0000, v87
	v_pk_add_f32 v[44:45], v[44:45], v[48:49]
	v_lshlrev_b32_e32 v50, 16, v85
	v_and_b32_e32 v51, 0xffff0000, v85
	v_pk_add_f32 v[48:49], v[42:43], v[54:55]
	v_pk_add_f32 v[42:43], v[40:41], v[52:53]
	v_mul_f32_e32 v52, v45, v45
	v_pk_add_f32 v[46:47], v[46:47], v[50:51]
	v_fmac_f32_e32 v52, v44, v44
	v_fmac_f32_e32 v52, v46, v46
	v_fmac_f32_e32 v52, v47, v47
	v_fmac_f32_e32 v52, v42, v42
	v_fmac_f32_e32 v52, v43, v43
	v_fmac_f32_e32 v52, v48, v48
	v_cvt_pk_bf16_f32 v40, v44, v45
	s_nop 0
	v_lshlrev_b32_e32 v44, 16, v80
	v_and_b32_e32 v45, 0xffff0000, v80
	v_fmac_f32_e32 v52, v49, v49
	v_cvt_pk_bf16_f32 v41, v46, v47
	v_cvt_pk_bf16_f32 v42, v42, v43
	v_cvt_pk_bf16_f32 v43, v48, v49
	v_lshlrev_b32_e32 v46, 16, v81
	v_and_b32_e32 v47, 0xffff0000, v81
	v_lshlrev_b32_e32 v48, 16, v82
	v_and_b32_e32 v49, 0xffff0000, v82
	v_pk_add_f32 v[36:37], v[36:37], v[44:45]
	v_pk_add_f32 v[38:39], v[38:39], v[46:47]
	v_pk_add_f32 v[46:47], v[32:33], v[48:49]
	v_mul_f32_e32 v32, v37, v37
	v_fmac_f32_e32 v32, v36, v36
	v_fmac_f32_e32 v32, v38, v38
	v_fmac_f32_e32 v32, v39, v39
	v_lshlrev_b32_e32 v50, 16, v83
	v_and_b32_e32 v51, 0xffff0000, v83
	v_fmac_f32_e32 v32, v46, v46
	v_pk_add_f32 v[44:45], v[34:35], v[50:51]
	v_fmac_f32_e32 v32, v47, v47
	v_fmac_f32_e32 v32, v44, v44
	v_fmac_f32_e32 v32, v45, v45
	v_add_f32_e32 v35, v52, v32
	ds_bpermute_b32 v50, v196, v35
	v_lshl_add_u64 v[32:33], s[76:77], 0, v[98:99]
	v_lshl_add_u64 v[48:49], v[170:171], 1, v[32:33]
	v_cvt_pk_bf16_f32 v34, v36, v37
	v_cvt_pk_bf16_f32 v36, v46, v47
	s_waitcnt lgkmcnt(0)
	v_add_f32_e32 v32, v35, v50
	ds_bpermute_b32 v33, v195, v32
	v_cvt_pk_bf16_f32 v35, v38, v39
	v_cvt_pk_bf16_f32 v37, v44, v45
	global_store_dwordx4 v[48:49], v[40:43], off
	global_store_dwordx4 v[48:49], v[34:37], off offset:256
	s_and_saveexec_b64 s[4:5], s[0:1]
	s_cbranch_execz .LBB0_697
	s_waitcnt lgkmcnt(0)
	v_add_f32_e32 v34, v32, v33
	s_lshl_b32 s22, s10, 2
	v_lshlrev_b64 v[32:33], 6, v[96:97]
	s_ashr_i32 s23, s22, 31
	v_lshl_add_u64 v[32:33], s[6:7], 0, v[32:33]
	v_lshl_add_u64 v[32:33], s[22:23], 2, v[32:33]
	s_lshl_b32 s12, s37, 2
	v_lshl_add_u64 v[32:33], v[32:33], 0, s[12:13]
	global_store_dword v[32:33], v34, off
; __device__ __forceinline__ unsigned pk2(float lo, float hi) { const f32x2 v = (f32x2){lo, hi}; const bf16x2_t b = __builtin_convertvector(v, bf16x2_t); return __builtin_bit_cast(unsigned, b); }
; __device__ __forceinline__ void unpack8(const u32x4 v, float* f) { f[0] = bf_lo(v.x); f[1] = bf_hi(v.x); f[2] = bf_lo(v.y); f[3] = bf_hi(v.y); f[4] = bf_lo(v.z); f[5] = bf_hi(v.z); f[6] = bf_lo(v.w); f[7] = bf_hi(v.w); }
;     __device__ __forceinline__ void operator()(const f32x4 (&acc)[2][2][4][2], const Unit& u, int wr, int wc, int fr, int fq, const float (&)[8]) const {
;     ...
;             for (int m = 0; m < 4; ++m) { const int row = row0 + ai * HALF + m * 16; const size_t ro = (size_t)row * DM + col0; float s = 0.f;
; #pragma unroll
;                 for (int bj = 0; bj < 2; ++bj) { float b8[8]; unpack8(bv[m][bj], b8);
;                     const f32x4 v0 = (f32x4){b8[0], b8[1], b8[2], b8[3]} + acc[ai][bj][m][0], v1 = (f32x4){b8[4], b8[5], b8[6], b8[7]} + acc[ai][bj][m][1];
;                     s += v0[0] * v0[0] + v0[1] * v0[1] + v0[2] * v0[2] + v0[3] * v0[3] + v1[0] * v1[0] + v1[1] * v1[1] + v1[2] * v1[2] + v1[3] * v1[3];
;                     if (LAST) { *(f32x4*)(out + ro + bj * HALF) = v0; *(f32x4*)(out + ro + bj * HALF + 4) = v1; }
;                     else { u32x4 w; w.x = pk2(v0[0], v0[1]); w.y = pk2(v0[2], v0[3]); w.z = pk2(v1[0], v1[1]); w.w = pk2(v1[2], v1[3]); *(u32x4*)(xb + ro + bj * HALF) = w; } }
;                 s += __shfl_xor(s, 16); s += __shfl_xor(s, 32);
;                 if (fq == 0) ss[(size_t)row * 16 + u.pn * 4 + wc] = s; }
.LBB0_697:
	s_or_b64 exec, exec, s[4:5]
	s_nop 0
	v_lshlrev_b32_e32 v32, 16, v76
	s_waitcnt lgkmcnt(0)
	v_and_b32_e32 v33, 0xffff0000, v76
	v_lshlrev_b32_e32 v36, 16, v78
	v_and_b32_e32 v37, 0xffff0000, v78
	v_lshlrev_b32_e32 v38, 16, v79
	v_and_b32_e32 v39, 0xffff0000, v79
	v_pk_add_f32 v[28:29], v[28:29], v[32:33]
	v_lshlrev_b32_e32 v34, 16, v77
	v_and_b32_e32 v35, 0xffff0000, v77
	v_pk_add_f32 v[32:33], v[26:27], v[38:39]
	v_pk_add_f32 v[26:27], v[24:25], v[36:37]
	v_mul_f32_e32 v36, v29, v29
	v_pk_add_f32 v[30:31], v[30:31], v[34:35]
	v_fmac_f32_e32 v36, v28, v28
	v_fmac_f32_e32 v36, v30, v30
	v_fmac_f32_e32 v36, v31, v31
	v_fmac_f32_e32 v36, v26, v26
	v_fmac_f32_e32 v36, v27, v27
	v_fmac_f32_e32 v36, v32, v32
	v_cvt_pk_bf16_f32 v24, v28, v29
	s_nop 0
	v_lshlrev_b32_e32 v28, 16, v72
	v_and_b32_e32 v29, 0xffff0000, v72
	v_fmac_f32_e32 v36, v33, v33
	v_cvt_pk_bf16_f32 v25, v30, v31
	v_cvt_pk_bf16_f32 v26, v26, v27
	v_cvt_pk_bf16_f32 v27, v32, v33
	v_lshlrev_b32_e32 v30, 16, v73
	v_and_b32_e32 v31, 0xffff0000, v73
	v_lshlrev_b32_e32 v32, 16, v74
	v_and_b32_e32 v33, 0xffff0000, v74
	v_pk_add_f32 v[20:21], v[20:21], v[28:29]
	v_pk_add_f32 v[22:23], v[22:23], v[30:31]
	v_pk_add_f32 v[30:31], v[16:17], v[32:33]
	v_mul_f32_e32 v16, v21, v21
	v_fmac_f32_e32 v16, v20, v20
	v_fmac_f32_e32 v16, v22, v22
	v_fmac_f32_e32 v16, v23, v23
	v_lshlrev_b32_e32 v34, 16, v75
	v_and_b32_e32 v35, 0xffff0000, v75
	v_fmac_f32_e32 v16, v30, v30
	v_pk_add_f32 v[28:29], v[18:19], v[34:35]
	v_fmac_f32_e32 v16, v31, v31
	v_fmac_f32_e32 v16, v28, v28
	v_fmac_f32_e32 v16, v29, v29
	v_add_f32_e32 v19, v36, v16
	ds_bpermute_b32 v34, v196, v19
	v_lshl_add_u64 v[16:17], s[76:77], 0, v[94:95]
	v_lshl_add_u64 v[32:33], v[170:171], 1, v[16:17]
	v_cvt_pk_bf16_f32 v18, v20, v21
	v_cvt_pk_bf16_f32 v20, v30, v31
	s_waitcnt lgkmcnt(0)
	v_add_f32_e32 v16, v19, v34
	ds_bpermute_b32 v17, v195, v16
	v_cvt_pk_bf16_f32 v19, v22, v23
	v_cvt_pk_bf16_f32 v21, v28, v29
	global_store_dwordx4 v[32:33], v[24:27], off
	global_store_dwordx4 v[32:33], v[18:21], off offset:256
	s_and_saveexec_b64 s[4:5], s[0:1]
	s_cbranch_execz .LBB0_699
	s_waitcnt lgkmcnt(0)
	v_add_f32_e32 v18, v16, v17
	s_lshl_b32 s22, s10, 2
	v_lshlrev_b64 v[16:17], 6, v[92:93]
	s_ashr_i32 s23, s22, 31
	v_lshl_add_u64 v[16:17], s[6:7], 0, v[16:17]
	v_lshl_add_u64 v[16:17], s[22:23], 2, v[16:17]
	s_lshl_b32 s12, s37, 2
	v_lshl_add_u64 v[16:17], v[16:17], 0, s[12:13]
	global_store_dword v[16:17], v18, off
.LBB0_699:
	s_or_b64 exec, exec, s[4:5]
	s_nop 0
	v_lshlrev_b32_e32 v16, 16, v68
	s_waitcnt lgkmcnt(0)
	v_and_b32_e32 v17, 0xffff0000, v68
	v_lshlrev_b32_e32 v20, 16, v70
	v_and_b32_e32 v21, 0xffff0000, v70
	v_lshlrev_b32_e32 v22, 16, v71
	v_and_b32_e32 v23, 0xffff0000, v71
	v_pk_add_f32 v[12:13], v[12:13], v[16:17]
	v_lshlrev_b32_e32 v18, 16, v69
	v_and_b32_e32 v19, 0xffff0000, v69
	v_pk_add_f32 v[16:17], v[10:11], v[22:23]
	v_pk_add_f32 v[10:11], v[8:9], v[20:21]
	v_mul_f32_e32 v20, v13, v13
	v_pk_add_f32 v[14:15], v[14:15], v[18:19]
	v_fmac_f32_e32 v20, v12, v12
	v_fmac_f32_e32 v20, v14, v14
	v_fmac_f32_e32 v20, v15, v15
	v_fmac_f32_e32 v20, v10, v10
	v_fmac_f32_e32 v20, v11, v11
	v_fmac_f32_e32 v20, v16, v16
	v_cvt_pk_bf16_f32 v8, v12, v13
	s_nop 0
	v_lshlrev_b32_e32 v12, 16, v64
	v_and_b32_e32 v13, 0xffff0000, v64
	v_fmac_f32_e32 v20, v17, v17
	v_cvt_pk_bf16_f32 v9, v14, v15
	v_cvt_pk_bf16_f32 v10, v10, v11
	v_cvt_pk_bf16_f32 v11, v16, v17
	v_lshlrev_b32_e32 v14, 16, v65
	v_and_b32_e32 v15, 0xffff0000, v65
	v_lshlrev_b32_e32 v16, 16, v66
	v_and_b32_e32 v17, 0xffff0000, v66
	v_pk_add_f32 v[4:5], v[4:5], v[12:13]
	v_pk_add_f32 v[6:7], v[6:7], v[14:15]
	v_pk_add_f32 v[14:15], v[0:1], v[16:17]
	v_mul_f32_e32 v0, v5, v5
	v_fmac_f32_e32 v0, v4, v4
	v_fmac_f32_e32 v0, v6, v6
	v_fmac_f32_e32 v0, v7, v7
	v_lshlrev_b32_e32 v18, 16, v67
	v_and_b32_e32 v19, 0xffff0000, v67
	v_fmac_f32_e32 v0, v14, v14
	v_pk_add_f32 v[12:13], v[2:3], v[18:19]
	v_fmac_f32_e32 v0, v15, v15
	v_fmac_f32_e32 v0, v12, v12
	v_fmac_f32_e32 v0, v13, v13
	v_add_f32_e32 v3, v20, v0
	ds_bpermute_b32 v18, v196, v3
	v_lshl_add_u64 v[0:1], s[76:77], 0, v[90:91]
	v_lshl_add_u64 v[16:17], v[170:171], 1, v[0:1]
	v_cvt_pk_bf16_f32 v2, v4, v5
	v_cvt_pk_bf16_f32 v4, v14, v15
	s_waitcnt lgkmcnt(0)
	v_add_f32_e32 v0, v3, v18
	ds_bpermute_b32 v1, v195, v0
	v_cvt_pk_bf16_f32 v3, v6, v7
	v_cvt_pk_bf16_f32 v5, v12, v13
	global_store_dwordx4 v[16:17], v[8:11], off
	global_store_dwordx4 v[16:17], v[2:5], off offset:256
	s_and_saveexec_b64 s[4:5], s[0:1]
	s_cbranch_execz .LBB0_674
	s_waitcnt lgkmcnt(0)
	v_add_f32_e32 v2, v0, v1
	s_lshl_b32 s22, s10, 2
	v_lshlrev_b64 v[0:1], 6, v[88:89]
	s_ashr_i32 s23, s22, 31
	v_lshl_add_u64 v[0:1], s[6:7], 0, v[0:1]
	v_lshl_add_u64 v[0:1], s[22:23], 2, v[0:1]
	s_lshl_b32 s12, s37, 2
	v_lshl_add_u64 v[0:1], v[0:1], 0, s[12:13]
	global_store_dword v[0:1], v2, off
	s_branch .LBB0_674

; #define PG8_STAGE(bufoff, gbase, voff) do { _Pragma("unroll") for (int _i = 0; _i < 2; ++_i) \
;         __builtin_amdgcn_global_load_lds((const unsigned*)((const char*)(gbase) + (voff)[_i]), (LAS unsigned*)(lds + (bufoff) + ldsw + _i * 8192), 16, 0, 0); } while (0)
; #define PG8_LDA(dst, b, h) do { _Pragma("unroll") for (int m = 0; m < 4; ++m) _Pragma("unroll") for (int k = 0; k < 2; ++k) dst[m][k] = *(const LAS bf16x8*)(lds + PG8_SA(b, h) + aoff + m * 2048 + k * 1024); } while (0)
; #define PG8_LDB(dst, b, h) do { _Pragma("unroll") for (int n = 0; n < 2; ++n) _Pragma("unroll") for (int k = 0; k < 2; ++k) dst[n][k] = *(const LAS bf16x8*)(lds + PG8_SB(b, h) + boff + n * 2048 + k * 1024); } while (0)
; #define PG8_MMA(ai, bj, At, Bt) do { __builtin_amdgcn_s_setprio(1); _Pragma("unroll") for (int m = 0; m < 4; ++m) _Pragma("unroll") for (int n = 0; n < 2; ++n) _Pragma("unroll") for (int k = 0; k < 2; ++k) \
;         acc[ai][bj][m][n] = __builtin_amdgcn_mfma_f32_16x16x32_bf16(Bt[n][k], At[m][k], acc[ai][bj][m][n], 0, 0, 0); __builtin_amdgcn_s_setprio(0); } while (0)
; #define PG8_WAIT_L(n) asm volatile("s_waitcnt lgkmcnt(" #n ")" ::: "memory")
; #define PG8_BAR __builtin_amdgcn_s_barrier()
; #define PG8_SCHED __builtin_amdgcn_sched_barrier(0)
; template <class Epi>
; __device__ __forceinline__ void gemm_phase(LAS unsigned char* lds, const Gemm g, const StaticOrder& S, const Epi& E) {
;     ...
;             PG8_LDB(B0, 0, 0); PG8_SCHED; PG8_LDA(At, 0, 0); PG8_STAGE(PG8_SA(1, 1), a1 + hstepA, voffA);
;             PG8_WAIT_L(8); PG8_BAR; PG8_WAIT_L(0); PG8_MMA(0, 0, At, B0); PG8_BAR; PG8_SCHED;
;             PG8_LDB(B1, 0, 1); PG8_STAGE(PG8_SB(0, 0), b2, voffB);
;             PG8_BAR; PG8_WAIT_L(0); PG8_MMA(0, 1, At, B1); PG8_BAR;
;             PG8_LDA(At, 0, 1); PG8_STAGE(PG8_SA(0, 0), a2, voffA);
;             PG8_BAR; PG8_WAIT_L(0); PG8_MMA(1, 0, At, B0); PG8_BAR; PG8_SCHED;
.LBB0_844:
	ds_read_b128 v[128:131], v191
	ds_read_b128 v[132:135], v191 offset:1024
	ds_read_b128 v[136:139], v191 offset:2048
	ds_read_b128 v[140:143], v191 offset:3072
	s_add_u32 s24, s22, 0xfff00080
	s_addc_u32 s25, s23, -1
	s_cmp_eq_u32 s48, 60
	s_cselect_b32 s27, s17, s25
	s_cselect_b32 s26, s44, s24
	s_cselect_b32 s25, s15, s47
	s_cselect_b32 s24, s45, s46
	v_lshl_add_u64 v[186:187], s[22:23], 0, v[162:163]
	s_add_i32 m0, s7, 0xc000
	ds_read_b128 v[144:147], v192
	ds_read_b128 v[148:151], v192 offset:1024
	ds_read_b128 v[170:173], v192 offset:2048
	ds_read_b128 v[174:177], v192 offset:3072
	ds_read_b128 v[178:181], v192 offset:4096
	ds_read_b128 v[182:185], v192 offset:5120
	ds_read_b128 v[196:199], v192 offset:6144
	ds_read_b128 v[200:203], v192 offset:7168
	global_load_lds_dwordx4 v[186:187], off
	v_lshl_add_u64 v[186:187], s[22:23], 0, v[164:165]
	s_add_i32 m0, s7, 0xe000
	s_nop 0
	global_load_lds_dwordx4 v[186:187], off
	s_waitcnt lgkmcnt(8)
	s_barrier
	s_waitcnt lgkmcnt(0)
	s_setprio 1
	s_waitcnt lgkmcnt(0)
	v_mfma_f32_16x16x32_bf16 v[124:127], v[128:131], v[144:147], v[124:127]
	v_mfma_f32_16x16x32_bf16 v[120:123], v[136:139], v[144:147], v[120:123]
	v_mfma_f32_16x16x32_bf16 v[108:111], v[128:131], v[170:173], v[108:111]
	v_mfma_f32_16x16x32_bf16 v[104:107], v[136:139], v[170:173], v[104:107]
	v_mfma_f32_16x16x32_bf16 v[92:95], v[128:131], v[178:181], v[92:95]
	v_mfma_f32_16x16x32_bf16 v[88:91], v[136:139], v[178:181], v[88:91]
	v_mfma_f32_16x16x32_bf16 v[76:79], v[128:131], v[196:199], v[76:79]
	v_mfma_f32_16x16x32_bf16 v[72:75], v[136:139], v[196:199], v[72:75]
	v_mfma_f32_16x16x32_bf16 v[124:127], v[132:135], v[148:151], v[124:127]
	v_mfma_f32_16x16x32_bf16 v[120:123], v[140:143], v[148:151], v[120:123]
	v_mfma_f32_16x16x32_bf16 v[108:111], v[132:135], v[174:177], v[108:111]
	v_mfma_f32_16x16x32_bf16 v[104:107], v[140:143], v[174:177], v[104:107]
	v_mfma_f32_16x16x32_bf16 v[92:95], v[132:135], v[182:185], v[92:95]
	v_mfma_f32_16x16x32_bf16 v[88:91], v[140:143], v[182:185], v[88:91]
	v_mfma_f32_16x16x32_bf16 v[76:79], v[132:135], v[200:203], v[76:79]
	v_mfma_f32_16x16x32_bf16 v[72:75], v[140:143], v[200:203], v[72:75]
	s_setprio 0
	s_barrier
	s_add_i32 s49, s42, s31
	v_lshl_add_u64 v[186:187], s[24:25], 0, v[156:157]
	s_mov_b32 m0, s49
	ds_read_b128 v[204:207], v193
	ds_read_b128 v[208:211], v193 offset:1024
	ds_read_b128 v[212:215], v193 offset:2048
	ds_read_b128 v[216:219], v193 offset:3072
	global_load_lds_dwordx4 v[186:187], off
	v_lshl_add_u64 v[220:221], s[24:25], 0, v[160:161]
	s_add_i32 m0, s49, 0x2000
	s_nop 0
	global_load_lds_dwordx4 v[220:221], off
	s_barrier
	s_waitcnt lgkmcnt(0)
	s_setprio 1
	s_waitcnt lgkmcnt(0)
	v_mfma_f32_16x16x32_bf16 v[116:119], v[204:207], v[144:147], v[116:119]
	v_mfma_f32_16x16x32_bf16 v[112:115], v[212:215], v[144:147], v[112:115]
	v_mfma_f32_16x16x32_bf16 v[100:103], v[204:207], v[170:173], v[100:103]
	v_mfma_f32_16x16x32_bf16 v[96:99], v[212:215], v[170:173], v[96:99]
	v_mfma_f32_16x16x32_bf16 v[84:87], v[204:207], v[178:181], v[84:87]
	v_mfma_f32_16x16x32_bf16 v[80:83], v[212:215], v[178:181], v[80:83]
	v_mfma_f32_16x16x32_bf16 v[68:71], v[204:207], v[196:199], v[68:71]
	v_mfma_f32_16x16x32_bf16 v[64:67], v[212:215], v[196:199], v[64:67]
	v_mfma_f32_16x16x32_bf16 v[116:119], v[208:211], v[148:151], v[116:119]
	v_mfma_f32_16x16x32_bf16 v[112:115], v[216:219], v[148:151], v[112:115]
	v_mfma_f32_16x16x32_bf16 v[100:103], v[208:211], v[174:177], v[100:103]
	v_mfma_f32_16x16x32_bf16 v[96:99], v[216:219], v[174:177], v[96:99]
	v_mfma_f32_16x16x32_bf16 v[84:87], v[208:211], v[182:185], v[84:87]
	v_mfma_f32_16x16x32_bf16 v[80:83], v[216:219], v[182:185], v[80:83]
	v_mfma_f32_16x16x32_bf16 v[68:71], v[208:211], v[200:203], v[68:71]
	v_mfma_f32_16x16x32_bf16 v[64:67], v[216:219], v[200:203], v[64:67]
	s_setprio 0
	s_mov_b32 m0, s7
	v_lshl_add_u64 v[222:223], s[26:27], 0, v[154:155]
	s_barrier
	ds_read_b128 v[144:147], v192 offset:16384
	ds_read_b128 v[148:151], v192 offset:17408
	ds_read_b128 v[170:173], v192 offset:18432
	ds_read_b128 v[174:177], v192 offset:19456
	ds_read_b128 v[178:181], v192 offset:20480
	ds_read_b128 v[182:185], v192 offset:21504
	ds_read_b128 v[196:199], v192 offset:22528
	ds_read_b128 v[200:203], v192 offset:23552
	global_load_lds_dwordx4 v[222:223], off
	v_lshl_add_u64 v[224:225], s[26:27], 0, v[158:159]
	s_mov_b32 m0, s34
	s_nop 0
	global_load_lds_dwordx4 v[224:225], off
	s_barrier
	s_waitcnt lgkmcnt(0)
	s_setprio 1
	s_waitcnt lgkmcnt(0)
	v_mfma_f32_16x16x32_bf16 v[60:63], v[128:131], v[144:147], v[60:63]
	v_mfma_f32_16x16x32_bf16 v[56:59], v[136:139], v[144:147], v[56:59]
	v_mfma_f32_16x16x32_bf16 v[44:47], v[128:131], v[170:173], v[44:47]
	v_mfma_f32_16x16x32_bf16 v[40:43], v[136:139], v[170:173], v[40:43]
	v_mfma_f32_16x16x32_bf16 v[28:31], v[128:131], v[178:181], v[28:31]
	v_mfma_f32_16x16x32_bf16 v[24:27], v[136:139], v[178:181], v[24:27]
	v_mfma_f32_16x16x32_bf16 v[12:15], v[128:131], v[196:199], v[12:15]
	v_mfma_f32_16x16x32_bf16 v[8:11], v[136:139], v[196:199], v[8:11]
	v_mfma_f32_16x16x32_bf16 v[60:63], v[132:135], v[148:151], v[60:63]
	v_mfma_f32_16x16x32_bf16 v[56:59], v[140:143], v[148:151], v[56:59]
	v_mfma_f32_16x16x32_bf16 v[44:47], v[132:135], v[174:177], v[44:47]
	v_mfma_f32_16x16x32_bf16 v[40:43], v[140:143], v[174:177], v[40:43]
	v_mfma_f32_16x16x32_bf16 v[28:31], v[132:135], v[182:185], v[28:31]
	v_mfma_f32_16x16x32_bf16 v[24:27], v[140:143], v[182:185], v[24:27]
	v_mfma_f32_16x16x32_bf16 v[12:15], v[132:135], v[200:203], v[12:15]
	v_mfma_f32_16x16x32_bf16 v[8:11], v[140:143], v[200:203], v[8:11]
	s_setprio 0
	s_barrier
; #define PG8_STAGE(bufoff, gbase, voff) do { _Pragma("unroll") for (int _i = 0; _i < 2; ++_i) \
;         __builtin_amdgcn_global_load_lds((const unsigned*)((const char*)(gbase) + (voff)[_i]), (LAS unsigned*)(lds + (bufoff) + ldsw + _i * 8192), 16, 0, 0); } while (0)
; #define PG8_LDA(dst, b, h) do { _Pragma("unroll") for (int m = 0; m < 4; ++m) _Pragma("unroll") for (int k = 0; k < 2; ++k) dst[m][k] = *(const LAS bf16x8*)(lds + PG8_SA(b, h) + aoff + m * 2048 + k * 1024); } while (0)
; #define PG8_LDB(dst, b, h) do { _Pragma("unroll") for (int n = 0; n < 2; ++n) _Pragma("unroll") for (int k = 0; k < 2; ++k) dst[n][k] = *(const LAS bf16x8*)(lds + PG8_SB(b, h) + boff + n * 2048 + k * 1024); } while (0)
; #define PG8_MMA(ai, bj, At, Bt) do { __builtin_amdgcn_s_setprio(1); _Pragma("unroll") for (int m = 0; m < 4; ++m) _Pragma("unroll") for (int n = 0; n < 2; ++n) _Pragma("unroll") for (int k = 0; k < 2; ++k) \
;         acc[ai][bj][m][n] = __builtin_amdgcn_mfma_f32_16x16x32_bf16(Bt[n][k], At[m][k], acc[ai][bj][m][n], 0, 0, 0); __builtin_amdgcn_s_setprio(0); } while (0)
; #define PG8_WAIT_V(n) asm volatile("s_waitcnt vmcnt(" #n ")" ::: "memory")
; #define PG8_WAIT_L(n) asm volatile("s_waitcnt lgkmcnt(" #n ")" ::: "memory")
; #define PG8_BAR __builtin_amdgcn_s_barrier()
; #define PG8_SCHED __builtin_amdgcn_sched_barrier(0)
; template <class Epi>
; __device__ __forceinline__ void gemm_phase(LAS unsigned char* lds, const Gemm g, const StaticOrder& S, const Epi& E) {
;     ...
;             PG8_STAGE(PG8_SB(0, 1), b2 + hstepB, voffB);
;             PG8_WAIT_V(6); PG8_BAR; PG8_MMA(1, 1, At, B1); PG8_BAR;
;             PG8_LDB(B0, 1, 0); PG8_SCHED; PG8_LDA(At, 1, 0); PG8_STAGE(PG8_SA(0, 1), a2 + hstepA, voffA);
;             PG8_WAIT_L(8); PG8_BAR; PG8_WAIT_L(0); PG8_MMA(0, 0, At, B0); PG8_BAR; PG8_SCHED;
;             PG8_LDB(B1, 1, 1); PG8_STAGE(PG8_SB(1, 0), b3, voffB);
;             PG8_BAR; PG8_WAIT_L(0); PG8_MMA(0, 1, At, B1); PG8_BAR;
;             PG8_LDA(At, 1, 1); PG8_STAGE(PG8_SA(1, 0), a3, voffA);
;             PG8_BAR; PG8_WAIT_L(0); PG8_MMA(1, 0, At, B0); PG8_BAR; PG8_SCHED;
	s_add_u32 s50, s24, 0x100000
	s_addc_u32 s51, s25, 0
	s_add_i32 s49, s43, s31
	v_lshl_add_u64 v[128:129], s[50:51], 0, v[156:157]
	s_mov_b32 m0, s49
	s_nop 0
	global_load_lds_dwordx4 v[128:129], off
	v_lshl_add_u64 v[128:129], s[50:51], 0, v[160:161]
	s_add_i32 m0, s49, 0x2000
	s_nop 0
	global_load_lds_dwordx4 v[128:129], off
	s_waitcnt vmcnt(6)
	s_barrier
	s_setprio 1
	v_mfma_f32_16x16x32_bf16 v[52:55], v[204:207], v[144:147], v[52:55]
	v_mfma_f32_16x16x32_bf16 v[48:51], v[212:215], v[144:147], v[48:51]
	v_mfma_f32_16x16x32_bf16 v[36:39], v[204:207], v[170:173], v[36:39]
	v_mfma_f32_16x16x32_bf16 v[32:35], v[212:215], v[170:173], v[32:35]
	v_mfma_f32_16x16x32_bf16 v[20:23], v[204:207], v[178:181], v[20:23]
	v_mfma_f32_16x16x32_bf16 v[16:19], v[212:215], v[178:181], v[16:19]
	v_mfma_f32_16x16x32_bf16 v[4:7], v[204:207], v[196:199], v[4:7]
	v_mfma_f32_16x16x32_bf16 v[0:3], v[212:215], v[196:199], v[0:3]
	v_mfma_f32_16x16x32_bf16 v[52:55], v[208:211], v[148:151], v[52:55]
	v_mfma_f32_16x16x32_bf16 v[48:51], v[216:219], v[148:151], v[48:51]
	v_mfma_f32_16x16x32_bf16 v[36:39], v[208:211], v[174:177], v[36:39]
	v_mfma_f32_16x16x32_bf16 v[32:35], v[216:219], v[174:177], v[32:35]
	v_mfma_f32_16x16x32_bf16 v[20:23], v[208:211], v[182:185], v[20:23]
	v_mfma_f32_16x16x32_bf16 v[16:19], v[216:219], v[182:185], v[16:19]
	v_mfma_f32_16x16x32_bf16 v[4:7], v[208:211], v[200:203], v[4:7]
	v_mfma_f32_16x16x32_bf16 v[0:3], v[216:219], v[200:203], v[0:3]
	s_setprio 0
	s_add_i32 s49, 0, 0x18000
	v_add_u32_e32 v140, s49, v189
	s_barrier
	ds_read_b128 v[128:131], v140
	ds_read_b128 v[132:135], v140 offset:1024
	ds_read_b128 v[136:139], v140 offset:2048
	ds_read_b128 v[140:143], v140 offset:3072
	s_add_u32 s26, s26, 0x100000
	s_addc_u32 s27, s27, 0
	s_mov_b32 m0, s35
	v_lshl_add_u64 v[204:205], s[26:27], 0, v[154:155]
	ds_read_b128 v[144:147], v192 offset:32768
	ds_read_b128 v[148:151], v192 offset:33792
	ds_read_b128 v[170:173], v192 offset:34816
	ds_read_b128 v[174:177], v192 offset:35840
	ds_read_b128 v[178:181], v192 offset:36864
	ds_read_b128 v[182:185], v192 offset:37888
	ds_read_b128 v[196:199], v192 offset:38912
	ds_read_b128 v[200:203], v192 offset:39936
	global_load_lds_dwordx4 v[204:205], off
	v_lshl_add_u64 v[204:205], s[26:27], 0, v[158:159]
	s_mov_b32 m0, s36
	s_nop 0
	global_load_lds_dwordx4 v[204:205], off
	s_waitcnt lgkmcnt(8)
	s_barrier
	s_waitcnt lgkmcnt(0)
	s_setprio 1
	s_waitcnt lgkmcnt(0)
	v_mfma_f32_16x16x32_bf16 v[124:127], v[128:131], v[144:147], v[124:127]
	v_mfma_f32_16x16x32_bf16 v[120:123], v[136:139], v[144:147], v[120:123]
	v_mfma_f32_16x16x32_bf16 v[108:111], v[128:131], v[170:173], v[108:111]
	v_mfma_f32_16x16x32_bf16 v[104:107], v[136:139], v[170:173], v[104:107]
	v_mfma_f32_16x16x32_bf16 v[92:95], v[128:131], v[178:181], v[92:95]
	v_mfma_f32_16x16x32_bf16 v[88:91], v[136:139], v[178:181], v[88:91]
	v_mfma_f32_16x16x32_bf16 v[76:79], v[128:131], v[196:199], v[76:79]
	v_mfma_f32_16x16x32_bf16 v[72:75], v[136:139], v[196:199], v[72:75]
	v_mfma_f32_16x16x32_bf16 v[124:127], v[132:135], v[148:151], v[124:127]
	v_mfma_f32_16x16x32_bf16 v[120:123], v[140:143], v[148:151], v[120:123]
	v_mfma_f32_16x16x32_bf16 v[108:111], v[132:135], v[174:177], v[108:111]
	v_mfma_f32_16x16x32_bf16 v[104:107], v[140:143], v[174:177], v[104:107]
	v_mfma_f32_16x16x32_bf16 v[92:95], v[132:135], v[182:185], v[92:95]
	v_mfma_f32_16x16x32_bf16 v[88:91], v[140:143], v[182:185], v[88:91]
	v_mfma_f32_16x16x32_bf16 v[76:79], v[132:135], v[200:203], v[76:79]
	v_mfma_f32_16x16x32_bf16 v[72:75], v[140:143], v[200:203], v[72:75]
	s_setprio 0
	s_barrier
	s_add_i32 s26, 0, 0x1c000
	s_add_i32 s27, s49, s31
	v_add_u32_e32 v195, s26, v189
	v_lshl_add_u64 v[186:187], v[186:187], 0, s[12:13]
	s_mov_b32 m0, s27
	ds_read_b128 v[204:207], v195
	ds_read_b128 v[208:211], v195 offset:1024
	ds_read_b128 v[212:215], v195 offset:2048
	ds_read_b128 v[216:219], v195 offset:3072
	global_load_lds_dwordx4 v[186:187], off
	v_lshl_add_u64 v[186:187], v[220:221], 0, s[12:13]
	s_add_i32 m0, s27, 0x2000
	s_nop 0
	global_load_lds_dwordx4 v[186:187], off
	s_barrier
	s_waitcnt lgkmcnt(0)
	s_setprio 1
	s_waitcnt lgkmcnt(0)
	v_mfma_f32_16x16x32_bf16 v[116:119], v[204:207], v[144:147], v[116:119]
	v_mfma_f32_16x16x32_bf16 v[112:115], v[212:215], v[144:147], v[112:115]
	v_mfma_f32_16x16x32_bf16 v[100:103], v[204:207], v[170:173], v[100:103]
	v_mfma_f32_16x16x32_bf16 v[96:99], v[212:215], v[170:173], v[96:99]
	v_mfma_f32_16x16x32_bf16 v[84:87], v[204:207], v[178:181], v[84:87]
	v_mfma_f32_16x16x32_bf16 v[80:83], v[212:215], v[178:181], v[80:83]
	v_mfma_f32_16x16x32_bf16 v[68:71], v[204:207], v[196:199], v[68:71]
	v_mfma_f32_16x16x32_bf16 v[64:67], v[212:215], v[196:199], v[64:67]
	v_mfma_f32_16x16x32_bf16 v[116:119], v[208:211], v[148:151], v[116:119]
	v_mfma_f32_16x16x32_bf16 v[112:115], v[216:219], v[148:151], v[112:115]
	v_mfma_f32_16x16x32_bf16 v[100:103], v[208:211], v[174:177], v[100:103]
	v_mfma_f32_16x16x32_bf16 v[96:99], v[216:219], v[174:177], v[96:99]
	v_mfma_f32_16x16x32_bf16 v[84:87], v[208:211], v[182:185], v[84:87]
	v_mfma_f32_16x16x32_bf16 v[80:83], v[216:219], v[182:185], v[80:83]
	v_mfma_f32_16x16x32_bf16 v[68:71], v[208:211], v[200:203], v[68:71]
	v_mfma_f32_16x16x32_bf16 v[64:67], v[216:219], v[200:203], v[64:67]
	s_setprio 0
	s_mov_b32 m0, s38
	v_lshl_add_u64 v[186:187], v[222:223], 0, s[12:13]
	s_barrier
	ds_read_b128 v[144:147], v192 offset:49152
	ds_read_b128 v[148:151], v192 offset:50176
	ds_read_b128 v[170:173], v192 offset:51200
	ds_read_b128 v[174:177], v192 offset:52224
	ds_read_b128 v[178:181], v192 offset:53248
	ds_read_b128 v[182:185], v192 offset:54272
	ds_read_b128 v[196:199], v192 offset:55296
	ds_read_b128 v[200:203], v192 offset:56320
	global_load_lds_dwordx4 v[186:187], off
	v_lshl_add_u64 v[186:187], v[224:225], 0, s[12:13]
	s_mov_b32 m0, s39
	s_nop 0
	global_load_lds_dwordx4 v[186:187], off
	s_barrier
; #define PG8_STAGE(bufoff, gbase, voff) do { _Pragma("unroll") for (int _i = 0; _i < 2; ++_i) \
;         __builtin_amdgcn_global_load_lds((const unsigned*)((const char*)(gbase) + (voff)[_i]), (LAS unsigned*)(lds + (bufoff) + ldsw + _i * 8192), 16, 0, 0); } while (0)
; #define PG8_LDA(dst, b, h) do { _Pragma("unroll") for (int m = 0; m < 4; ++m) _Pragma("unroll") for (int k = 0; k < 2; ++k) dst[m][k] = *(const LAS bf16x8*)(lds + PG8_SA(b, h) + aoff + m * 2048 + k * 1024); } while (0)
; #define PG8_MMA(ai, bj, At, Bt) do { __builtin_amdgcn_s_setprio(1); _Pragma("unroll") for (int m = 0; m < 4; ++m) _Pragma("unroll") for (int n = 0; n < 2; ++n) _Pragma("unroll") for (int k = 0; k < 2; ++k) \
;         acc[ai][bj][m][n] = __builtin_amdgcn_mfma_f32_16x16x32_bf16(Bt[n][k], At[m][k], acc[ai][bj][m][n], 0, 0, 0); __builtin_amdgcn_s_setprio(0); } while (0)
; #define PG8_WAIT_V(n) asm volatile("s_waitcnt vmcnt(" #n ")" ::: "memory")
; #define PG8_WAIT_L(n) asm volatile("s_waitcnt lgkmcnt(" #n ")" ::: "memory")
; #define PG8_BAR __builtin_amdgcn_s_barrier()
; #define PG8_SCHED __builtin_amdgcn_sched_barrier(0)
; template <class Epi>
; __device__ __forceinline__ void gemm_phase(LAS unsigned char* lds, const Gemm g, const StaticOrder& S, const Epi& E) {
;     ...
;             PG8_BAR; PG8_WAIT_L(0); PG8_MMA(0, 1, At, B1); PG8_BAR;
;             PG8_LDA(At, 1, 1); PG8_STAGE(PG8_SA(1, 0), a3, voffA);
;             PG8_BAR; PG8_WAIT_L(0); PG8_MMA(1, 0, At, B0); PG8_BAR; PG8_SCHED;
;             PG8_STAGE(PG8_SB(1, 1), b3 + hstepB, voffB);
;             PG8_WAIT_V(6); PG8_BAR; PG8_MMA(1, 1, At, B1); PG8_BAR;
;         }
	s_waitcnt lgkmcnt(0)
	s_setprio 1
	s_waitcnt lgkmcnt(0)
	v_mfma_f32_16x16x32_bf16 v[60:63], v[128:131], v[144:147], v[60:63]
	v_mfma_f32_16x16x32_bf16 v[56:59], v[136:139], v[144:147], v[56:59]
	v_mfma_f32_16x16x32_bf16 v[44:47], v[128:131], v[170:173], v[44:47]
	v_mfma_f32_16x16x32_bf16 v[40:43], v[136:139], v[170:173], v[40:43]
	v_mfma_f32_16x16x32_bf16 v[28:31], v[128:131], v[178:181], v[28:31]
	v_mfma_f32_16x16x32_bf16 v[24:27], v[136:139], v[178:181], v[24:27]
	v_mfma_f32_16x16x32_bf16 v[12:15], v[128:131], v[196:199], v[12:15]
	v_mfma_f32_16x16x32_bf16 v[8:11], v[136:139], v[196:199], v[8:11]
	v_mfma_f32_16x16x32_bf16 v[60:63], v[132:135], v[148:151], v[60:63]
	v_mfma_f32_16x16x32_bf16 v[56:59], v[140:143], v[148:151], v[56:59]
	v_mfma_f32_16x16x32_bf16 v[44:47], v[132:135], v[174:177], v[44:47]
	v_mfma_f32_16x16x32_bf16 v[40:43], v[140:143], v[174:177], v[40:43]
	v_mfma_f32_16x16x32_bf16 v[28:31], v[132:135], v[182:185], v[28:31]
	v_mfma_f32_16x16x32_bf16 v[24:27], v[140:143], v[182:185], v[24:27]
	v_mfma_f32_16x16x32_bf16 v[12:15], v[132:135], v[200:203], v[12:15]
	v_mfma_f32_16x16x32_bf16 v[8:11], v[140:143], v[200:203], v[8:11]
	s_setprio 0
	s_barrier
	s_add_u32 s24, s24, 0x100080
	s_addc_u32 s25, s25, 0
	s_add_i32 s26, s26, s31
	v_lshl_add_u64 v[128:129], s[24:25], 0, v[156:157]
	s_mov_b32 m0, s26
	s_nop 0
	global_load_lds_dwordx4 v[128:129], off
	v_lshl_add_u64 v[128:129], s[24:25], 0, v[160:161]
	s_add_i32 m0, s26, 0x2000
	s_nop 0
	global_load_lds_dwordx4 v[128:129], off
	s_waitcnt vmcnt(6)
	s_barrier
	s_setprio 1
	v_mfma_f32_16x16x32_bf16 v[52:55], v[204:207], v[144:147], v[52:55]
	v_mfma_f32_16x16x32_bf16 v[48:51], v[212:215], v[144:147], v[48:51]
	v_mfma_f32_16x16x32_bf16 v[36:39], v[204:207], v[170:173], v[36:39]
	v_mfma_f32_16x16x32_bf16 v[32:35], v[212:215], v[170:173], v[32:35]
	v_mfma_f32_16x16x32_bf16 v[20:23], v[204:207], v[178:181], v[20:23]
	v_mfma_f32_16x16x32_bf16 v[16:19], v[212:215], v[178:181], v[16:19]
	v_mfma_f32_16x16x32_bf16 v[4:7], v[204:207], v[196:199], v[4:7]
	v_mfma_f32_16x16x32_bf16 v[0:3], v[212:215], v[196:199], v[0:3]
	v_mfma_f32_16x16x32_bf16 v[52:55], v[208:211], v[148:151], v[52:55]
	v_mfma_f32_16x16x32_bf16 v[48:51], v[216:219], v[148:151], v[48:51]
	v_mfma_f32_16x16x32_bf16 v[36:39], v[208:211], v[174:177], v[36:39]
	v_mfma_f32_16x16x32_bf16 v[32:35], v[216:219], v[174:177], v[32:35]
	v_mfma_f32_16x16x32_bf16 v[20:23], v[208:211], v[182:185], v[20:23]
	v_mfma_f32_16x16x32_bf16 v[16:19], v[216:219], v[182:185], v[16:19]
	v_mfma_f32_16x16x32_bf16 v[4:7], v[208:211], v[200:203], v[4:7]
	v_mfma_f32_16x16x32_bf16 v[0:3], v[216:219], v[200:203], v[0:3]
	s_setprio 0
	s_add_i32 s48, s48, 2
	s_add_u32 s22, s22, 0x100
	s_addc_u32 s23, s23, 0
	s_add_u32 s46, s46, 0x100
	s_addc_u32 s47, s47, 0
	s_cmp_gt_u32 s48, 61
	s_barrier
	s_cbranch_scc0 .LBB0_844
; __device__ __forceinline__ unsigned pk2(float lo, float hi) { const f32x2 v = (f32x2){lo, hi}; const bf16x2_t b = __builtin_convertvector(v, bf16x2_t); return __builtin_bit_cast(unsigned, b); }
; __device__ __forceinline__ void unpack8(const u32x4 v, float* f) { f[0] = bf_lo(v.x); f[1] = bf_hi(v.x); f[2] = bf_lo(v.y); f[3] = bf_hi(v.y); f[4] = bf_lo(v.z); f[5] = bf_hi(v.z); f[6] = bf_lo(v.w); f[7] = bf_hi(v.w); }
;     __device__ __forceinline__ void operator()(const f32x4 (&acc)[2][2][4][2], const Unit& u, int wr, int wc, int fr, int fq, const float (&)[8]) const {
;         const int row0 = u.pm * BM + wr * 64 + fr, col0 = u.pn * BM + wc * 32 + 8 * fq;
; #pragma unroll
;         for (int ai = 0; ai < 2; ++ai) {
;             u32x4 bv[4][2];
; #pragma unroll
;             for (int m = 0; m < 4; ++m)
; #pragma unroll
;                 for (int bj = 0; bj < 2; ++bj) bv[m][bj] = *(const u32x4*)(xb + (size_t)(row0 + ai * HALF + m * 16) * DM + col0 + bj * HALF);
; #pragma unroll
;             for (int m = 0; m < 4; ++m) { const int row = row0 + ai * HALF + m * 16; const size_t ro = (size_t)row * DM + col0; float s = 0.f;
; #pragma unroll
;                 for (int bj = 0; bj < 2; ++bj) { float b8[8]; unpack8(bv[m][bj], b8);
;                     const f32x4 v0 = (f32x4){b8[0], b8[1], b8[2], b8[3]} + acc[ai][bj][m][0], v1 = (f32x4){b8[4], b8[5], b8[6], b8[7]} + acc[ai][bj][m][1];
;                     s += v0[0] * v0[0] + v0[1] * v0[1] + v0[2] * v0[2] + v0[3] * v0[3] + v1[0] * v1[0] + v1[1] * v1[1] + v1[2] * v1[2] + v1[3] * v1[3];
;                     if (LAST) { *(f32x4*)(out + ro + bj * HALF) = v0; *(f32x4*)(out + ro + bj * HALF + 4) = v1; }
;                     else { u32x4 w; w.x = pk2(v0[0], v0[1]); w.y = pk2(v0[2], v0[3]); w.z = pk2(v1[0], v1[1]); w.w = pk2(v1[2], v1[3]); *(u32x4*)(xb + ro + bj * HALF) = w; } }
;                 s += __shfl_xor(s, 16); s += __shfl_xor(s, 32);
;                 if (fq == 0) ss[(size_t)row * 16 + u.pn * 4 + wc] = s; }
	v_lshl_or_b32 v170, s6, 8, v190
	v_lshl_add_u32 v172, s8, 8, v188
	v_ashrrev_i32_e32 v171, 31, v170
	v_lshlrev_b64 v[206:207], 1, v[170:171]
	v_ashrrev_i32_e32 v173, 31, v172
	v_lshl_add_u64 v[174:175], s[76:77], 0, v[206:207]
	v_lshlrev_b64 v[208:209], 11, v[172:173]
	v_lshl_add_u64 v[128:129], v[174:175], 0, v[208:209]
	global_load_dwordx4 v[198:201], v[128:129], off
	global_load_dwordx4 v[202:205], v[128:129], off offset:256
	v_or_b32_e32 v184, 16, v172
	v_or_b32_e32 v180, 32, v172
	v_or_b32_e32 v176, 48, v172
	v_ashrrev_i32_e32 v185, 31, v184
	v_ashrrev_i32_e32 v181, 31, v180
	v_ashrrev_i32_e32 v177, 31, v176
	v_lshlrev_b64 v[186:187], 11, v[184:185]
	v_lshlrev_b64 v[182:183], 11, v[180:181]
	v_lshlrev_b64 v[178:179], 11, v[176:177]
	v_lshl_add_u64 v[128:129], v[174:175], 0, v[186:187]
	v_lshl_add_u64 v[130:131], v[174:175], 0, v[182:183]
	v_lshl_add_u64 v[196:197], v[174:175], 0, v[178:179]
	global_load_dwordx4 v[148:151], v[128:129], off
	global_load_dwordx4 v[144:147], v[128:129], off offset:256
	global_load_dwordx4 v[140:143], v[130:131], off
	global_load_dwordx4 v[136:139], v[130:131], off offset:256
	global_load_dwordx4 v[132:135], v[196:197], off
	s_nop 0
	global_load_dwordx4 v[128:131], v[196:197], off offset:256
	v_add_u32_e32 v218, 0x80, v172
	v_ashrrev_i32_e32 v219, 31, v218
	v_lshlrev_b64 v[218:219], 11, v[218:219]
	v_lshl_add_u64 v[218:219], v[174:175], 0, v[218:219]
	global_load_dwordx4 v[220:223], v[218:219], off
	global_load_dwordx4 v[224:227], v[218:219], off offset:256
	v_add_u32_e32 v218, 0x90, v172
	v_ashrrev_i32_e32 v219, 31, v218
	v_lshlrev_b64 v[218:219], 11, v[218:219]
	v_lshl_add_u64 v[218:219], v[174:175], 0, v[218:219]
	global_load_dwordx4 v[228:231], v[218:219], off
	global_load_dwordx4 v[232:235], v[218:219], off offset:256
	v_add_u32_e32 v218, 0xa0, v172
	v_ashrrev_i32_e32 v219, 31, v218
	v_lshlrev_b64 v[218:219], 11, v[218:219]
	v_lshl_add_u64 v[218:219], v[174:175], 0, v[218:219]
	global_load_dwordx4 v[236:239], v[218:219], off
	global_load_dwordx4 v[240:243], v[218:219], off offset:256
	v_add_u32_e32 v218, 0xb0, v172
	v_ashrrev_i32_e32 v219, 31, v218
	v_lshlrev_b64 v[218:219], 11, v[218:219]
	v_lshl_add_u64 v[218:219], v[174:175], 0, v[218:219]
	global_load_dwordx4 v[244:247], v[218:219], off
	global_load_dwordx4 v[252:255], v[218:219], off offset:256
	v_and_b32_e32 v196, 64, v194
	v_xor_b32_e32 v195, 16, v194
	v_add_u32_e32 v196, 64, v196
	v_xor_b32_e32 v197, 32, v194
	v_cmp_lt_i32_e32 vcc, v195, v196
	s_waitcnt vmcnt(0)
	v_lshlrev_b32_e32 v210, 16, v198
	v_cndmask_b32_e32 v195, v194, v195, vcc
	v_cmp_lt_i32_e32 vcc, v197, v196
	v_and_b32_e32 v211, 0xffff0000, v198
	v_lshlrev_b32_e32 v214, 16, v202
	v_and_b32_e32 v215, 0xffff0000, v202
	v_cndmask_b32_e32 v197, v194, v197, vcc
	v_lshlrev_b32_e32 v212, 16, v200
	v_and_b32_e32 v213, 0xffff0000, v200
	v_lshlrev_b32_e32 v200, 16, v201
	v_and_b32_e32 v201, 0xffff0000, v201
	v_lshlrev_b32_e32 v216, 16, v204
	v_and_b32_e32 v217, 0xffff0000, v204
	v_pk_add_f32 v[124:125], v[124:125], v[210:211]
	v_pk_add_f32 v[116:117], v[116:117], v[214:215]
	v_lshlrev_b32_e32 v196, 2, v195
	v_lshlrev_b32_e32 v195, 2, v197
	v_lshlrev_b32_e32 v198, 16, v199
	v_and_b32_e32 v199, 0xffff0000, v199
	v_lshlrev_b32_e32 v202, 16, v203
	v_and_b32_e32 v203, 0xffff0000, v203
	v_pk_add_f32 v[122:123], v[122:123], v[200:201]
	v_pk_add_f32 v[200:201], v[112:113], v[216:217]
	v_mul_f32_e32 v197, v125, v125
	v_cvt_pk_bf16_f32 v112, v124, v125
	v_mul_f32_e32 v125, v117, v117
	v_pk_add_f32 v[126:127], v[126:127], v[198:199]
	v_pk_add_f32 v[118:119], v[118:119], v[202:203]
	v_fmac_f32_e32 v197, v124, v124
	v_fmac_f32_e32 v125, v116, v116
	v_fmac_f32_e32 v197, v126, v126
	v_fmac_f32_e32 v125, v118, v118
	v_pk_add_f32 v[120:121], v[120:121], v[212:213]
	v_fmac_f32_e32 v197, v127, v127
	v_fmac_f32_e32 v125, v119, v119
	v_lshlrev_b32_e32 v204, 16, v205
	v_and_b32_e32 v205, 0xffff0000, v205
	v_fmac_f32_e32 v197, v120, v120
	v_fmac_f32_e32 v125, v200, v200
	v_pk_add_f32 v[198:199], v[114:115], v[204:205]
	v_fmac_f32_e32 v197, v121, v121
	v_fmac_f32_e32 v125, v201, v201
	v_fmac_f32_e32 v197, v122, v122
	v_fmac_f32_e32 v125, v198, v198
	v_fmac_f32_e32 v197, v123, v123
	v_fmac_f32_e32 v125, v199, v199
	v_cvt_pk_bf16_f32 v115, v122, v123
	v_add_f32_e32 v122, v197, v125
	ds_bpermute_b32 v123, v196, v122
	v_cvt_pk_bf16_f32 v114, v120, v121
	v_lshl_add_u64 v[120:121], s[76:77], 0, v[208:209]
	v_cvt_pk_bf16_f32 v113, v126, v127
	v_lshl_add_u64 v[120:121], v[120:121], 0, v[206:207]
	global_store_dwordx4 v[120:121], v[112:115], off
	s_waitcnt lgkmcnt(0)
	s_nop 0
	v_add_f32_e32 v112, v122, v123
	ds_bpermute_b32 v113, v195, v112
	v_cvt_pk_bf16_f32 v114, v116, v117
	v_cvt_pk_bf16_f32 v115, v118, v119
	v_cvt_pk_bf16_f32 v116, v200, v201
	v_cvt_pk_bf16_f32 v117, v198, v199
	global_store_dwordx4 v[120:121], v[114:117], off offset:256
	s_and_saveexec_b64 s[22:23], s[0:1]
	s_cbranch_execz .LBB0_847
	s_waitcnt lgkmcnt(0)
	v_add_f32_e32 v114, v112, v113
	s_lshl_b32 s24, s6, 2
	v_lshlrev_b64 v[112:113], 6, v[172:173]
	s_ashr_i32 s25, s24, 31
	v_lshl_add_u64 v[112:113], s[10:11], 0, v[112:113]
	v_lshl_add_u64 v[112:113], s[24:25], 2, v[112:113]
	s_lshl_b32 s8, s37, 2
	v_lshl_add_u64 v[112:113], v[112:113], 0, s[8:9]
	global_store_dword v[112:113], v114, off

; __device__ __forceinline__ unsigned pk2(float lo, float hi) { const f32x2 v = (f32x2){lo, hi}; const bf16x2_t b = __builtin_convertvector(v, bf16x2_t); return __builtin_bit_cast(unsigned, b); }
; __device__ __forceinline__ void unpack8(const u32x4 v, float* f) { f[0] = bf_lo(v.x); f[1] = bf_hi(v.x); f[2] = bf_lo(v.y); f[3] = bf_hi(v.y); f[4] = bf_lo(v.z); f[5] = bf_hi(v.z); f[6] = bf_lo(v.w); f[7] = bf_hi(v.w); }
;     __device__ __forceinline__ void operator()(const f32x4 (&acc)[2][2][4][2], const Unit& u, int wr, int wc, int fr, int fq, const float (&)[8]) const {
;     ...
;                 for (int bj = 0; bj < 2; ++bj) bv[m][bj] = *(const u32x4*)(xb + (size_t)(row0 + ai * HALF + m * 16) * DM + col0 + bj * HALF);
; #pragma unroll
;             for (int m = 0; m < 4; ++m) { const int row = row0 + ai * HALF + m * 16; const size_t ro = (size_t)row * DM + col0; float s = 0.f;
; #pragma unroll
;                 for (int bj = 0; bj < 2; ++bj) { float b8[8]; unpack8(bv[m][bj], b8);
;                     const f32x4 v0 = (f32x4){b8[0], b8[1], b8[2], b8[3]} + acc[ai][bj][m][0], v1 = (f32x4){b8[4], b8[5], b8[6], b8[7]} + acc[ai][bj][m][1];
;                     s += v0[0] * v0[0] + v0[1] * v0[1] + v0[2] * v0[2] + v0[3] * v0[3] + v1[0] * v1[0] + v1[1] * v1[1] + v1[2] * v1[2] + v1[3] * v1[3];
;                     if (LAST) { *(f32x4*)(out + ro + bj * HALF) = v0; *(f32x4*)(out + ro + bj * HALF + 4) = v1; }
;                     else { u32x4 w; w.x = pk2(v0[0], v0[1]); w.y = pk2(v0[2], v0[3]); w.z = pk2(v1[0], v1[1]); w.w = pk2(v1[2], v1[3]); *(u32x4*)(xb + ro + bj * HALF) = w; } }
;                 s += __shfl_xor(s, 16); s += __shfl_xor(s, 32);
;                 if (fq == 0) ss[(size_t)row * 16 + u.pn * 4 + wc] = s; }
.LBB0_853:
	s_or_b64 exec, exec, s[22:23]
	v_add_u32_e32 v100, 0x80, v172
	v_ashrrev_i32_e32 v101, 31, v100
	v_lshlrev_b64 v[110:111], 11, v[100:101]
	s_waitcnt lgkmcnt(0)
	v_lshl_add_u64 v[64:65], v[174:175], 0, v[110:111]
	v_mov_b32_e32 v102, v220
	v_mov_b32_e32 v103, v221
	v_mov_b32_e32 v104, v222
	v_mov_b32_e32 v105, v223
	v_mov_b32_e32 v106, v224
	v_mov_b32_e32 v107, v225
	v_mov_b32_e32 v108, v226
	v_mov_b32_e32 v109, v227
	v_add_u32_e32 v96, 0x90, v172
	v_add_u32_e32 v92, 0xa0, v172
	v_add_u32_e32 v88, 0xb0, v172
	v_ashrrev_i32_e32 v97, 31, v96
	v_ashrrev_i32_e32 v93, 31, v92
	v_ashrrev_i32_e32 v89, 31, v88
	v_lshlrev_b64 v[98:99], 11, v[96:97]
	v_lshlrev_b64 v[94:95], 11, v[92:93]
	v_lshlrev_b64 v[90:91], 11, v[88:89]
	v_lshl_add_u64 v[64:65], v[174:175], 0, v[98:99]
	v_lshl_add_u64 v[66:67], v[174:175], 0, v[94:95]
	v_lshl_add_u64 v[112:113], v[174:175], 0, v[90:91]
	v_mov_b32_e32 v84, v228
	v_mov_b32_e32 v85, v229
	v_mov_b32_e32 v86, v230
	v_mov_b32_e32 v87, v231
	v_mov_b32_e32 v80, v232
	v_mov_b32_e32 v81, v233
	v_mov_b32_e32 v82, v234
	v_mov_b32_e32 v83, v235
	v_mov_b32_e32 v76, v236
	v_mov_b32_e32 v77, v237
	v_mov_b32_e32 v78, v238
	v_mov_b32_e32 v79, v239
	v_mov_b32_e32 v72, v240
	v_mov_b32_e32 v73, v241
	v_mov_b32_e32 v74, v242
	v_mov_b32_e32 v75, v243
	v_mov_b32_e32 v68, v244
	v_mov_b32_e32 v69, v245
	v_mov_b32_e32 v70, v246
	v_mov_b32_e32 v71, v247
	s_nop 0
	v_mov_b32_e32 v64, v252
	v_mov_b32_e32 v65, v253
	v_mov_b32_e32 v66, v254
	v_mov_b32_e32 v67, v255
	s_nop 0
	v_lshlrev_b32_e32 v112, 16, v102
	v_and_b32_e32 v113, 0xffff0000, v102
	s_nop 0
	v_lshlrev_b32_e32 v116, 16, v106
	v_and_b32_e32 v117, 0xffff0000, v106
	v_lshlrev_b32_e32 v114, 16, v104
	v_and_b32_e32 v115, 0xffff0000, v104
	v_lshlrev_b32_e32 v104, 16, v105
	v_and_b32_e32 v105, 0xffff0000, v105
	v_lshlrev_b32_e32 v106, 16, v107
	v_and_b32_e32 v107, 0xffff0000, v107
	v_lshlrev_b32_e32 v118, 16, v108
	v_and_b32_e32 v119, 0xffff0000, v108
	v_pk_add_f32 v[60:61], v[60:61], v[112:113]
	v_pk_add_f32 v[52:53], v[52:53], v[116:117]
	v_lshlrev_b32_e32 v102, 16, v103
	v_and_b32_e32 v103, 0xffff0000, v103
	v_pk_add_f32 v[58:59], v[58:59], v[104:105]
	v_pk_add_f32 v[54:55], v[54:55], v[106:107]
	v_pk_add_f32 v[104:105], v[48:49], v[118:119]
	v_mul_f32_e32 v106, v61, v61
	v_cvt_pk_bf16_f32 v48, v60, v61
	v_mul_f32_e32 v61, v53, v53
	v_pk_add_f32 v[62:63], v[62:63], v[102:103]
	v_fmac_f32_e32 v106, v60, v60
	v_fmac_f32_e32 v61, v52, v52
	v_fmac_f32_e32 v106, v62, v62
	v_fmac_f32_e32 v61, v54, v54
	v_pk_add_f32 v[56:57], v[56:57], v[114:115]
	v_fmac_f32_e32 v106, v63, v63
	v_fmac_f32_e32 v61, v55, v55
	v_lshlrev_b32_e32 v108, 16, v109
	v_and_b32_e32 v109, 0xffff0000, v109
	v_fmac_f32_e32 v106, v56, v56
	v_fmac_f32_e32 v61, v104, v104
	v_pk_add_f32 v[102:103], v[50:51], v[108:109]
	v_fmac_f32_e32 v106, v57, v57
	v_fmac_f32_e32 v61, v105, v105
	v_fmac_f32_e32 v106, v58, v58
	v_fmac_f32_e32 v61, v102, v102
	v_fmac_f32_e32 v106, v59, v59
	v_fmac_f32_e32 v61, v103, v103
	v_cvt_pk_bf16_f32 v51, v58, v59
	v_add_f32_e32 v58, v106, v61
	ds_bpermute_b32 v59, v196, v58
	v_cvt_pk_bf16_f32 v50, v56, v57
	v_lshl_add_u64 v[56:57], s[76:77], 0, v[110:111]
	v_cvt_pk_bf16_f32 v49, v62, v63
	v_lshl_add_u64 v[56:57], v[170:171], 1, v[56:57]
	global_store_dwordx4 v[56:57], v[48:51], off
	s_waitcnt lgkmcnt(0)
	s_nop 0
	v_add_f32_e32 v48, v58, v59
	ds_bpermute_b32 v49, v195, v48
	v_cvt_pk_bf16_f32 v50, v52, v53
	v_cvt_pk_bf16_f32 v51, v54, v55
	v_cvt_pk_bf16_f32 v52, v104, v105
	v_cvt_pk_bf16_f32 v53, v102, v103
	global_store_dwordx4 v[56:57], v[50:53], off offset:256
	s_and_saveexec_b64 s[22:23], s[0:1]
	s_cbranch_execz .LBB0_855
	s_waitcnt lgkmcnt(0)
	v_add_f32_e32 v50, v48, v49
	s_lshl_b32 s24, s6, 2
	v_lshlrev_b64 v[48:49], 6, v[100:101]
	s_ashr_i32 s25, s24, 31
	v_lshl_add_u64 v[48:49], s[10:11], 0, v[48:49]
	v_lshl_add_u64 v[48:49], s[24:25], 2, v[48:49]
	s_lshl_b32 s8, s37, 2
	v_lshl_add_u64 v[48:49], v[48:49], 0, s[8:9]
	global_store_dword v[48:49], v50, off
.LBB0_855:
	s_or_b64 exec, exec, s[22:23]
	s_nop 0
	v_lshlrev_b32_e32 v48, 16, v84
	s_waitcnt lgkmcnt(0)
	v_and_b32_e32 v49, 0xffff0000, v84
	v_lshlrev_b32_e32 v52, 16, v86
	v_and_b32_e32 v53, 0xffff0000, v86
	v_lshlrev_b32_e32 v54, 16, v87
	v_and_b32_e32 v55, 0xffff0000, v87
	v_pk_add_f32 v[44:45], v[44:45], v[48:49]
	v_lshlrev_b32_e32 v50, 16, v85
	v_and_b32_e32 v51, 0xffff0000, v85
	v_pk_add_f32 v[48:49], v[42:43], v[54:55]
	v_pk_add_f32 v[42:43], v[40:41], v[52:53]
	v_mul_f32_e32 v52, v45, v45
	v_pk_add_f32 v[46:47], v[46:47], v[50:51]
	v_fmac_f32_e32 v52, v44, v44
	v_fmac_f32_e32 v52, v46, v46
	v_fmac_f32_e32 v52, v47, v47
	v_fmac_f32_e32 v52, v42, v42
	v_fmac_f32_e32 v52, v43, v43
	v_fmac_f32_e32 v52, v48, v48
	v_cvt_pk_bf16_f32 v40, v44, v45
	s_nop 0
	v_lshlrev_b32_e32 v44, 16, v80
	v_and_b32_e32 v45, 0xffff0000, v80
	v_fmac_f32_e32 v52, v49, v49
	v_cvt_pk_bf16_f32 v41, v46, v47
	v_cvt_pk_bf16_f32 v42, v42, v43
	v_cvt_pk_bf16_f32 v43, v48, v49
	v_lshlrev_b32_e32 v46, 16, v81
	v_and_b32_e32 v47, 0xffff0000, v81
	v_lshlrev_b32_e32 v48, 16, v82
	v_and_b32_e32 v49, 0xffff0000, v82
	v_pk_add_f32 v[36:37], v[36:37], v[44:45]
	v_pk_add_f32 v[38:39], v[38:39], v[46:47]
	v_pk_add_f32 v[46:47], v[32:33], v[48:49]
	v_mul_f32_e32 v32, v37, v37
	v_fmac_f32_e32 v32, v36, v36
	v_fmac_f32_e32 v32, v38, v38
	v_fmac_f32_e32 v32, v39, v39
	v_lshlrev_b32_e32 v50, 16, v83
	v_and_b32_e32 v51, 0xffff0000, v83
	v_fmac_f32_e32 v32, v46, v46
	v_pk_add_f32 v[44:45], v[34:35], v[50:51]
	v_fmac_f32_e32 v32, v47, v47
	v_fmac_f32_e32 v32, v44, v44
	v_fmac_f32_e32 v32, v45, v45
	v_add_f32_e32 v35, v52, v32
	ds_bpermute_b32 v50, v196, v35
	v_lshl_add_u64 v[32:33], s[76:77], 0, v[98:99]
	v_lshl_add_u64 v[48:49], v[170:171], 1, v[32:33]
	v_cvt_pk_bf16_f32 v34, v36, v37
	v_cvt_pk_bf16_f32 v36, v46, v47
	s_waitcnt lgkmcnt(0)
	v_add_f32_e32 v32, v35, v50
	ds_bpermute_b32 v33, v195, v32
	v_cvt_pk_bf16_f32 v35, v38, v39
	v_cvt_pk_bf16_f32 v37, v44, v45
	global_store_dwordx4 v[48:49], v[40:43], off
	global_store_dwordx4 v[48:49], v[34:37], off offset:256
	s_and_saveexec_b64 s[22:23], s[0:1]
	s_cbranch_execz .LBB0_857
	s_waitcnt lgkmcnt(0)
	v_add_f32_e32 v34, v32, v33
	s_lshl_b32 s24, s6, 2
	v_lshlrev_b64 v[32:33], 6, v[96:97]
	s_ashr_i32 s25, s24, 31
	v_lshl_add_u64 v[32:33], s[10:11], 0, v[32:33]
	v_lshl_add_u64 v[32:33], s[24:25], 2, v[32:33]
	s_lshl_b32 s8, s37, 2
	v_lshl_add_u64 v[32:33], v[32:33], 0, s[8:9]
	global_store_dword v[32:33], v34, off
; __device__ __forceinline__ unsigned pk2(float lo, float hi) { const f32x2 v = (f32x2){lo, hi}; const bf16x2_t b = __builtin_convertvector(v, bf16x2_t); return __builtin_bit_cast(unsigned, b); }
; __device__ __forceinline__ void unpack8(const u32x4 v, float* f) { f[0] = bf_lo(v.x); f[1] = bf_hi(v.x); f[2] = bf_lo(v.y); f[3] = bf_hi(v.y); f[4] = bf_lo(v.z); f[5] = bf_hi(v.z); f[6] = bf_lo(v.w); f[7] = bf_hi(v.w); }
;     __device__ __forceinline__ void operator()(const f32x4 (&acc)[2][2][4][2], const Unit& u, int wr, int wc, int fr, int fq, const float (&)[8]) const {
;     ...
;             for (int m = 0; m < 4; ++m) { const int row = row0 + ai * HALF + m * 16; const size_t ro = (size_t)row * DM + col0; float s = 0.f;
; #pragma unroll
;                 for (int bj = 0; bj < 2; ++bj) { float b8[8]; unpack8(bv[m][bj], b8);
;                     const f32x4 v0 = (f32x4){b8[0], b8[1], b8[2], b8[3]} + acc[ai][bj][m][0], v1 = (f32x4){b8[4], b8[5], b8[6], b8[7]} + acc[ai][bj][m][1];
;                     s += v0[0] * v0[0] + v0[1] * v0[1] + v0[2] * v0[2] + v0[3] * v0[3] + v1[0] * v1[0] + v1[1] * v1[1] + v1[2] * v1[2] + v1[3] * v1[3];
;                     if (LAST) { *(f32x4*)(out + ro + bj * HALF) = v0; *(f32x4*)(out + ro + bj * HALF + 4) = v1; }
;                     else { u32x4 w; w.x = pk2(v0[0], v0[1]); w.y = pk2(v0[2], v0[3]); w.z = pk2(v1[0], v1[1]); w.w = pk2(v1[2], v1[3]); *(u32x4*)(xb + ro + bj * HALF) = w; } }
;                 s += __shfl_xor(s, 16); s += __shfl_xor(s, 32);
;                 if (fq == 0) ss[(size_t)row * 16 + u.pn * 4 + wc] = s; }
.LBB0_857:
	s_or_b64 exec, exec, s[22:23]
	s_nop 0
	v_lshlrev_b32_e32 v32, 16, v76
	s_waitcnt lgkmcnt(0)
	v_and_b32_e32 v33, 0xffff0000, v76
	v_lshlrev_b32_e32 v36, 16, v78
	v_and_b32_e32 v37, 0xffff0000, v78
	v_lshlrev_b32_e32 v38, 16, v79
	v_and_b32_e32 v39, 0xffff0000, v79
	v_pk_add_f32 v[28:29], v[28:29], v[32:33]
	v_lshlrev_b32_e32 v34, 16, v77
	v_and_b32_e32 v35, 0xffff0000, v77
	v_pk_add_f32 v[32:33], v[26:27], v[38:39]
	v_pk_add_f32 v[26:27], v[24:25], v[36:37]
	v_mul_f32_e32 v36, v29, v29
	v_pk_add_f32 v[30:31], v[30:31], v[34:35]
	v_fmac_f32_e32 v36, v28, v28
	v_fmac_f32_e32 v36, v30, v30
	v_fmac_f32_e32 v36, v31, v31
	v_fmac_f32_e32 v36, v26, v26
	v_fmac_f32_e32 v36, v27, v27
	v_fmac_f32_e32 v36, v32, v32
	v_cvt_pk_bf16_f32 v24, v28, v29
	s_nop 0
	v_lshlrev_b32_e32 v28, 16, v72
	v_and_b32_e32 v29, 0xffff0000, v72
	v_fmac_f32_e32 v36, v33, v33
	v_cvt_pk_bf16_f32 v25, v30, v31
	v_cvt_pk_bf16_f32 v26, v26, v27
	v_cvt_pk_bf16_f32 v27, v32, v33
	v_lshlrev_b32_e32 v30, 16, v73
	v_and_b32_e32 v31, 0xffff0000, v73
	v_lshlrev_b32_e32 v32, 16, v74
	v_and_b32_e32 v33, 0xffff0000, v74
	v_pk_add_f32 v[20:21], v[20:21], v[28:29]
	v_pk_add_f32 v[22:23], v[22:23], v[30:31]
	v_pk_add_f32 v[30:31], v[16:17], v[32:33]
	v_mul_f32_e32 v16, v21, v21
	v_fmac_f32_e32 v16, v20, v20
	v_fmac_f32_e32 v16, v22, v22
	v_fmac_f32_e32 v16, v23, v23
	v_lshlrev_b32_e32 v34, 16, v75
	v_and_b32_e32 v35, 0xffff0000, v75
	v_fmac_f32_e32 v16, v30, v30
	v_pk_add_f32 v[28:29], v[18:19], v[34:35]
	v_fmac_f32_e32 v16, v31, v31
	v_fmac_f32_e32 v16, v28, v28
	v_fmac_f32_e32 v16, v29, v29
	v_add_f32_e32 v19, v36, v16
	ds_bpermute_b32 v34, v196, v19
	v_lshl_add_u64 v[16:17], s[76:77], 0, v[94:95]
	v_lshl_add_u64 v[32:33], v[170:171], 1, v[16:17]
	v_cvt_pk_bf16_f32 v18, v20, v21
	v_cvt_pk_bf16_f32 v20, v30, v31
	s_waitcnt lgkmcnt(0)
	v_add_f32_e32 v16, v19, v34
	ds_bpermute_b32 v17, v195, v16
	v_cvt_pk_bf16_f32 v19, v22, v23
	v_cvt_pk_bf16_f32 v21, v28, v29
	global_store_dwordx4 v[32:33], v[24:27], off
	global_store_dwordx4 v[32:33], v[18:21], off offset:256
	s_and_saveexec_b64 s[22:23], s[0:1]
	s_cbranch_execz .LBB0_859
	s_waitcnt lgkmcnt(0)
	v_add_f32_e32 v18, v16, v17
	s_lshl_b32 s24, s6, 2
	v_lshlrev_b64 v[16:17], 6, v[92:93]
	s_ashr_i32 s25, s24, 31
	v_lshl_add_u64 v[16:17], s[10:11], 0, v[16:17]
	v_lshl_add_u64 v[16:17], s[24:25], 2, v[16:17]
	s_lshl_b32 s8, s37, 2
	v_lshl_add_u64 v[16:17], v[16:17], 0, s[8:9]
	global_store_dword v[16:17], v18, off
.LBB0_859:
	s_or_b64 exec, exec, s[22:23]
	s_nop 0
	v_lshlrev_b32_e32 v16, 16, v68
	s_waitcnt lgkmcnt(0)
	v_and_b32_e32 v17, 0xffff0000, v68
	v_lshlrev_b32_e32 v20, 16, v70
	v_and_b32_e32 v21, 0xffff0000, v70
	v_lshlrev_b32_e32 v22, 16, v71
	v_and_b32_e32 v23, 0xffff0000, v71
	v_pk_add_f32 v[12:13], v[12:13], v[16:17]
	v_lshlrev_b32_e32 v18, 16, v69
	v_and_b32_e32 v19, 0xffff0000, v69
	v_pk_add_f32 v[16:17], v[10:11], v[22:23]
	v_pk_add_f32 v[10:11], v[8:9], v[20:21]
	v_mul_f32_e32 v20, v13, v13
	v_pk_add_f32 v[14:15], v[14:15], v[18:19]
	v_fmac_f32_e32 v20, v12, v12
	v_fmac_f32_e32 v20, v14, v14
	v_fmac_f32_e32 v20, v15, v15
	v_fmac_f32_e32 v20, v10, v10
	v_fmac_f32_e32 v20, v11, v11
	v_fmac_f32_e32 v20, v16, v16
	v_cvt_pk_bf16_f32 v8, v12, v13
	s_nop 0
	v_lshlrev_b32_e32 v12, 16, v64
	v_and_b32_e32 v13, 0xffff0000, v64
	v_fmac_f32_e32 v20, v17, v17
	v_cvt_pk_bf16_f32 v9, v14, v15
	v_cvt_pk_bf16_f32 v10, v10, v11
	v_cvt_pk_bf16_f32 v11, v16, v17
	v_lshlrev_b32_e32 v14, 16, v65
	v_and_b32_e32 v15, 0xffff0000, v65
	v_lshlrev_b32_e32 v16, 16, v66
	v_and_b32_e32 v17, 0xffff0000, v66
	v_pk_add_f32 v[4:5], v[4:5], v[12:13]
	v_pk_add_f32 v[6:7], v[6:7], v[14:15]
	v_pk_add_f32 v[14:15], v[0:1], v[16:17]
	v_mul_f32_e32 v0, v5, v5
	v_fmac_f32_e32 v0, v4, v4
	v_fmac_f32_e32 v0, v6, v6
	v_fmac_f32_e32 v0, v7, v7
	v_lshlrev_b32_e32 v18, 16, v67
	v_and_b32_e32 v19, 0xffff0000, v67
	v_fmac_f32_e32 v0, v14, v14
	v_pk_add_f32 v[12:13], v[2:3], v[18:19]
	v_fmac_f32_e32 v0, v15, v15
	v_fmac_f32_e32 v0, v12, v12
	v_fmac_f32_e32 v0, v13, v13
	v_add_f32_e32 v3, v20, v0
	ds_bpermute_b32 v18, v196, v3
	v_lshl_add_u64 v[0:1], s[76:77], 0, v[90:91]
	v_lshl_add_u64 v[16:17], v[170:171], 1, v[0:1]
	v_cvt_pk_bf16_f32 v2, v4, v5
	v_cvt_pk_bf16_f32 v4, v14, v15
	s_waitcnt lgkmcnt(0)
	v_add_f32_e32 v0, v3, v18
	ds_bpermute_b32 v1, v195, v0
	v_cvt_pk_bf16_f32 v3, v6, v7
	v_cvt_pk_bf16_f32 v5, v12, v13
	global_store_dwordx4 v[16:17], v[8:11], off
	global_store_dwordx4 v[16:17], v[2:5], off offset:256
	s_and_saveexec_b64 s[22:23], s[0:1]
	s_cbranch_execz .LBB0_836
	s_waitcnt lgkmcnt(0)
	v_add_f32_e32 v2, v0, v1
	s_lshl_b32 s24, s6, 2
	v_lshlrev_b64 v[0:1], 6, v[88:89]
	s_ashr_i32 s25, s24, 31
	v_lshl_add_u64 v[0:1], s[10:11], 0, v[0:1]
	v_lshl_add_u64 v[0:1], s[24:25], 2, v[0:1]
	s_lshl_b32 s8, s37, 2
	v_lshl_add_u64 v[0:1], v[0:1], 0, s[8:9]
	global_store_dword v[0:1], v2, off
	s_branch .LBB0_836

; #define PG8_STAGE(bufoff, gbase, voff) do { _Pragma("unroll") for (int _i = 0; _i < 2; ++_i) \
;         __builtin_amdgcn_global_load_lds((const unsigned*)((const char*)(gbase) + (voff)[_i]), (LAS unsigned*)(lds + (bufoff) + ldsw + _i * 8192), 16, 0, 0); } while (0)
; #define PG8_LDA(dst, b, h) do { _Pragma("unroll") for (int m = 0; m < 4; ++m) _Pragma("unroll") for (int k = 0; k < 2; ++k) dst[m][k] = *(const LAS bf16x8*)(lds + PG8_SA(b, h) + aoff + m * 2048 + k * 1024); } while (0)
; #define PG8_LDB(dst, b, h) do { _Pragma("unroll") for (int n = 0; n < 2; ++n) _Pragma("unroll") for (int k = 0; k < 2; ++k) dst[n][k] = *(const LAS bf16x8*)(lds + PG8_SB(b, h) + boff + n * 2048 + k * 1024); } while (0)
; #define PG8_MMA(ai, bj, At, Bt) do { __builtin_amdgcn_s_setprio(1); _Pragma("unroll") for (int m = 0; m < 4; ++m) _Pragma("unroll") for (int n = 0; n < 2; ++n) _Pragma("unroll") for (int k = 0; k < 2; ++k) \
;         acc[ai][bj][m][n] = __builtin_amdgcn_mfma_f32_16x16x32_bf16(Bt[n][k], At[m][k], acc[ai][bj][m][n], 0, 0, 0); __builtin_amdgcn_s_setprio(0); } while (0)
; #define PG8_WAIT_L(n) asm volatile("s_waitcnt lgkmcnt(" #n ")" ::: "memory")
; #define PG8_BAR __builtin_amdgcn_s_barrier()
; #define PG8_SCHED __builtin_amdgcn_sched_barrier(0)
; template <class Epi>
; __device__ __forceinline__ void gemm_phase(LAS unsigned char* lds, const Gemm g, const StaticOrder& S, const Epi& E) {
;     ...
;         for (int t = 0; t < nt; t += 2) {
;             const bool last = (t == nt - 2);
;             const char* a1 = cA + (size_t)(t + 1) * kstep;
;             const char* a2 = last ? nA : cA + (size_t)(t + 2) * kstep; const char* b2 = last ? nB : cB + (size_t)(t + 2) * kstep;
;             const char* a3 = a2 + kstep; const char* b3 = b2 + kstep;
;             if (last) E.pre(cur, wr, fr, epre);
;             PG8_LDB(B0, 0, 0); PG8_SCHED; PG8_LDA(At, 0, 0); PG8_STAGE(PG8_SA(1, 1), a1 + hstepA, voffA);
;             PG8_WAIT_L(8); PG8_BAR; PG8_WAIT_L(0); PG8_MMA(0, 0, At, B0); PG8_BAR; PG8_SCHED;
;             PG8_LDB(B1, 0, 1); PG8_STAGE(PG8_SB(0, 0), b2, voffB);
;             PG8_BAR; PG8_WAIT_L(0); PG8_MMA(0, 1, At, B1); PG8_BAR;
;             PG8_LDA(At, 0, 1); PG8_STAGE(PG8_SA(0, 0), a2, voffA);
;             PG8_BAR; PG8_WAIT_L(0); PG8_MMA(1, 0, At, B0); PG8_BAR; PG8_SCHED;
.LBB0_1118:
	ds_read_b128 v[128:131], v190
	ds_read_b128 v[132:135], v190 offset:1024
	ds_read_b128 v[136:139], v190 offset:2048
	ds_read_b128 v[140:143], v190 offset:3072
	s_add_u32 s22, s4, 0xffec0080
	s_addc_u32 s23, s5, -1
	s_cmp_eq_u32 s46, 12
	s_cselect_b32 s25, s19, s23
	s_cselect_b32 s24, s18, s22
	s_cselect_b32 s23, s17, s45
	s_cselect_b32 s22, s43, s44
	v_lshl_add_u64 v[186:187], s[4:5], 0, v[162:163]
	s_add_i32 m0, s9, 0xc000
	ds_read_b128 v[144:147], v191
	ds_read_b128 v[148:151], v191 offset:1024
	ds_read_b128 v[170:173], v191 offset:2048
	ds_read_b128 v[174:177], v191 offset:3072
	ds_read_b128 v[178:181], v191 offset:4096
	ds_read_b128 v[182:185], v191 offset:5120
	ds_read_b128 v[194:197], v191 offset:6144
	ds_read_b128 v[198:201], v191 offset:7168
	global_load_lds_dwordx4 v[186:187], off
	v_lshl_add_u64 v[186:187], s[4:5], 0, v[164:165]
	s_add_i32 m0, s9, 0xe000
	s_nop 0
	global_load_lds_dwordx4 v[186:187], off
	s_waitcnt lgkmcnt(8)
	s_barrier
	s_waitcnt lgkmcnt(0)
	s_setprio 1
	s_waitcnt lgkmcnt(0)
	v_mfma_f32_16x16x32_bf16 v[124:127], v[128:131], v[144:147], v[124:127]
	v_mfma_f32_16x16x32_bf16 v[120:123], v[136:139], v[144:147], v[120:123]
	v_mfma_f32_16x16x32_bf16 v[108:111], v[128:131], v[170:173], v[108:111]
	v_mfma_f32_16x16x32_bf16 v[104:107], v[136:139], v[170:173], v[104:107]
	v_mfma_f32_16x16x32_bf16 v[92:95], v[128:131], v[178:181], v[92:95]
	v_mfma_f32_16x16x32_bf16 v[88:91], v[136:139], v[178:181], v[88:91]
	v_mfma_f32_16x16x32_bf16 v[76:79], v[128:131], v[194:197], v[76:79]
	v_mfma_f32_16x16x32_bf16 v[72:75], v[136:139], v[194:197], v[72:75]
	v_mfma_f32_16x16x32_bf16 v[124:127], v[132:135], v[148:151], v[124:127]
	v_mfma_f32_16x16x32_bf16 v[120:123], v[140:143], v[148:151], v[120:123]
	v_mfma_f32_16x16x32_bf16 v[108:111], v[132:135], v[174:177], v[108:111]
	v_mfma_f32_16x16x32_bf16 v[104:107], v[140:143], v[174:177], v[104:107]
	v_mfma_f32_16x16x32_bf16 v[92:95], v[132:135], v[182:185], v[92:95]
	v_mfma_f32_16x16x32_bf16 v[88:91], v[140:143], v[182:185], v[88:91]
	v_mfma_f32_16x16x32_bf16 v[76:79], v[132:135], v[198:201], v[76:79]
	v_mfma_f32_16x16x32_bf16 v[72:75], v[140:143], v[198:201], v[72:75]
	s_setprio 0
	s_barrier
	s_add_i32 s47, s40, s29
	v_lshl_add_u64 v[186:187], s[22:23], 0, v[156:157]
	s_mov_b32 m0, s47
	ds_read_b128 v[202:205], v192
	ds_read_b128 v[206:209], v192 offset:1024
	ds_read_b128 v[210:213], v192 offset:2048
	ds_read_b128 v[214:217], v192 offset:3072
	global_load_lds_dwordx4 v[186:187], off
	v_lshl_add_u64 v[218:219], s[22:23], 0, v[160:161]
	s_add_i32 m0, s47, 0x2000
	s_nop 0
	global_load_lds_dwordx4 v[218:219], off
	s_barrier
	s_waitcnt lgkmcnt(0)
	s_setprio 1
	s_waitcnt lgkmcnt(0)
	v_mfma_f32_16x16x32_bf16 v[116:119], v[202:205], v[144:147], v[116:119]
	v_mfma_f32_16x16x32_bf16 v[112:115], v[210:213], v[144:147], v[112:115]
	v_mfma_f32_16x16x32_bf16 v[100:103], v[202:205], v[170:173], v[100:103]
	v_mfma_f32_16x16x32_bf16 v[96:99], v[210:213], v[170:173], v[96:99]
	v_mfma_f32_16x16x32_bf16 v[84:87], v[202:205], v[178:181], v[84:87]
	v_mfma_f32_16x16x32_bf16 v[80:83], v[210:213], v[178:181], v[80:83]
	v_mfma_f32_16x16x32_bf16 v[68:71], v[202:205], v[194:197], v[68:71]
	v_mfma_f32_16x16x32_bf16 v[64:67], v[210:213], v[194:197], v[64:67]
	v_mfma_f32_16x16x32_bf16 v[116:119], v[206:209], v[148:151], v[116:119]
	v_mfma_f32_16x16x32_bf16 v[112:115], v[214:217], v[148:151], v[112:115]
	v_mfma_f32_16x16x32_bf16 v[100:103], v[206:209], v[174:177], v[100:103]
	v_mfma_f32_16x16x32_bf16 v[96:99], v[214:217], v[174:177], v[96:99]
	v_mfma_f32_16x16x32_bf16 v[84:87], v[206:209], v[182:185], v[84:87]
	v_mfma_f32_16x16x32_bf16 v[80:83], v[214:217], v[182:185], v[80:83]
	v_mfma_f32_16x16x32_bf16 v[68:71], v[206:209], v[198:201], v[68:71]
	v_mfma_f32_16x16x32_bf16 v[64:67], v[214:217], v[198:201], v[64:67]
	s_setprio 0
	s_mov_b32 m0, s9
	v_lshl_add_u64 v[220:221], s[24:25], 0, v[154:155]
	s_barrier
	ds_read_b128 v[144:147], v191 offset:16384
	ds_read_b128 v[148:151], v191 offset:17408
	ds_read_b128 v[170:173], v191 offset:18432
	ds_read_b128 v[174:177], v191 offset:19456
	ds_read_b128 v[178:181], v191 offset:20480
	ds_read_b128 v[182:185], v191 offset:21504
	ds_read_b128 v[194:197], v191 offset:22528
	ds_read_b128 v[198:201], v191 offset:23552
	global_load_lds_dwordx4 v[220:221], off
	v_lshl_add_u64 v[222:223], s[24:25], 0, v[158:159]
	s_mov_b32 m0, s30
	s_nop 0
	global_load_lds_dwordx4 v[222:223], off
	s_barrier
	s_waitcnt lgkmcnt(0)
	s_setprio 1
	s_waitcnt lgkmcnt(0)
	v_mfma_f32_16x16x32_bf16 v[60:63], v[128:131], v[144:147], v[60:63]
	v_mfma_f32_16x16x32_bf16 v[56:59], v[136:139], v[144:147], v[56:59]
	v_mfma_f32_16x16x32_bf16 v[44:47], v[128:131], v[170:173], v[44:47]
	v_mfma_f32_16x16x32_bf16 v[40:43], v[136:139], v[170:173], v[40:43]
	v_mfma_f32_16x16x32_bf16 v[28:31], v[128:131], v[178:181], v[28:31]
	v_mfma_f32_16x16x32_bf16 v[24:27], v[136:139], v[178:181], v[24:27]
	v_mfma_f32_16x16x32_bf16 v[12:15], v[128:131], v[194:197], v[12:15]
	v_mfma_f32_16x16x32_bf16 v[8:11], v[136:139], v[194:197], v[8:11]
	v_mfma_f32_16x16x32_bf16 v[60:63], v[132:135], v[148:151], v[60:63]
	v_mfma_f32_16x16x32_bf16 v[56:59], v[140:143], v[148:151], v[56:59]
	v_mfma_f32_16x16x32_bf16 v[44:47], v[132:135], v[174:177], v[44:47]
	v_mfma_f32_16x16x32_bf16 v[40:43], v[140:143], v[174:177], v[40:43]
	v_mfma_f32_16x16x32_bf16 v[28:31], v[132:135], v[182:185], v[28:31]
	v_mfma_f32_16x16x32_bf16 v[24:27], v[140:143], v[182:185], v[24:27]
	v_mfma_f32_16x16x32_bf16 v[12:15], v[132:135], v[198:201], v[12:15]
	v_mfma_f32_16x16x32_bf16 v[8:11], v[140:143], v[198:201], v[8:11]
	s_setprio 0
	s_barrier
; #define PG8_STAGE(bufoff, gbase, voff) do { _Pragma("unroll") for (int _i = 0; _i < 2; ++_i) \
;         __builtin_amdgcn_global_load_lds((const unsigned*)((const char*)(gbase) + (voff)[_i]), (LAS unsigned*)(lds + (bufoff) + ldsw + _i * 8192), 16, 0, 0); } while (0)
; #define PG8_LDA(dst, b, h) do { _Pragma("unroll") for (int m = 0; m < 4; ++m) _Pragma("unroll") for (int k = 0; k < 2; ++k) dst[m][k] = *(const LAS bf16x8*)(lds + PG8_SA(b, h) + aoff + m * 2048 + k * 1024); } while (0)
; #define PG8_LDB(dst, b, h) do { _Pragma("unroll") for (int n = 0; n < 2; ++n) _Pragma("unroll") for (int k = 0; k < 2; ++k) dst[n][k] = *(const LAS bf16x8*)(lds + PG8_SB(b, h) + boff + n * 2048 + k * 1024); } while (0)
; #define PG8_MMA(ai, bj, At, Bt) do { __builtin_amdgcn_s_setprio(1); _Pragma("unroll") for (int m = 0; m < 4; ++m) _Pragma("unroll") for (int n = 0; n < 2; ++n) _Pragma("unroll") for (int k = 0; k < 2; ++k) \
;         acc[ai][bj][m][n] = __builtin_amdgcn_mfma_f32_16x16x32_bf16(Bt[n][k], At[m][k], acc[ai][bj][m][n], 0, 0, 0); __builtin_amdgcn_s_setprio(0); } while (0)
; #define PG8_WAIT_V(n) asm volatile("s_waitcnt vmcnt(" #n ")" ::: "memory")
; #define PG8_WAIT_L(n) asm volatile("s_waitcnt lgkmcnt(" #n ")" ::: "memory")
; #define PG8_BAR __builtin_amdgcn_s_barrier()
; #define PG8_SCHED __builtin_amdgcn_sched_barrier(0)
; template <class Epi>
; __device__ __forceinline__ void gemm_phase(LAS unsigned char* lds, const Gemm g, const StaticOrder& S, const Epi& E) {
;     ...
;             PG8_STAGE(PG8_SB(0, 1), b2 + hstepB, voffB);
;             PG8_WAIT_V(6); PG8_BAR; PG8_MMA(1, 1, At, B1); PG8_BAR;
;             PG8_LDB(B0, 1, 0); PG8_SCHED; PG8_LDA(At, 1, 0); PG8_STAGE(PG8_SA(0, 1), a2 + hstepA, voffA);
;             PG8_WAIT_L(8); PG8_BAR; PG8_WAIT_L(0); PG8_MMA(0, 0, At, B0); PG8_BAR; PG8_SCHED;
;             PG8_LDB(B1, 1, 1); PG8_STAGE(PG8_SB(1, 0), b3, voffB);
;             PG8_BAR; PG8_WAIT_L(0); PG8_MMA(0, 1, At, B1); PG8_BAR;
;             PG8_LDA(At, 1, 1); PG8_STAGE(PG8_SA(1, 0), a3, voffA);
;             PG8_BAR; PG8_WAIT_L(0); PG8_MMA(1, 0, At, B0); PG8_BAR; PG8_SCHED;
	s_add_u32 s48, s22, 0x40000
	s_addc_u32 s49, s23, 0
	s_add_i32 s47, s41, s29
	v_lshl_add_u64 v[128:129], s[48:49], 0, v[156:157]
	s_mov_b32 m0, s47
	s_nop 0
	global_load_lds_dwordx4 v[128:129], off
	v_lshl_add_u64 v[128:129], s[48:49], 0, v[160:161]
	s_add_i32 m0, s47, 0x2000
	s_nop 0
	global_load_lds_dwordx4 v[128:129], off
	s_waitcnt vmcnt(6)
	s_barrier
	s_setprio 1
	v_mfma_f32_16x16x32_bf16 v[52:55], v[202:205], v[144:147], v[52:55]
	v_mfma_f32_16x16x32_bf16 v[48:51], v[210:213], v[144:147], v[48:51]
	v_mfma_f32_16x16x32_bf16 v[36:39], v[202:205], v[170:173], v[36:39]
	v_mfma_f32_16x16x32_bf16 v[32:35], v[210:213], v[170:173], v[32:35]
	v_mfma_f32_16x16x32_bf16 v[20:23], v[202:205], v[178:181], v[20:23]
	v_mfma_f32_16x16x32_bf16 v[16:19], v[210:213], v[178:181], v[16:19]
	v_mfma_f32_16x16x32_bf16 v[4:7], v[202:205], v[194:197], v[4:7]
	v_mfma_f32_16x16x32_bf16 v[0:3], v[210:213], v[194:197], v[0:3]
	v_mfma_f32_16x16x32_bf16 v[52:55], v[206:209], v[148:151], v[52:55]
	v_mfma_f32_16x16x32_bf16 v[48:51], v[214:217], v[148:151], v[48:51]
	v_mfma_f32_16x16x32_bf16 v[36:39], v[206:209], v[174:177], v[36:39]
	v_mfma_f32_16x16x32_bf16 v[32:35], v[214:217], v[174:177], v[32:35]
	v_mfma_f32_16x16x32_bf16 v[20:23], v[206:209], v[182:185], v[20:23]
	v_mfma_f32_16x16x32_bf16 v[16:19], v[214:217], v[182:185], v[16:19]
	v_mfma_f32_16x16x32_bf16 v[4:7], v[206:209], v[198:201], v[4:7]
	v_mfma_f32_16x16x32_bf16 v[0:3], v[214:217], v[198:201], v[0:3]
	s_setprio 0
	s_add_i32 s47, 0, 0x18000
	v_add_u32_e32 v140, s47, v188
	s_barrier
	ds_read_b128 v[128:131], v140
	ds_read_b128 v[132:135], v140 offset:1024
	ds_read_b128 v[136:139], v140 offset:2048
	ds_read_b128 v[140:143], v140 offset:3072
	s_add_u32 s24, s24, 0x140000
	s_addc_u32 s25, s25, 0
	s_mov_b32 m0, s31
	v_lshl_add_u64 v[202:203], s[24:25], 0, v[154:155]
	ds_read_b128 v[144:147], v191 offset:32768
	ds_read_b128 v[148:151], v191 offset:33792
	ds_read_b128 v[170:173], v191 offset:34816
	ds_read_b128 v[174:177], v191 offset:35840
	ds_read_b128 v[178:181], v191 offset:36864
	ds_read_b128 v[182:185], v191 offset:37888
	ds_read_b128 v[194:197], v191 offset:38912
	ds_read_b128 v[198:201], v191 offset:39936
	global_load_lds_dwordx4 v[202:203], off
	v_lshl_add_u64 v[202:203], s[24:25], 0, v[158:159]
	s_mov_b32 m0, s34
	s_nop 0
	global_load_lds_dwordx4 v[202:203], off
	s_waitcnt lgkmcnt(8)
	s_barrier
	s_waitcnt lgkmcnt(0)
	s_setprio 1
	s_waitcnt lgkmcnt(0)
	v_mfma_f32_16x16x32_bf16 v[124:127], v[128:131], v[144:147], v[124:127]
	v_mfma_f32_16x16x32_bf16 v[120:123], v[136:139], v[144:147], v[120:123]
	v_mfma_f32_16x16x32_bf16 v[108:111], v[128:131], v[170:173], v[108:111]
	v_mfma_f32_16x16x32_bf16 v[104:107], v[136:139], v[170:173], v[104:107]
	v_mfma_f32_16x16x32_bf16 v[92:95], v[128:131], v[178:181], v[92:95]
	v_mfma_f32_16x16x32_bf16 v[88:91], v[136:139], v[178:181], v[88:91]
	v_mfma_f32_16x16x32_bf16 v[76:79], v[128:131], v[194:197], v[76:79]
	v_mfma_f32_16x16x32_bf16 v[72:75], v[136:139], v[194:197], v[72:75]
	v_mfma_f32_16x16x32_bf16 v[124:127], v[132:135], v[148:151], v[124:127]
	v_mfma_f32_16x16x32_bf16 v[120:123], v[140:143], v[148:151], v[120:123]
	v_mfma_f32_16x16x32_bf16 v[108:111], v[132:135], v[174:177], v[108:111]
	v_mfma_f32_16x16x32_bf16 v[104:107], v[140:143], v[174:177], v[104:107]
	v_mfma_f32_16x16x32_bf16 v[92:95], v[132:135], v[182:185], v[92:95]
	v_mfma_f32_16x16x32_bf16 v[88:91], v[140:143], v[182:185], v[88:91]
	v_mfma_f32_16x16x32_bf16 v[76:79], v[132:135], v[198:201], v[76:79]
	v_mfma_f32_16x16x32_bf16 v[72:75], v[140:143], v[198:201], v[72:75]
	s_setprio 0
	s_barrier
	s_add_i32 s24, 0, 0x1c000
	s_add_i32 s25, s47, s29
	v_add_u32_e32 v214, s24, v188
	v_lshl_add_u64 v[186:187], v[186:187], 0, s[14:15]
	s_mov_b32 m0, s25
	ds_read_b128 v[202:205], v214
	ds_read_b128 v[206:209], v214 offset:1024
	ds_read_b128 v[210:213], v214 offset:2048
	ds_read_b128 v[214:217], v214 offset:3072
	global_load_lds_dwordx4 v[186:187], off
	v_lshl_add_u64 v[186:187], v[218:219], 0, s[14:15]
	s_add_i32 m0, s25, 0x2000
	s_nop 0
	global_load_lds_dwordx4 v[186:187], off
	s_barrier
	s_waitcnt lgkmcnt(0)
	s_setprio 1
	s_waitcnt lgkmcnt(0)
	v_mfma_f32_16x16x32_bf16 v[116:119], v[202:205], v[144:147], v[116:119]
	v_mfma_f32_16x16x32_bf16 v[112:115], v[210:213], v[144:147], v[112:115]
	v_mfma_f32_16x16x32_bf16 v[100:103], v[202:205], v[170:173], v[100:103]
	v_mfma_f32_16x16x32_bf16 v[96:99], v[210:213], v[170:173], v[96:99]
	v_mfma_f32_16x16x32_bf16 v[84:87], v[202:205], v[178:181], v[84:87]
	v_mfma_f32_16x16x32_bf16 v[80:83], v[210:213], v[178:181], v[80:83]
	v_mfma_f32_16x16x32_bf16 v[68:71], v[202:205], v[194:197], v[68:71]
	v_mfma_f32_16x16x32_bf16 v[64:67], v[210:213], v[194:197], v[64:67]
	v_mfma_f32_16x16x32_bf16 v[116:119], v[206:209], v[148:151], v[116:119]
	v_mfma_f32_16x16x32_bf16 v[112:115], v[214:217], v[148:151], v[112:115]
	v_mfma_f32_16x16x32_bf16 v[100:103], v[206:209], v[174:177], v[100:103]
	v_mfma_f32_16x16x32_bf16 v[96:99], v[214:217], v[174:177], v[96:99]
	v_mfma_f32_16x16x32_bf16 v[84:87], v[206:209], v[182:185], v[84:87]
	v_mfma_f32_16x16x32_bf16 v[80:83], v[214:217], v[182:185], v[80:83]
	v_mfma_f32_16x16x32_bf16 v[68:71], v[206:209], v[198:201], v[68:71]
	v_mfma_f32_16x16x32_bf16 v[64:67], v[214:217], v[198:201], v[64:67]
	s_setprio 0
	s_mov_b32 m0, s36
	v_lshl_add_u64 v[186:187], v[220:221], 0, s[14:15]
	s_barrier
	ds_read_b128 v[144:147], v191 offset:49152
	ds_read_b128 v[148:151], v191 offset:50176
	ds_read_b128 v[170:173], v191 offset:51200
	ds_read_b128 v[174:177], v191 offset:52224
	ds_read_b128 v[178:181], v191 offset:53248
	ds_read_b128 v[182:185], v191 offset:54272
	ds_read_b128 v[194:197], v191 offset:55296
	ds_read_b128 v[198:201], v191 offset:56320
	global_load_lds_dwordx4 v[186:187], off
	v_lshl_add_u64 v[186:187], v[222:223], 0, s[14:15]
	s_mov_b32 m0, s37
	s_nop 0
	global_load_lds_dwordx4 v[186:187], off
	s_barrier
; #define PG8_STAGE(bufoff, gbase, voff) do { _Pragma("unroll") for (int _i = 0; _i < 2; ++_i) \
;         __builtin_amdgcn_global_load_lds((const unsigned*)((const char*)(gbase) + (voff)[_i]), (LAS unsigned*)(lds + (bufoff) + ldsw + _i * 8192), 16, 0, 0); } while (0)
; #define PG8_LDA(dst, b, h) do { _Pragma("unroll") for (int m = 0; m < 4; ++m) _Pragma("unroll") for (int k = 0; k < 2; ++k) dst[m][k] = *(const LAS bf16x8*)(lds + PG8_SA(b, h) + aoff + m * 2048 + k * 1024); } while (0)
; #define PG8_MMA(ai, bj, At, Bt) do { __builtin_amdgcn_s_setprio(1); _Pragma("unroll") for (int m = 0; m < 4; ++m) _Pragma("unroll") for (int n = 0; n < 2; ++n) _Pragma("unroll") for (int k = 0; k < 2; ++k) \
;         acc[ai][bj][m][n] = __builtin_amdgcn_mfma_f32_16x16x32_bf16(Bt[n][k], At[m][k], acc[ai][bj][m][n], 0, 0, 0); __builtin_amdgcn_s_setprio(0); } while (0)
; #define PG8_WAIT_V(n) asm volatile("s_waitcnt vmcnt(" #n ")" ::: "memory")
; #define PG8_WAIT_L(n) asm volatile("s_waitcnt lgkmcnt(" #n ")" ::: "memory")
; #define PG8_BAR __builtin_amdgcn_s_barrier()
; #define PG8_SCHED __builtin_amdgcn_sched_barrier(0)
; template <class Epi>
; __device__ __forceinline__ void gemm_phase(LAS unsigned char* lds, const Gemm g, const StaticOrder& S, const Epi& E) {
;     ...
;             PG8_BAR; PG8_WAIT_L(0); PG8_MMA(0, 1, At, B1); PG8_BAR;
;             PG8_LDA(At, 1, 1); PG8_STAGE(PG8_SA(1, 0), a3, voffA);
;             PG8_BAR; PG8_WAIT_L(0); PG8_MMA(1, 0, At, B0); PG8_BAR; PG8_SCHED;
;             PG8_STAGE(PG8_SB(1, 1), b3 + hstepB, voffB);
;             PG8_WAIT_V(6); PG8_BAR; PG8_MMA(1, 1, At, B1); PG8_BAR;
;         }
	s_waitcnt lgkmcnt(0)
	s_setprio 1
	s_waitcnt lgkmcnt(0)
	v_mfma_f32_16x16x32_bf16 v[60:63], v[128:131], v[144:147], v[60:63]
	v_mfma_f32_16x16x32_bf16 v[56:59], v[136:139], v[144:147], v[56:59]
	v_mfma_f32_16x16x32_bf16 v[44:47], v[128:131], v[170:173], v[44:47]
	v_mfma_f32_16x16x32_bf16 v[40:43], v[136:139], v[170:173], v[40:43]
	v_mfma_f32_16x16x32_bf16 v[28:31], v[128:131], v[178:181], v[28:31]
	v_mfma_f32_16x16x32_bf16 v[24:27], v[136:139], v[178:181], v[24:27]
	v_mfma_f32_16x16x32_bf16 v[12:15], v[128:131], v[194:197], v[12:15]
	v_mfma_f32_16x16x32_bf16 v[8:11], v[136:139], v[194:197], v[8:11]
	v_mfma_f32_16x16x32_bf16 v[60:63], v[132:135], v[148:151], v[60:63]
	v_mfma_f32_16x16x32_bf16 v[56:59], v[140:143], v[148:151], v[56:59]
	v_mfma_f32_16x16x32_bf16 v[44:47], v[132:135], v[174:177], v[44:47]
	v_mfma_f32_16x16x32_bf16 v[40:43], v[140:143], v[174:177], v[40:43]
	v_mfma_f32_16x16x32_bf16 v[28:31], v[132:135], v[182:185], v[28:31]
	v_mfma_f32_16x16x32_bf16 v[24:27], v[140:143], v[182:185], v[24:27]
	v_mfma_f32_16x16x32_bf16 v[12:15], v[132:135], v[198:201], v[12:15]
	v_mfma_f32_16x16x32_bf16 v[8:11], v[140:143], v[198:201], v[8:11]
	s_setprio 0
	s_barrier
	s_add_u32 s22, s22, 0x40080
	s_addc_u32 s23, s23, 0
	s_add_i32 s24, s24, s29
	v_lshl_add_u64 v[128:129], s[22:23], 0, v[156:157]
	s_mov_b32 m0, s24
	s_nop 0
	global_load_lds_dwordx4 v[128:129], off
	v_lshl_add_u64 v[128:129], s[22:23], 0, v[160:161]
	s_add_i32 m0, s24, 0x2000
	s_nop 0
	global_load_lds_dwordx4 v[128:129], off
	s_waitcnt vmcnt(6)
	s_barrier
	s_setprio 1
	v_mfma_f32_16x16x32_bf16 v[52:55], v[202:205], v[144:147], v[52:55]
	v_mfma_f32_16x16x32_bf16 v[48:51], v[210:213], v[144:147], v[48:51]
	v_mfma_f32_16x16x32_bf16 v[36:39], v[202:205], v[170:173], v[36:39]
	v_mfma_f32_16x16x32_bf16 v[32:35], v[210:213], v[170:173], v[32:35]
	v_mfma_f32_16x16x32_bf16 v[20:23], v[202:205], v[178:181], v[20:23]
	v_mfma_f32_16x16x32_bf16 v[16:19], v[210:213], v[178:181], v[16:19]
	v_mfma_f32_16x16x32_bf16 v[4:7], v[202:205], v[194:197], v[4:7]
	v_mfma_f32_16x16x32_bf16 v[0:3], v[210:213], v[194:197], v[0:3]
	v_mfma_f32_16x16x32_bf16 v[52:55], v[206:209], v[148:151], v[52:55]
	v_mfma_f32_16x16x32_bf16 v[48:51], v[214:217], v[148:151], v[48:51]
	v_mfma_f32_16x16x32_bf16 v[36:39], v[206:209], v[174:177], v[36:39]
	v_mfma_f32_16x16x32_bf16 v[32:35], v[214:217], v[174:177], v[32:35]
	v_mfma_f32_16x16x32_bf16 v[20:23], v[206:209], v[182:185], v[20:23]
	v_mfma_f32_16x16x32_bf16 v[16:19], v[214:217], v[182:185], v[16:19]
	v_mfma_f32_16x16x32_bf16 v[4:7], v[206:209], v[198:201], v[4:7]
	v_mfma_f32_16x16x32_bf16 v[0:3], v[214:217], v[198:201], v[0:3]
	s_setprio 0
	s_add_i32 s46, s46, 2
	s_add_u32 s4, s4, 0x100
	s_addc_u32 s5, s5, 0
	s_add_u32 s44, s44, 0x100
	s_addc_u32 s45, s45, 0
	s_cmp_gt_u32 s46, 13
	s_barrier
	s_cbranch_scc0 .LBB0_1118
; __device__ __forceinline__ unsigned pk2(float lo, float hi) { const f32x2 v = (f32x2){lo, hi}; const bf16x2_t b = __builtin_convertvector(v, bf16x2_t); return __builtin_bit_cast(unsigned, b); }
; __device__ __forceinline__ void unpack8(const u32x4 v, float* f) { f[0] = bf_lo(v.x); f[1] = bf_hi(v.x); f[2] = bf_lo(v.y); f[3] = bf_hi(v.y); f[4] = bf_lo(v.z); f[5] = bf_hi(v.z); f[6] = bf_lo(v.w); f[7] = bf_hi(v.w); }
;     __device__ __forceinline__ void operator()(const f32x4 (&acc)[2][2][4][2], const Unit& u, int wr, int wc, int fr, int fq, const float (&)[8]) const {
;         const int row0 = u.pm * BM + wr * 64 + fr, col0 = u.pn * BM + wc * 32 + 8 * fq;
; #pragma unroll
;         for (int ai = 0; ai < 2; ++ai) {
;             u32x4 bv[4][2];
; #pragma unroll
;             for (int m = 0; m < 4; ++m)
; #pragma unroll
;                 for (int bj = 0; bj < 2; ++bj) bv[m][bj] = *(const u32x4*)(xb + (size_t)(row0 + ai * HALF + m * 16) * DM + col0 + bj * HALF);
; #pragma unroll
;             for (int m = 0; m < 4; ++m) { const int row = row0 + ai * HALF + m * 16; const size_t ro = (size_t)row * DM + col0; float s = 0.f;
; #pragma unroll
;                 for (int bj = 0; bj < 2; ++bj) { float b8[8]; unpack8(bv[m][bj], b8);
;                     const f32x4 v0 = (f32x4){b8[0], b8[1], b8[2], b8[3]} + acc[ai][bj][m][0], v1 = (f32x4){b8[4], b8[5], b8[6], b8[7]} + acc[ai][bj][m][1];
;                     s += v0[0] * v0[0] + v0[1] * v0[1] + v0[2] * v0[2] + v0[3] * v0[3] + v1[0] * v1[0] + v1[1] * v1[1] + v1[2] * v1[2] + v1[3] * v1[3];
;                     if (LAST) { *(f32x4*)(out + ro + bj * HALF) = v0; *(f32x4*)(out + ro + bj * HALF + 4) = v1; }
;                     else { u32x4 w; w.x = pk2(v0[0], v0[1]); w.y = pk2(v0[2], v0[3]); w.z = pk2(v1[0], v1[1]); w.w = pk2(v1[2], v1[3]); *(u32x4*)(xb + ro + bj * HALF) = w; } }
;                 s += __shfl_xor(s, 16); s += __shfl_xor(s, 32);
;                 if (fq == 0) ss[(size_t)row * 16 + u.pn * 4 + wc] = s; }
	v_lshl_or_b32 v170, s8, 8, v189
	v_lshl_add_u32 v172, s10, 8, v153
	v_ashrrev_i32_e32 v171, 31, v170
	v_lshlrev_b64 v[204:205], 1, v[170:171]
	v_ashrrev_i32_e32 v173, 31, v172
	v_lshl_add_u64 v[174:175], s[76:77], 0, v[204:205]
	v_lshlrev_b64 v[206:207], 11, v[172:173]
	v_lshl_add_u64 v[128:129], v[174:175], 0, v[206:207]
	global_load_dwordx4 v[196:199], v[128:129], off
	global_load_dwordx4 v[200:203], v[128:129], off offset:256
	v_or_b32_e32 v184, 16, v172
	v_or_b32_e32 v180, 32, v172
	v_or_b32_e32 v176, 48, v172
	v_ashrrev_i32_e32 v185, 31, v184
	v_ashrrev_i32_e32 v181, 31, v180
	v_ashrrev_i32_e32 v177, 31, v176
	v_lshlrev_b64 v[186:187], 11, v[184:185]
	v_lshlrev_b64 v[182:183], 11, v[180:181]
	v_lshlrev_b64 v[178:179], 11, v[176:177]
	v_lshl_add_u64 v[128:129], v[174:175], 0, v[186:187]
	v_lshl_add_u64 v[130:131], v[174:175], 0, v[182:183]
	v_lshl_add_u64 v[194:195], v[174:175], 0, v[178:179]
	global_load_dwordx4 v[148:151], v[128:129], off
	global_load_dwordx4 v[144:147], v[128:129], off offset:256
	global_load_dwordx4 v[140:143], v[130:131], off
	global_load_dwordx4 v[136:139], v[130:131], off offset:256
	global_load_dwordx4 v[132:135], v[194:195], off
	s_nop 0
	global_load_dwordx4 v[128:131], v[194:195], off offset:256
	v_add_u32_e32 v226, 0x80, v172
	v_ashrrev_i32_e32 v227, 31, v226
	v_lshlrev_b64 v[226:227], 11, v[226:227]
	v_lshl_add_u64 v[226:227], v[174:175], 0, v[226:227]
	global_load_dwordx4 v[216:219], v[226:227], off
	global_load_dwordx4 v[220:223], v[226:227], off offset:256
	v_add_u32_e32 v226, 0x90, v172
	v_ashrrev_i32_e32 v227, 31, v226
	v_lshlrev_b64 v[226:227], 11, v[226:227]
	v_lshl_add_u64 v[226:227], v[174:175], 0, v[226:227]
	global_load_dwordx4 v[228:231], v[226:227], off
	global_load_dwordx4 v[232:235], v[226:227], off offset:256
	v_add_u32_e32 v226, 0xa0, v172
	v_ashrrev_i32_e32 v227, 31, v226
	v_lshlrev_b64 v[226:227], 11, v[226:227]
	v_lshl_add_u64 v[226:227], v[174:175], 0, v[226:227]
	global_load_dwordx4 v[236:239], v[226:227], off
	global_load_dwordx4 v[240:243], v[226:227], off offset:256
	v_add_u32_e32 v226, 0xb0, v172
	v_ashrrev_i32_e32 v227, 31, v226
	v_lshlrev_b64 v[226:227], 11, v[226:227]
	v_lshl_add_u64 v[226:227], v[174:175], 0, v[226:227]
	global_load_dwordx4 v[244:247], v[226:227], off
	global_load_dwordx4 v[252:255], v[226:227], off offset:256
	v_and_b32_e32 v195, 64, v193
	v_xor_b32_e32 v194, 16, v193
	v_add_u32_e32 v195, 64, v195
	v_xor_b32_e32 v208, 32, v193
	v_cmp_lt_i32_e32 vcc, v194, v195
	s_waitcnt vmcnt(0)
	v_and_b32_e32 v209, 0xffff0000, v196
	v_cndmask_b32_e32 v194, v193, v194, vcc
	v_cmp_lt_i32_e32 vcc, v208, v195
	v_lshlrev_b32_e32 v195, 2, v194
	v_lshlrev_b32_e32 v212, 16, v200
	v_cndmask_b32_e32 v208, v193, v208, vcc
	v_lshlrev_b32_e32 v194, 2, v208
	v_lshlrev_b32_e32 v208, 16, v196
	v_and_b32_e32 v213, 0xffff0000, v200
	v_lshlrev_b32_e32 v210, 16, v198
	v_and_b32_e32 v211, 0xffff0000, v198
	v_lshlrev_b32_e32 v198, 16, v199
	v_and_b32_e32 v199, 0xffff0000, v199
	v_lshlrev_b32_e32 v200, 16, v201
	v_and_b32_e32 v201, 0xffff0000, v201
	v_lshlrev_b32_e32 v214, 16, v202
	v_and_b32_e32 v215, 0xffff0000, v202
	v_pk_add_f32 v[124:125], v[124:125], v[208:209]
	v_pk_add_f32 v[116:117], v[116:117], v[212:213]
	v_lshlrev_b32_e32 v196, 16, v197
	v_and_b32_e32 v197, 0xffff0000, v197
	v_pk_add_f32 v[122:123], v[122:123], v[198:199]
	v_pk_add_f32 v[118:119], v[118:119], v[200:201]
	v_pk_add_f32 v[198:199], v[112:113], v[214:215]
	v_mul_f32_e32 v200, v125, v125
	v_cvt_pk_bf16_f32 v112, v124, v125
	v_mul_f32_e32 v125, v117, v117
	v_pk_add_f32 v[126:127], v[126:127], v[196:197]
	v_fmac_f32_e32 v200, v124, v124
	v_fmac_f32_e32 v125, v116, v116
	v_fmac_f32_e32 v200, v126, v126
	v_fmac_f32_e32 v125, v118, v118
	v_pk_add_f32 v[120:121], v[120:121], v[210:211]
	v_fmac_f32_e32 v200, v127, v127
	v_fmac_f32_e32 v125, v119, v119
	v_lshlrev_b32_e32 v202, 16, v203
	v_and_b32_e32 v203, 0xffff0000, v203
	v_fmac_f32_e32 v200, v120, v120
	v_fmac_f32_e32 v125, v198, v198
	v_pk_add_f32 v[196:197], v[114:115], v[202:203]
	v_fmac_f32_e32 v200, v121, v121
	v_fmac_f32_e32 v125, v199, v199
	v_fmac_f32_e32 v200, v122, v122
	v_fmac_f32_e32 v125, v196, v196
	v_fmac_f32_e32 v200, v123, v123
	v_fmac_f32_e32 v125, v197, v197
	v_cvt_pk_bf16_f32 v115, v122, v123
	v_add_f32_e32 v122, v200, v125
	ds_bpermute_b32 v123, v195, v122
	v_cvt_pk_bf16_f32 v114, v120, v121
	v_lshl_add_u64 v[120:121], s[76:77], 0, v[206:207]
	v_cvt_pk_bf16_f32 v113, v126, v127
	v_lshl_add_u64 v[120:121], v[120:121], 0, v[204:205]
	global_store_dwordx4 v[120:121], v[112:115], off
	s_waitcnt lgkmcnt(0)
	s_nop 0
	v_add_f32_e32 v112, v122, v123
	ds_bpermute_b32 v113, v194, v112
	v_cvt_pk_bf16_f32 v114, v116, v117
	v_cvt_pk_bf16_f32 v115, v118, v119
	v_cvt_pk_bf16_f32 v116, v198, v199
	v_cvt_pk_bf16_f32 v117, v196, v197
	global_store_dwordx4 v[120:121], v[114:117], off offset:256
	s_and_saveexec_b64 s[4:5], s[0:1]
	s_cbranch_execz .LBB0_1121
	s_waitcnt lgkmcnt(0)
	v_add_f32_e32 v114, v112, v113
	s_lshl_b32 s22, s8, 2
	v_lshlrev_b64 v[112:113], 6, v[172:173]
	s_ashr_i32 s23, s22, 31
	v_lshl_add_u64 v[112:113], s[12:13], 0, v[112:113]
	v_lshl_add_u64 v[112:113], s[22:23], 2, v[112:113]
	s_lshl_b32 s10, s35, 2
	v_lshl_add_u64 v[112:113], v[112:113], 0, s[10:11]
	global_store_dword v[112:113], v114, off

; __device__ __forceinline__ unsigned pk2(float lo, float hi) { const f32x2 v = (f32x2){lo, hi}; const bf16x2_t b = __builtin_convertvector(v, bf16x2_t); return __builtin_bit_cast(unsigned, b); }
; __device__ __forceinline__ void unpack8(const u32x4 v, float* f) { f[0] = bf_lo(v.x); f[1] = bf_hi(v.x); f[2] = bf_lo(v.y); f[3] = bf_hi(v.y); f[4] = bf_lo(v.z); f[5] = bf_hi(v.z); f[6] = bf_lo(v.w); f[7] = bf_hi(v.w); }
;     __device__ __forceinline__ void operator()(const f32x4 (&acc)[2][2][4][2], const Unit& u, int wr, int wc, int fr, int fq, const float (&)[8]) const {
;     ...
;                 for (int bj = 0; bj < 2; ++bj) bv[m][bj] = *(const u32x4*)(xb + (size_t)(row0 + ai * HALF + m * 16) * DM + col0 + bj * HALF);
; #pragma unroll
;             for (int m = 0; m < 4; ++m) { const int row = row0 + ai * HALF + m * 16; const size_t ro = (size_t)row * DM + col0; float s = 0.f;
; #pragma unroll
;                 for (int bj = 0; bj < 2; ++bj) { float b8[8]; unpack8(bv[m][bj], b8);
;                     const f32x4 v0 = (f32x4){b8[0], b8[1], b8[2], b8[3]} + acc[ai][bj][m][0], v1 = (f32x4){b8[4], b8[5], b8[6], b8[7]} + acc[ai][bj][m][1];
;                     s += v0[0] * v0[0] + v0[1] * v0[1] + v0[2] * v0[2] + v0[3] * v0[3] + v1[0] * v1[0] + v1[1] * v1[1] + v1[2] * v1[2] + v1[3] * v1[3];
;                     if (LAST) { *(f32x4*)(out + ro + bj * HALF) = v0; *(f32x4*)(out + ro + bj * HALF + 4) = v1; }
;                     else { u32x4 w; w.x = pk2(v0[0], v0[1]); w.y = pk2(v0[2], v0[3]); w.z = pk2(v1[0], v1[1]); w.w = pk2(v1[2], v1[3]); *(u32x4*)(xb + ro + bj * HALF) = w; } }
;                 s += __shfl_xor(s, 16); s += __shfl_xor(s, 32);
;                 if (fq == 0) ss[(size_t)row * 16 + u.pn * 4 + wc] = s; }
.LBB0_1127:
	s_or_b64 exec, exec, s[4:5]
	v_add_u32_e32 v100, 0x80, v172
	v_ashrrev_i32_e32 v101, 31, v100
	v_lshlrev_b64 v[110:111], 11, v[100:101]
	s_waitcnt lgkmcnt(0)
	v_lshl_add_u64 v[64:65], v[174:175], 0, v[110:111]
	v_mov_b32_e32 v102, v216
	v_mov_b32_e32 v103, v217
	v_mov_b32_e32 v104, v218
	v_mov_b32_e32 v105, v219
	v_mov_b32_e32 v106, v220
	v_mov_b32_e32 v107, v221
	v_mov_b32_e32 v108, v222
	v_mov_b32_e32 v109, v223
	v_add_u32_e32 v96, 0x90, v172
	v_add_u32_e32 v92, 0xa0, v172
	v_add_u32_e32 v88, 0xb0, v172
	v_ashrrev_i32_e32 v97, 31, v96
	v_ashrrev_i32_e32 v93, 31, v92
	v_ashrrev_i32_e32 v89, 31, v88
	v_lshlrev_b64 v[98:99], 11, v[96:97]
	v_lshlrev_b64 v[94:95], 11, v[92:93]
	v_lshlrev_b64 v[90:91], 11, v[88:89]
	v_lshl_add_u64 v[64:65], v[174:175], 0, v[98:99]
	v_lshl_add_u64 v[66:67], v[174:175], 0, v[94:95]
	v_lshl_add_u64 v[112:113], v[174:175], 0, v[90:91]
	v_mov_b32_e32 v84, v228
	v_mov_b32_e32 v85, v229
	v_mov_b32_e32 v86, v230
	v_mov_b32_e32 v87, v231
	v_mov_b32_e32 v80, v232
	v_mov_b32_e32 v81, v233
	v_mov_b32_e32 v82, v234
	v_mov_b32_e32 v83, v235
	v_mov_b32_e32 v76, v236
	v_mov_b32_e32 v77, v237
	v_mov_b32_e32 v78, v238
	v_mov_b32_e32 v79, v239
	v_mov_b32_e32 v72, v240
	v_mov_b32_e32 v73, v241
	v_mov_b32_e32 v74, v242
	v_mov_b32_e32 v75, v243
	v_mov_b32_e32 v68, v244
	v_mov_b32_e32 v69, v245
	v_mov_b32_e32 v70, v246
	v_mov_b32_e32 v71, v247
	s_nop 0
	v_mov_b32_e32 v64, v252
	v_mov_b32_e32 v65, v253
	v_mov_b32_e32 v66, v254
	v_mov_b32_e32 v67, v255
	s_nop 0
	v_lshlrev_b32_e32 v112, 16, v102
	v_and_b32_e32 v113, 0xffff0000, v102
	s_nop 0
	v_lshlrev_b32_e32 v116, 16, v106
	v_and_b32_e32 v117, 0xffff0000, v106
	v_lshlrev_b32_e32 v114, 16, v104
	v_and_b32_e32 v115, 0xffff0000, v104
	v_lshlrev_b32_e32 v104, 16, v105
	v_and_b32_e32 v105, 0xffff0000, v105
	v_lshlrev_b32_e32 v106, 16, v107
	v_and_b32_e32 v107, 0xffff0000, v107
	v_lshlrev_b32_e32 v118, 16, v108
	v_and_b32_e32 v119, 0xffff0000, v108
	v_pk_add_f32 v[60:61], v[60:61], v[112:113]
	v_pk_add_f32 v[52:53], v[52:53], v[116:117]
	v_lshlrev_b32_e32 v102, 16, v103
	v_and_b32_e32 v103, 0xffff0000, v103
	v_pk_add_f32 v[58:59], v[58:59], v[104:105]
	v_pk_add_f32 v[54:55], v[54:55], v[106:107]
	v_pk_add_f32 v[104:105], v[48:49], v[118:119]
	v_mul_f32_e32 v106, v61, v61
	v_cvt_pk_bf16_f32 v48, v60, v61
	v_mul_f32_e32 v61, v53, v53
	v_pk_add_f32 v[62:63], v[62:63], v[102:103]
	v_fmac_f32_e32 v106, v60, v60
	v_fmac_f32_e32 v61, v52, v52
	v_fmac_f32_e32 v106, v62, v62
	v_fmac_f32_e32 v61, v54, v54
	v_pk_add_f32 v[56:57], v[56:57], v[114:115]
	v_fmac_f32_e32 v106, v63, v63
	v_fmac_f32_e32 v61, v55, v55
	v_lshlrev_b32_e32 v108, 16, v109
	v_and_b32_e32 v109, 0xffff0000, v109
	v_fmac_f32_e32 v106, v56, v56
	v_fmac_f32_e32 v61, v104, v104
	v_pk_add_f32 v[102:103], v[50:51], v[108:109]
	v_fmac_f32_e32 v106, v57, v57
	v_fmac_f32_e32 v61, v105, v105
	v_fmac_f32_e32 v106, v58, v58
	v_fmac_f32_e32 v61, v102, v102
	v_fmac_f32_e32 v106, v59, v59
	v_fmac_f32_e32 v61, v103, v103
	v_cvt_pk_bf16_f32 v51, v58, v59
	v_add_f32_e32 v58, v106, v61
	ds_bpermute_b32 v59, v195, v58
	v_cvt_pk_bf16_f32 v50, v56, v57
	v_lshl_add_u64 v[56:57], s[76:77], 0, v[110:111]
	v_cvt_pk_bf16_f32 v49, v62, v63
	v_lshl_add_u64 v[56:57], v[170:171], 1, v[56:57]
	global_store_dwordx4 v[56:57], v[48:51], off
	s_waitcnt lgkmcnt(0)
	s_nop 0
	v_add_f32_e32 v48, v58, v59
	ds_bpermute_b32 v49, v194, v48
	v_cvt_pk_bf16_f32 v50, v52, v53
	v_cvt_pk_bf16_f32 v51, v54, v55
	v_cvt_pk_bf16_f32 v52, v104, v105
	v_cvt_pk_bf16_f32 v53, v102, v103
	global_store_dwordx4 v[56:57], v[50:53], off offset:256
	s_and_saveexec_b64 s[4:5], s[0:1]
	s_cbranch_execz .LBB0_1129
	s_waitcnt lgkmcnt(0)
	v_add_f32_e32 v50, v48, v49
	s_lshl_b32 s22, s8, 2
	v_lshlrev_b64 v[48:49], 6, v[100:101]
	s_ashr_i32 s23, s22, 31
	v_lshl_add_u64 v[48:49], s[12:13], 0, v[48:49]
	v_lshl_add_u64 v[48:49], s[22:23], 2, v[48:49]
	s_lshl_b32 s10, s35, 2
	v_lshl_add_u64 v[48:49], v[48:49], 0, s[10:11]
	global_store_dword v[48:49], v50, off
.LBB0_1129:
	s_or_b64 exec, exec, s[4:5]
	s_nop 0
	v_lshlrev_b32_e32 v48, 16, v84
	s_waitcnt lgkmcnt(0)
	v_and_b32_e32 v49, 0xffff0000, v84
	v_lshlrev_b32_e32 v52, 16, v86
	v_and_b32_e32 v53, 0xffff0000, v86
	v_lshlrev_b32_e32 v54, 16, v87
	v_and_b32_e32 v55, 0xffff0000, v87
	v_pk_add_f32 v[44:45], v[44:45], v[48:49]
	v_lshlrev_b32_e32 v50, 16, v85
	v_and_b32_e32 v51, 0xffff0000, v85
	v_pk_add_f32 v[48:49], v[42:43], v[54:55]
	v_pk_add_f32 v[42:43], v[40:41], v[52:53]
	v_mul_f32_e32 v52, v45, v45
	v_pk_add_f32 v[46:47], v[46:47], v[50:51]
	v_fmac_f32_e32 v52, v44, v44
	v_fmac_f32_e32 v52, v46, v46
	v_fmac_f32_e32 v52, v47, v47
	v_fmac_f32_e32 v52, v42, v42
	v_fmac_f32_e32 v52, v43, v43
	v_fmac_f32_e32 v52, v48, v48
	v_cvt_pk_bf16_f32 v40, v44, v45
	s_nop 0
	v_lshlrev_b32_e32 v44, 16, v80
	v_and_b32_e32 v45, 0xffff0000, v80
	v_fmac_f32_e32 v52, v49, v49
	v_cvt_pk_bf16_f32 v41, v46, v47
	v_cvt_pk_bf16_f32 v42, v42, v43
	v_cvt_pk_bf16_f32 v43, v48, v49
	v_lshlrev_b32_e32 v46, 16, v81
	v_and_b32_e32 v47, 0xffff0000, v81
	v_lshlrev_b32_e32 v48, 16, v82
	v_and_b32_e32 v49, 0xffff0000, v82
	v_pk_add_f32 v[36:37], v[36:37], v[44:45]
	v_pk_add_f32 v[38:39], v[38:39], v[46:47]
	v_pk_add_f32 v[46:47], v[32:33], v[48:49]
	v_mul_f32_e32 v32, v37, v37
	v_fmac_f32_e32 v32, v36, v36
	v_fmac_f32_e32 v32, v38, v38
	v_fmac_f32_e32 v32, v39, v39
	v_lshlrev_b32_e32 v50, 16, v83
	v_and_b32_e32 v51, 0xffff0000, v83
	v_fmac_f32_e32 v32, v46, v46
	v_pk_add_f32 v[44:45], v[34:35], v[50:51]
	v_fmac_f32_e32 v32, v47, v47
	v_fmac_f32_e32 v32, v44, v44
	v_fmac_f32_e32 v32, v45, v45
	v_add_f32_e32 v35, v52, v32
	ds_bpermute_b32 v50, v195, v35
	v_lshl_add_u64 v[32:33], s[76:77], 0, v[98:99]
	v_lshl_add_u64 v[48:49], v[170:171], 1, v[32:33]
	v_cvt_pk_bf16_f32 v34, v36, v37
	v_cvt_pk_bf16_f32 v36, v46, v47
	s_waitcnt lgkmcnt(0)
	v_add_f32_e32 v32, v35, v50
	ds_bpermute_b32 v33, v194, v32
	v_cvt_pk_bf16_f32 v35, v38, v39
	v_cvt_pk_bf16_f32 v37, v44, v45
	global_store_dwordx4 v[48:49], v[40:43], off
	global_store_dwordx4 v[48:49], v[34:37], off offset:256
	s_and_saveexec_b64 s[4:5], s[0:1]
	s_cbranch_execz .LBB0_1131
	s_waitcnt lgkmcnt(0)
	v_add_f32_e32 v34, v32, v33
	s_lshl_b32 s22, s8, 2
	v_lshlrev_b64 v[32:33], 6, v[96:97]
	s_ashr_i32 s23, s22, 31
	v_lshl_add_u64 v[32:33], s[12:13], 0, v[32:33]
	v_lshl_add_u64 v[32:33], s[22:23], 2, v[32:33]
	s_lshl_b32 s10, s35, 2
	v_lshl_add_u64 v[32:33], v[32:33], 0, s[10:11]
	global_store_dword v[32:33], v34, off
; __device__ __forceinline__ unsigned pk2(float lo, float hi) { const f32x2 v = (f32x2){lo, hi}; const bf16x2_t b = __builtin_convertvector(v, bf16x2_t); return __builtin_bit_cast(unsigned, b); }
; __device__ __forceinline__ void unpack8(const u32x4 v, float* f) { f[0] = bf_lo(v.x); f[1] = bf_hi(v.x); f[2] = bf_lo(v.y); f[3] = bf_hi(v.y); f[4] = bf_lo(v.z); f[5] = bf_hi(v.z); f[6] = bf_lo(v.w); f[7] = bf_hi(v.w); }
;     __device__ __forceinline__ void operator()(const f32x4 (&acc)[2][2][4][2], const Unit& u, int wr, int wc, int fr, int fq, const float (&)[8]) const {
;     ...
;             for (int m = 0; m < 4; ++m) { const int row = row0 + ai * HALF + m * 16; const size_t ro = (size_t)row * DM + col0; float s = 0.f;
; #pragma unroll
;                 for (int bj = 0; bj < 2; ++bj) { float b8[8]; unpack8(bv[m][bj], b8);
;                     const f32x4 v0 = (f32x4){b8[0], b8[1], b8[2], b8[3]} + acc[ai][bj][m][0], v1 = (f32x4){b8[4], b8[5], b8[6], b8[7]} + acc[ai][bj][m][1];
;                     s += v0[0] * v0[0] + v0[1] * v0[1] + v0[2] * v0[2] + v0[3] * v0[3] + v1[0] * v1[0] + v1[1] * v1[1] + v1[2] * v1[2] + v1[3] * v1[3];
;                     if (LAST) { *(f32x4*)(out + ro + bj * HALF) = v0; *(f32x4*)(out + ro + bj * HALF + 4) = v1; }
;                     else { u32x4 w; w.x = pk2(v0[0], v0[1]); w.y = pk2(v0[2], v0[3]); w.z = pk2(v1[0], v1[1]); w.w = pk2(v1[2], v1[3]); *(u32x4*)(xb + ro + bj * HALF) = w; } }
;                 s += __shfl_xor(s, 16); s += __shfl_xor(s, 32);
;                 if (fq == 0) ss[(size_t)row * 16 + u.pn * 4 + wc] = s; }
.LBB0_1131:
	s_or_b64 exec, exec, s[4:5]
	s_nop 0
	v_lshlrev_b32_e32 v32, 16, v76
	s_waitcnt lgkmcnt(0)
	v_and_b32_e32 v33, 0xffff0000, v76
	v_lshlrev_b32_e32 v36, 16, v78
	v_and_b32_e32 v37, 0xffff0000, v78
	v_lshlrev_b32_e32 v38, 16, v79
	v_and_b32_e32 v39, 0xffff0000, v79
	v_pk_add_f32 v[28:29], v[28:29], v[32:33]
	v_lshlrev_b32_e32 v34, 16, v77
	v_and_b32_e32 v35, 0xffff0000, v77
	v_pk_add_f32 v[32:33], v[26:27], v[38:39]
	v_pk_add_f32 v[26:27], v[24:25], v[36:37]
	v_mul_f32_e32 v36, v29, v29
	v_pk_add_f32 v[30:31], v[30:31], v[34:35]
	v_fmac_f32_e32 v36, v28, v28
	v_fmac_f32_e32 v36, v30, v30
	v_fmac_f32_e32 v36, v31, v31
	v_fmac_f32_e32 v36, v26, v26
	v_fmac_f32_e32 v36, v27, v27
	v_fmac_f32_e32 v36, v32, v32
	v_cvt_pk_bf16_f32 v24, v28, v29
	s_nop 0
	v_lshlrev_b32_e32 v28, 16, v72
	v_and_b32_e32 v29, 0xffff0000, v72
	v_fmac_f32_e32 v36, v33, v33
	v_cvt_pk_bf16_f32 v25, v30, v31
	v_cvt_pk_bf16_f32 v26, v26, v27
	v_cvt_pk_bf16_f32 v27, v32, v33
	v_lshlrev_b32_e32 v30, 16, v73
	v_and_b32_e32 v31, 0xffff0000, v73
	v_lshlrev_b32_e32 v32, 16, v74
	v_and_b32_e32 v33, 0xffff0000, v74
	v_pk_add_f32 v[20:21], v[20:21], v[28:29]
	v_pk_add_f32 v[22:23], v[22:23], v[30:31]
	v_pk_add_f32 v[30:31], v[16:17], v[32:33]
	v_mul_f32_e32 v16, v21, v21
	v_fmac_f32_e32 v16, v20, v20
	v_fmac_f32_e32 v16, v22, v22
	v_fmac_f32_e32 v16, v23, v23
	v_lshlrev_b32_e32 v34, 16, v75
	v_and_b32_e32 v35, 0xffff0000, v75
	v_fmac_f32_e32 v16, v30, v30
	v_pk_add_f32 v[28:29], v[18:19], v[34:35]
	v_fmac_f32_e32 v16, v31, v31
	v_fmac_f32_e32 v16, v28, v28
	v_fmac_f32_e32 v16, v29, v29
	v_add_f32_e32 v19, v36, v16
	ds_bpermute_b32 v34, v195, v19
	v_lshl_add_u64 v[16:17], s[76:77], 0, v[94:95]
	v_lshl_add_u64 v[32:33], v[170:171], 1, v[16:17]
	v_cvt_pk_bf16_f32 v18, v20, v21
	v_cvt_pk_bf16_f32 v20, v30, v31
	s_waitcnt lgkmcnt(0)
	v_add_f32_e32 v16, v19, v34
	ds_bpermute_b32 v17, v194, v16
	v_cvt_pk_bf16_f32 v19, v22, v23
	v_cvt_pk_bf16_f32 v21, v28, v29
	global_store_dwordx4 v[32:33], v[24:27], off
	global_store_dwordx4 v[32:33], v[18:21], off offset:256
	s_and_saveexec_b64 s[4:5], s[0:1]
	s_cbranch_execz .LBB0_1133
	s_waitcnt lgkmcnt(0)
	v_add_f32_e32 v18, v16, v17
	s_lshl_b32 s22, s8, 2
	v_lshlrev_b64 v[16:17], 6, v[92:93]
	s_ashr_i32 s23, s22, 31
	v_lshl_add_u64 v[16:17], s[12:13], 0, v[16:17]
	v_lshl_add_u64 v[16:17], s[22:23], 2, v[16:17]
	s_lshl_b32 s10, s35, 2
	v_lshl_add_u64 v[16:17], v[16:17], 0, s[10:11]
	global_store_dword v[16:17], v18, off
.LBB0_1133:
	s_or_b64 exec, exec, s[4:5]
	s_nop 0
	v_lshlrev_b32_e32 v16, 16, v68
	s_waitcnt lgkmcnt(0)
	v_and_b32_e32 v17, 0xffff0000, v68
	v_lshlrev_b32_e32 v20, 16, v70
	v_and_b32_e32 v21, 0xffff0000, v70
	v_lshlrev_b32_e32 v22, 16, v71
	v_and_b32_e32 v23, 0xffff0000, v71
	v_pk_add_f32 v[12:13], v[12:13], v[16:17]
	v_lshlrev_b32_e32 v18, 16, v69
	v_and_b32_e32 v19, 0xffff0000, v69
	v_pk_add_f32 v[16:17], v[10:11], v[22:23]
	v_pk_add_f32 v[10:11], v[8:9], v[20:21]
	v_mul_f32_e32 v20, v13, v13
	v_pk_add_f32 v[14:15], v[14:15], v[18:19]
	v_fmac_f32_e32 v20, v12, v12
	v_fmac_f32_e32 v20, v14, v14
	v_fmac_f32_e32 v20, v15, v15
	v_fmac_f32_e32 v20, v10, v10
	v_fmac_f32_e32 v20, v11, v11
	v_fmac_f32_e32 v20, v16, v16
	v_cvt_pk_bf16_f32 v8, v12, v13
	s_nop 0
	v_lshlrev_b32_e32 v12, 16, v64
	v_and_b32_e32 v13, 0xffff0000, v64
	v_fmac_f32_e32 v20, v17, v17
	v_cvt_pk_bf16_f32 v9, v14, v15
	v_cvt_pk_bf16_f32 v10, v10, v11
	v_cvt_pk_bf16_f32 v11, v16, v17
	v_lshlrev_b32_e32 v14, 16, v65
	v_and_b32_e32 v15, 0xffff0000, v65
	v_lshlrev_b32_e32 v16, 16, v66
	v_and_b32_e32 v17, 0xffff0000, v66
	v_pk_add_f32 v[4:5], v[4:5], v[12:13]
	v_pk_add_f32 v[6:7], v[6:7], v[14:15]
	v_pk_add_f32 v[14:15], v[0:1], v[16:17]
	v_mul_f32_e32 v0, v5, v5
	v_fmac_f32_e32 v0, v4, v4
	v_fmac_f32_e32 v0, v6, v6
	v_fmac_f32_e32 v0, v7, v7
	v_lshlrev_b32_e32 v18, 16, v67
	v_and_b32_e32 v19, 0xffff0000, v67
	v_fmac_f32_e32 v0, v14, v14
	v_pk_add_f32 v[12:13], v[2:3], v[18:19]
	v_fmac_f32_e32 v0, v15, v15
	v_fmac_f32_e32 v0, v12, v12
	v_fmac_f32_e32 v0, v13, v13
	v_add_f32_e32 v3, v20, v0
	ds_bpermute_b32 v18, v195, v3
	v_lshl_add_u64 v[0:1], s[76:77], 0, v[90:91]
	v_lshl_add_u64 v[16:17], v[170:171], 1, v[0:1]
	v_cvt_pk_bf16_f32 v2, v4, v5
	v_cvt_pk_bf16_f32 v4, v14, v15
	s_waitcnt lgkmcnt(0)
	v_add_f32_e32 v0, v3, v18
	ds_bpermute_b32 v1, v194, v0
	v_cvt_pk_bf16_f32 v3, v6, v7
	v_cvt_pk_bf16_f32 v5, v12, v13
	global_store_dwordx4 v[16:17], v[8:11], off
	global_store_dwordx4 v[16:17], v[2:5], off offset:256
	s_and_saveexec_b64 s[4:5], s[0:1]
	s_cbranch_execz .LBB0_1108
	s_waitcnt lgkmcnt(0)
	v_add_f32_e32 v2, v0, v1
	s_lshl_b32 s22, s8, 2
	v_lshlrev_b64 v[0:1], 6, v[88:89]
	s_ashr_i32 s23, s22, 31
	v_lshl_add_u64 v[0:1], s[12:13], 0, v[0:1]
	v_lshl_add_u64 v[0:1], s[22:23], 2, v[0:1]
	s_lshl_b32 s10, s35, 2
	v_lshl_add_u64 v[0:1], v[0:1], 0, s[10:11]
	global_store_dword v[0:1], v2, off
	s_branch .LBB0_1108

; #define PG8_STAGE(bufoff, gbase, voff) do { _Pragma("unroll") for (int _i = 0; _i < 2; ++_i) \
;         __builtin_amdgcn_global_load_lds((const unsigned*)((const char*)(gbase) + (voff)[_i]), (LAS unsigned*)(lds + (bufoff) + ldsw + _i * 8192), 16, 0, 0); } while (0)
; #define PG8_LDA(dst, b, h) do { _Pragma("unroll") for (int m = 0; m < 4; ++m) _Pragma("unroll") for (int k = 0; k < 2; ++k) dst[m][k] = *(const LAS bf16x8*)(lds + PG8_SA(b, h) + aoff + m * 2048 + k * 1024); } while (0)
; #define PG8_LDB(dst, b, h) do { _Pragma("unroll") for (int n = 0; n < 2; ++n) _Pragma("unroll") for (int k = 0; k < 2; ++k) dst[n][k] = *(const LAS bf16x8*)(lds + PG8_SB(b, h) + boff + n * 2048 + k * 1024); } while (0)
; #define PG8_MMA(ai, bj, At, Bt) do { __builtin_amdgcn_s_setprio(1); _Pragma("unroll") for (int m = 0; m < 4; ++m) _Pragma("unroll") for (int n = 0; n < 2; ++n) _Pragma("unroll") for (int k = 0; k < 2; ++k) \
;         acc[ai][bj][m][n] = __builtin_amdgcn_mfma_f32_16x16x32_bf16(Bt[n][k], At[m][k], acc[ai][bj][m][n], 0, 0, 0); __builtin_amdgcn_s_setprio(0); } while (0)
; #define PG8_WAIT_L(n) asm volatile("s_waitcnt lgkmcnt(" #n ")" ::: "memory")
; #define PG8_BAR __builtin_amdgcn_s_barrier()
; #define PG8_SCHED __builtin_amdgcn_sched_barrier(0)
; template <class Epi>
; __device__ __forceinline__ void gemm_phase(LAS unsigned char* lds, const Gemm g, const StaticOrder& S, const Epi& E) {
;     ...
;         for (int t = 0; t < nt; t += 2) {
;             const bool last = (t == nt - 2);
;             const char* a1 = cA + (size_t)(t + 1) * kstep;
;             const char* a2 = last ? nA : cA + (size_t)(t + 2) * kstep; const char* b2 = last ? nB : cB + (size_t)(t + 2) * kstep;
;             const char* a3 = a2 + kstep; const char* b3 = b2 + kstep;
;             if (last) E.pre(cur, wr, fr, epre);
;             PG8_LDB(B0, 0, 0); PG8_SCHED; PG8_LDA(At, 0, 0); PG8_STAGE(PG8_SA(1, 1), a1 + hstepA, voffA);
;             PG8_WAIT_L(8); PG8_BAR; PG8_WAIT_L(0); PG8_MMA(0, 0, At, B0); PG8_BAR; PG8_SCHED;
;             PG8_LDB(B1, 0, 1); PG8_STAGE(PG8_SB(0, 0), b2, voffB);
;             PG8_BAR; PG8_WAIT_L(0); PG8_MMA(0, 1, At, B1); PG8_BAR;
;             PG8_LDA(At, 0, 1); PG8_STAGE(PG8_SA(0, 0), a2, voffA);
;             PG8_BAR; PG8_WAIT_L(0); PG8_MMA(1, 0, At, B0); PG8_BAR; PG8_SCHED;
.LBB0_1278:
	ds_read_b128 v[128:131], v190
	ds_read_b128 v[132:135], v190 offset:1024
	ds_read_b128 v[136:139], v190 offset:2048
	ds_read_b128 v[140:143], v190 offset:3072
	s_add_u32 s24, s22, 0xfff00080
	s_addc_u32 s25, s23, -1
	s_cmp_eq_u32 s48, 60
	s_cselect_b32 s27, s17, s25
	s_cselect_b32 s26, s44, s24
	s_cselect_b32 s25, s15, s47
	s_cselect_b32 s24, s45, s46
	v_lshl_add_u64 v[186:187], s[22:23], 0, v[162:163]
	s_add_i32 m0, s7, 0xc000
	ds_read_b128 v[144:147], v191
	ds_read_b128 v[148:151], v191 offset:1024
	ds_read_b128 v[170:173], v191 offset:2048
	ds_read_b128 v[174:177], v191 offset:3072
	ds_read_b128 v[178:181], v191 offset:4096
	ds_read_b128 v[182:185], v191 offset:5120
	ds_read_b128 v[194:197], v191 offset:6144
	ds_read_b128 v[198:201], v191 offset:7168
	global_load_lds_dwordx4 v[186:187], off
	v_lshl_add_u64 v[186:187], s[22:23], 0, v[164:165]
	s_add_i32 m0, s7, 0xe000
	s_nop 0
	global_load_lds_dwordx4 v[186:187], off
	s_waitcnt lgkmcnt(8)
	s_barrier
	s_waitcnt lgkmcnt(0)
	s_setprio 1
	s_waitcnt lgkmcnt(0)
	v_mfma_f32_16x16x32_bf16 v[124:127], v[128:131], v[144:147], v[124:127]
	v_mfma_f32_16x16x32_bf16 v[120:123], v[136:139], v[144:147], v[120:123]
	v_mfma_f32_16x16x32_bf16 v[108:111], v[128:131], v[170:173], v[108:111]
	v_mfma_f32_16x16x32_bf16 v[104:107], v[136:139], v[170:173], v[104:107]
	v_mfma_f32_16x16x32_bf16 v[92:95], v[128:131], v[178:181], v[92:95]
	v_mfma_f32_16x16x32_bf16 v[88:91], v[136:139], v[178:181], v[88:91]
	v_mfma_f32_16x16x32_bf16 v[76:79], v[128:131], v[194:197], v[76:79]
	v_mfma_f32_16x16x32_bf16 v[72:75], v[136:139], v[194:197], v[72:75]
	v_mfma_f32_16x16x32_bf16 v[124:127], v[132:135], v[148:151], v[124:127]
	v_mfma_f32_16x16x32_bf16 v[120:123], v[140:143], v[148:151], v[120:123]
	v_mfma_f32_16x16x32_bf16 v[108:111], v[132:135], v[174:177], v[108:111]
	v_mfma_f32_16x16x32_bf16 v[104:107], v[140:143], v[174:177], v[104:107]
	v_mfma_f32_16x16x32_bf16 v[92:95], v[132:135], v[182:185], v[92:95]
	v_mfma_f32_16x16x32_bf16 v[88:91], v[140:143], v[182:185], v[88:91]
	v_mfma_f32_16x16x32_bf16 v[76:79], v[132:135], v[198:201], v[76:79]
	v_mfma_f32_16x16x32_bf16 v[72:75], v[140:143], v[198:201], v[72:75]
	s_setprio 0
	s_barrier
	s_add_i32 s49, s42, s31
	v_lshl_add_u64 v[186:187], s[24:25], 0, v[156:157]
	s_mov_b32 m0, s49
	ds_read_b128 v[202:205], v192
	ds_read_b128 v[206:209], v192 offset:1024
	ds_read_b128 v[210:213], v192 offset:2048
	ds_read_b128 v[214:217], v192 offset:3072
	global_load_lds_dwordx4 v[186:187], off
	v_lshl_add_u64 v[218:219], s[24:25], 0, v[160:161]
	s_add_i32 m0, s49, 0x2000
	s_nop 0
	global_load_lds_dwordx4 v[218:219], off
	s_barrier
	s_waitcnt lgkmcnt(0)
	s_setprio 1
	s_waitcnt lgkmcnt(0)
	v_mfma_f32_16x16x32_bf16 v[116:119], v[202:205], v[144:147], v[116:119]
	v_mfma_f32_16x16x32_bf16 v[112:115], v[210:213], v[144:147], v[112:115]
	v_mfma_f32_16x16x32_bf16 v[100:103], v[202:205], v[170:173], v[100:103]
	v_mfma_f32_16x16x32_bf16 v[96:99], v[210:213], v[170:173], v[96:99]
	v_mfma_f32_16x16x32_bf16 v[84:87], v[202:205], v[178:181], v[84:87]
	v_mfma_f32_16x16x32_bf16 v[80:83], v[210:213], v[178:181], v[80:83]
	v_mfma_f32_16x16x32_bf16 v[68:71], v[202:205], v[194:197], v[68:71]
	v_mfma_f32_16x16x32_bf16 v[64:67], v[210:213], v[194:197], v[64:67]
	v_mfma_f32_16x16x32_bf16 v[116:119], v[206:209], v[148:151], v[116:119]
	v_mfma_f32_16x16x32_bf16 v[112:115], v[214:217], v[148:151], v[112:115]
	v_mfma_f32_16x16x32_bf16 v[100:103], v[206:209], v[174:177], v[100:103]
	v_mfma_f32_16x16x32_bf16 v[96:99], v[214:217], v[174:177], v[96:99]
	v_mfma_f32_16x16x32_bf16 v[84:87], v[206:209], v[182:185], v[84:87]
	v_mfma_f32_16x16x32_bf16 v[80:83], v[214:217], v[182:185], v[80:83]
	v_mfma_f32_16x16x32_bf16 v[68:71], v[206:209], v[198:201], v[68:71]
	v_mfma_f32_16x16x32_bf16 v[64:67], v[214:217], v[198:201], v[64:67]
	s_setprio 0
	s_mov_b32 m0, s7
	v_lshl_add_u64 v[220:221], s[26:27], 0, v[154:155]
	s_barrier
	ds_read_b128 v[144:147], v191 offset:16384
	ds_read_b128 v[148:151], v191 offset:17408
	ds_read_b128 v[170:173], v191 offset:18432
	ds_read_b128 v[174:177], v191 offset:19456
	ds_read_b128 v[178:181], v191 offset:20480
	ds_read_b128 v[182:185], v191 offset:21504
	ds_read_b128 v[194:197], v191 offset:22528
	ds_read_b128 v[198:201], v191 offset:23552
	global_load_lds_dwordx4 v[220:221], off
	v_lshl_add_u64 v[222:223], s[26:27], 0, v[158:159]
	s_mov_b32 m0, s34
	s_nop 0
	global_load_lds_dwordx4 v[222:223], off
	s_barrier
	s_waitcnt lgkmcnt(0)
	s_setprio 1
	s_waitcnt lgkmcnt(0)
	v_mfma_f32_16x16x32_bf16 v[60:63], v[128:131], v[144:147], v[60:63]
	v_mfma_f32_16x16x32_bf16 v[56:59], v[136:139], v[144:147], v[56:59]
	v_mfma_f32_16x16x32_bf16 v[44:47], v[128:131], v[170:173], v[44:47]
	v_mfma_f32_16x16x32_bf16 v[40:43], v[136:139], v[170:173], v[40:43]
	v_mfma_f32_16x16x32_bf16 v[28:31], v[128:131], v[178:181], v[28:31]
	v_mfma_f32_16x16x32_bf16 v[24:27], v[136:139], v[178:181], v[24:27]
	v_mfma_f32_16x16x32_bf16 v[12:15], v[128:131], v[194:197], v[12:15]
	v_mfma_f32_16x16x32_bf16 v[8:11], v[136:139], v[194:197], v[8:11]
	v_mfma_f32_16x16x32_bf16 v[60:63], v[132:135], v[148:151], v[60:63]
	v_mfma_f32_16x16x32_bf16 v[56:59], v[140:143], v[148:151], v[56:59]
	v_mfma_f32_16x16x32_bf16 v[44:47], v[132:135], v[174:177], v[44:47]
	v_mfma_f32_16x16x32_bf16 v[40:43], v[140:143], v[174:177], v[40:43]
	v_mfma_f32_16x16x32_bf16 v[28:31], v[132:135], v[182:185], v[28:31]
	v_mfma_f32_16x16x32_bf16 v[24:27], v[140:143], v[182:185], v[24:27]
	v_mfma_f32_16x16x32_bf16 v[12:15], v[132:135], v[198:201], v[12:15]
	v_mfma_f32_16x16x32_bf16 v[8:11], v[140:143], v[198:201], v[8:11]
	s_setprio 0
	s_barrier
; #define PG8_STAGE(bufoff, gbase, voff) do { _Pragma("unroll") for (int _i = 0; _i < 2; ++_i) \
;         __builtin_amdgcn_global_load_lds((const unsigned*)((const char*)(gbase) + (voff)[_i]), (LAS unsigned*)(lds + (bufoff) + ldsw + _i * 8192), 16, 0, 0); } while (0)
; #define PG8_LDA(dst, b, h) do { _Pragma("unroll") for (int m = 0; m < 4; ++m) _Pragma("unroll") for (int k = 0; k < 2; ++k) dst[m][k] = *(const LAS bf16x8*)(lds + PG8_SA(b, h) + aoff + m * 2048 + k * 1024); } while (0)
; #define PG8_LDB(dst, b, h) do { _Pragma("unroll") for (int n = 0; n < 2; ++n) _Pragma("unroll") for (int k = 0; k < 2; ++k) dst[n][k] = *(const LAS bf16x8*)(lds + PG8_SB(b, h) + boff + n * 2048 + k * 1024); } while (0)
; #define PG8_MMA(ai, bj, At, Bt) do { __builtin_amdgcn_s_setprio(1); _Pragma("unroll") for (int m = 0; m < 4; ++m) _Pragma("unroll") for (int n = 0; n < 2; ++n) _Pragma("unroll") for (int k = 0; k < 2; ++k) \
;         acc[ai][bj][m][n] = __builtin_amdgcn_mfma_f32_16x16x32_bf16(Bt[n][k], At[m][k], acc[ai][bj][m][n], 0, 0, 0); __builtin_amdgcn_s_setprio(0); } while (0)
; #define PG8_WAIT_V(n) asm volatile("s_waitcnt vmcnt(" #n ")" ::: "memory")
; #define PG8_WAIT_L(n) asm volatile("s_waitcnt lgkmcnt(" #n ")" ::: "memory")
; #define PG8_BAR __builtin_amdgcn_s_barrier()
; #define PG8_SCHED __builtin_amdgcn_sched_barrier(0)
; template <class Epi>
; __device__ __forceinline__ void gemm_phase(LAS unsigned char* lds, const Gemm g, const StaticOrder& S, const Epi& E) {
;     ...
;             PG8_STAGE(PG8_SB(0, 1), b2 + hstepB, voffB);
;             PG8_WAIT_V(6); PG8_BAR; PG8_MMA(1, 1, At, B1); PG8_BAR;
;             PG8_LDB(B0, 1, 0); PG8_SCHED; PG8_LDA(At, 1, 0); PG8_STAGE(PG8_SA(0, 1), a2 + hstepA, voffA);
;             PG8_WAIT_L(8); PG8_BAR; PG8_WAIT_L(0); PG8_MMA(0, 0, At, B0); PG8_BAR; PG8_SCHED;
;             PG8_LDB(B1, 1, 1); PG8_STAGE(PG8_SB(1, 0), b3, voffB);
;             PG8_BAR; PG8_WAIT_L(0); PG8_MMA(0, 1, At, B1); PG8_BAR;
;             PG8_LDA(At, 1, 1); PG8_STAGE(PG8_SA(1, 0), a3, voffA);
;             PG8_BAR; PG8_WAIT_L(0); PG8_MMA(1, 0, At, B0); PG8_BAR; PG8_SCHED;
	s_add_u32 s50, s24, 0x100000
	s_addc_u32 s51, s25, 0
	s_add_i32 s49, s43, s31
	v_lshl_add_u64 v[128:129], s[50:51], 0, v[156:157]
	s_mov_b32 m0, s49
	s_nop 0
	global_load_lds_dwordx4 v[128:129], off
	v_lshl_add_u64 v[128:129], s[50:51], 0, v[160:161]
	s_add_i32 m0, s49, 0x2000
	s_nop 0
	global_load_lds_dwordx4 v[128:129], off
	s_waitcnt vmcnt(6)
	s_barrier
	s_setprio 1
	v_mfma_f32_16x16x32_bf16 v[52:55], v[202:205], v[144:147], v[52:55]
	v_mfma_f32_16x16x32_bf16 v[48:51], v[210:213], v[144:147], v[48:51]
	v_mfma_f32_16x16x32_bf16 v[36:39], v[202:205], v[170:173], v[36:39]
	v_mfma_f32_16x16x32_bf16 v[32:35], v[210:213], v[170:173], v[32:35]
	v_mfma_f32_16x16x32_bf16 v[20:23], v[202:205], v[178:181], v[20:23]
	v_mfma_f32_16x16x32_bf16 v[16:19], v[210:213], v[178:181], v[16:19]
	v_mfma_f32_16x16x32_bf16 v[4:7], v[202:205], v[194:197], v[4:7]
	v_mfma_f32_16x16x32_bf16 v[0:3], v[210:213], v[194:197], v[0:3]
	v_mfma_f32_16x16x32_bf16 v[52:55], v[206:209], v[148:151], v[52:55]
	v_mfma_f32_16x16x32_bf16 v[48:51], v[214:217], v[148:151], v[48:51]
	v_mfma_f32_16x16x32_bf16 v[36:39], v[206:209], v[174:177], v[36:39]
	v_mfma_f32_16x16x32_bf16 v[32:35], v[214:217], v[174:177], v[32:35]
	v_mfma_f32_16x16x32_bf16 v[20:23], v[206:209], v[182:185], v[20:23]
	v_mfma_f32_16x16x32_bf16 v[16:19], v[214:217], v[182:185], v[16:19]
	v_mfma_f32_16x16x32_bf16 v[4:7], v[206:209], v[198:201], v[4:7]
	v_mfma_f32_16x16x32_bf16 v[0:3], v[214:217], v[198:201], v[0:3]
	s_setprio 0
	s_add_i32 s49, 0, 0x18000
	v_add_u32_e32 v140, s49, v188
	s_barrier
	ds_read_b128 v[128:131], v140
	ds_read_b128 v[132:135], v140 offset:1024
	ds_read_b128 v[136:139], v140 offset:2048
	ds_read_b128 v[140:143], v140 offset:3072
	s_add_u32 s26, s26, 0x100000
	s_addc_u32 s27, s27, 0
	s_mov_b32 m0, s35
	v_lshl_add_u64 v[202:203], s[26:27], 0, v[154:155]
	ds_read_b128 v[144:147], v191 offset:32768
	ds_read_b128 v[148:151], v191 offset:33792
	ds_read_b128 v[170:173], v191 offset:34816
	ds_read_b128 v[174:177], v191 offset:35840
	ds_read_b128 v[178:181], v191 offset:36864
	ds_read_b128 v[182:185], v191 offset:37888
	ds_read_b128 v[194:197], v191 offset:38912
	ds_read_b128 v[198:201], v191 offset:39936
	global_load_lds_dwordx4 v[202:203], off
	v_lshl_add_u64 v[202:203], s[26:27], 0, v[158:159]
	s_mov_b32 m0, s36
	s_nop 0
	global_load_lds_dwordx4 v[202:203], off
	s_waitcnt lgkmcnt(8)
	s_barrier
	s_waitcnt lgkmcnt(0)
	s_setprio 1
	s_waitcnt lgkmcnt(0)
	v_mfma_f32_16x16x32_bf16 v[124:127], v[128:131], v[144:147], v[124:127]
	v_mfma_f32_16x16x32_bf16 v[120:123], v[136:139], v[144:147], v[120:123]
	v_mfma_f32_16x16x32_bf16 v[108:111], v[128:131], v[170:173], v[108:111]
	v_mfma_f32_16x16x32_bf16 v[104:107], v[136:139], v[170:173], v[104:107]
	v_mfma_f32_16x16x32_bf16 v[92:95], v[128:131], v[178:181], v[92:95]
	v_mfma_f32_16x16x32_bf16 v[88:91], v[136:139], v[178:181], v[88:91]
	v_mfma_f32_16x16x32_bf16 v[76:79], v[128:131], v[194:197], v[76:79]
	v_mfma_f32_16x16x32_bf16 v[72:75], v[136:139], v[194:197], v[72:75]
	v_mfma_f32_16x16x32_bf16 v[124:127], v[132:135], v[148:151], v[124:127]
	v_mfma_f32_16x16x32_bf16 v[120:123], v[140:143], v[148:151], v[120:123]
	v_mfma_f32_16x16x32_bf16 v[108:111], v[132:135], v[174:177], v[108:111]
	v_mfma_f32_16x16x32_bf16 v[104:107], v[140:143], v[174:177], v[104:107]
	v_mfma_f32_16x16x32_bf16 v[92:95], v[132:135], v[182:185], v[92:95]
	v_mfma_f32_16x16x32_bf16 v[88:91], v[140:143], v[182:185], v[88:91]
	v_mfma_f32_16x16x32_bf16 v[76:79], v[132:135], v[198:201], v[76:79]
	v_mfma_f32_16x16x32_bf16 v[72:75], v[140:143], v[198:201], v[72:75]
	s_setprio 0
	s_barrier
	s_add_i32 s26, 0, 0x1c000
	s_add_i32 s27, s49, s31
	v_add_u32_e32 v214, s26, v188
	v_lshl_add_u64 v[186:187], v[186:187], 0, s[12:13]
	s_mov_b32 m0, s27
	ds_read_b128 v[202:205], v214
	ds_read_b128 v[206:209], v214 offset:1024
	ds_read_b128 v[210:213], v214 offset:2048
	ds_read_b128 v[214:217], v214 offset:3072
	global_load_lds_dwordx4 v[186:187], off
	v_lshl_add_u64 v[186:187], v[218:219], 0, s[12:13]
	s_add_i32 m0, s27, 0x2000
	s_nop 0
	global_load_lds_dwordx4 v[186:187], off
	s_barrier
	s_waitcnt lgkmcnt(0)
	s_setprio 1
	s_waitcnt lgkmcnt(0)
	v_mfma_f32_16x16x32_bf16 v[116:119], v[202:205], v[144:147], v[116:119]
	v_mfma_f32_16x16x32_bf16 v[112:115], v[210:213], v[144:147], v[112:115]
	v_mfma_f32_16x16x32_bf16 v[100:103], v[202:205], v[170:173], v[100:103]
	v_mfma_f32_16x16x32_bf16 v[96:99], v[210:213], v[170:173], v[96:99]
	v_mfma_f32_16x16x32_bf16 v[84:87], v[202:205], v[178:181], v[84:87]
	v_mfma_f32_16x16x32_bf16 v[80:83], v[210:213], v[178:181], v[80:83]
	v_mfma_f32_16x16x32_bf16 v[68:71], v[202:205], v[194:197], v[68:71]
	v_mfma_f32_16x16x32_bf16 v[64:67], v[210:213], v[194:197], v[64:67]
	v_mfma_f32_16x16x32_bf16 v[116:119], v[206:209], v[148:151], v[116:119]
	v_mfma_f32_16x16x32_bf16 v[112:115], v[214:217], v[148:151], v[112:115]
	v_mfma_f32_16x16x32_bf16 v[100:103], v[206:209], v[174:177], v[100:103]
	v_mfma_f32_16x16x32_bf16 v[96:99], v[214:217], v[174:177], v[96:99]
	v_mfma_f32_16x16x32_bf16 v[84:87], v[206:209], v[182:185], v[84:87]
	v_mfma_f32_16x16x32_bf16 v[80:83], v[214:217], v[182:185], v[80:83]
	v_mfma_f32_16x16x32_bf16 v[68:71], v[206:209], v[198:201], v[68:71]
	v_mfma_f32_16x16x32_bf16 v[64:67], v[214:217], v[198:201], v[64:67]
	s_setprio 0
	s_mov_b32 m0, s38
	v_lshl_add_u64 v[186:187], v[220:221], 0, s[12:13]
	s_barrier
	ds_read_b128 v[144:147], v191 offset:49152
	ds_read_b128 v[148:151], v191 offset:50176
	ds_read_b128 v[170:173], v191 offset:51200
	ds_read_b128 v[174:177], v191 offset:52224
	ds_read_b128 v[178:181], v191 offset:53248
	ds_read_b128 v[182:185], v191 offset:54272
	ds_read_b128 v[194:197], v191 offset:55296
	ds_read_b128 v[198:201], v191 offset:56320
	global_load_lds_dwordx4 v[186:187], off
	v_lshl_add_u64 v[186:187], v[222:223], 0, s[12:13]
	s_mov_b32 m0, s39
	s_nop 0
	global_load_lds_dwordx4 v[186:187], off
	s_barrier
; #define PG8_STAGE(bufoff, gbase, voff) do { _Pragma("unroll") for (int _i = 0; _i < 2; ++_i) \
;         __builtin_amdgcn_global_load_lds((const unsigned*)((const char*)(gbase) + (voff)[_i]), (LAS unsigned*)(lds + (bufoff) + ldsw + _i * 8192), 16, 0, 0); } while (0)
; #define PG8_LDA(dst, b, h) do { _Pragma("unroll") for (int m = 0; m < 4; ++m) _Pragma("unroll") for (int k = 0; k < 2; ++k) dst[m][k] = *(const LAS bf16x8*)(lds + PG8_SA(b, h) + aoff + m * 2048 + k * 1024); } while (0)
; #define PG8_MMA(ai, bj, At, Bt) do { __builtin_amdgcn_s_setprio(1); _Pragma("unroll") for (int m = 0; m < 4; ++m) _Pragma("unroll") for (int n = 0; n < 2; ++n) _Pragma("unroll") for (int k = 0; k < 2; ++k) \
;         acc[ai][bj][m][n] = __builtin_amdgcn_mfma_f32_16x16x32_bf16(Bt[n][k], At[m][k], acc[ai][bj][m][n], 0, 0, 0); __builtin_amdgcn_s_setprio(0); } while (0)
; #define PG8_WAIT_V(n) asm volatile("s_waitcnt vmcnt(" #n ")" ::: "memory")
; #define PG8_WAIT_L(n) asm volatile("s_waitcnt lgkmcnt(" #n ")" ::: "memory")
; #define PG8_BAR __builtin_amdgcn_s_barrier()
; #define PG8_SCHED __builtin_amdgcn_sched_barrier(0)
; template <class Epi>
; __device__ __forceinline__ void gemm_phase(LAS unsigned char* lds, const Gemm g, const StaticOrder& S, const Epi& E) {
;     ...
;             PG8_BAR; PG8_WAIT_L(0); PG8_MMA(0, 1, At, B1); PG8_BAR;
;             PG8_LDA(At, 1, 1); PG8_STAGE(PG8_SA(1, 0), a3, voffA);
;             PG8_BAR; PG8_WAIT_L(0); PG8_MMA(1, 0, At, B0); PG8_BAR; PG8_SCHED;
;             PG8_STAGE(PG8_SB(1, 1), b3 + hstepB, voffB);
;             PG8_WAIT_V(6); PG8_BAR; PG8_MMA(1, 1, At, B1); PG8_BAR;
;         }
	s_waitcnt lgkmcnt(0)
	s_setprio 1
	s_waitcnt lgkmcnt(0)
	v_mfma_f32_16x16x32_bf16 v[60:63], v[128:131], v[144:147], v[60:63]
	v_mfma_f32_16x16x32_bf16 v[56:59], v[136:139], v[144:147], v[56:59]
	v_mfma_f32_16x16x32_bf16 v[44:47], v[128:131], v[170:173], v[44:47]
	v_mfma_f32_16x16x32_bf16 v[40:43], v[136:139], v[170:173], v[40:43]
	v_mfma_f32_16x16x32_bf16 v[28:31], v[128:131], v[178:181], v[28:31]
	v_mfma_f32_16x16x32_bf16 v[24:27], v[136:139], v[178:181], v[24:27]
	v_mfma_f32_16x16x32_bf16 v[12:15], v[128:131], v[194:197], v[12:15]
	v_mfma_f32_16x16x32_bf16 v[8:11], v[136:139], v[194:197], v[8:11]
	v_mfma_f32_16x16x32_bf16 v[60:63], v[132:135], v[148:151], v[60:63]
	v_mfma_f32_16x16x32_bf16 v[56:59], v[140:143], v[148:151], v[56:59]
	v_mfma_f32_16x16x32_bf16 v[44:47], v[132:135], v[174:177], v[44:47]
	v_mfma_f32_16x16x32_bf16 v[40:43], v[140:143], v[174:177], v[40:43]
	v_mfma_f32_16x16x32_bf16 v[28:31], v[132:135], v[182:185], v[28:31]
	v_mfma_f32_16x16x32_bf16 v[24:27], v[140:143], v[182:185], v[24:27]
	v_mfma_f32_16x16x32_bf16 v[12:15], v[132:135], v[198:201], v[12:15]
	v_mfma_f32_16x16x32_bf16 v[8:11], v[140:143], v[198:201], v[8:11]
	s_setprio 0
	s_barrier
	s_add_u32 s24, s24, 0x100080
	s_addc_u32 s25, s25, 0
	s_add_i32 s26, s26, s31
	v_lshl_add_u64 v[128:129], s[24:25], 0, v[156:157]
	s_mov_b32 m0, s26
	s_nop 0
	global_load_lds_dwordx4 v[128:129], off
	v_lshl_add_u64 v[128:129], s[24:25], 0, v[160:161]
	s_add_i32 m0, s26, 0x2000
	s_nop 0
	global_load_lds_dwordx4 v[128:129], off
	s_waitcnt vmcnt(6)
	s_barrier
	s_setprio 1
	v_mfma_f32_16x16x32_bf16 v[52:55], v[202:205], v[144:147], v[52:55]
	v_mfma_f32_16x16x32_bf16 v[48:51], v[210:213], v[144:147], v[48:51]
	v_mfma_f32_16x16x32_bf16 v[36:39], v[202:205], v[170:173], v[36:39]
	v_mfma_f32_16x16x32_bf16 v[32:35], v[210:213], v[170:173], v[32:35]
	v_mfma_f32_16x16x32_bf16 v[20:23], v[202:205], v[178:181], v[20:23]
	v_mfma_f32_16x16x32_bf16 v[16:19], v[210:213], v[178:181], v[16:19]
	v_mfma_f32_16x16x32_bf16 v[4:7], v[202:205], v[194:197], v[4:7]
	v_mfma_f32_16x16x32_bf16 v[0:3], v[210:213], v[194:197], v[0:3]
	v_mfma_f32_16x16x32_bf16 v[52:55], v[206:209], v[148:151], v[52:55]
	v_mfma_f32_16x16x32_bf16 v[48:51], v[214:217], v[148:151], v[48:51]
	v_mfma_f32_16x16x32_bf16 v[36:39], v[206:209], v[174:177], v[36:39]
	v_mfma_f32_16x16x32_bf16 v[32:35], v[214:217], v[174:177], v[32:35]
	v_mfma_f32_16x16x32_bf16 v[20:23], v[206:209], v[182:185], v[20:23]
	v_mfma_f32_16x16x32_bf16 v[16:19], v[214:217], v[182:185], v[16:19]
	v_mfma_f32_16x16x32_bf16 v[4:7], v[206:209], v[198:201], v[4:7]
	v_mfma_f32_16x16x32_bf16 v[0:3], v[214:217], v[198:201], v[0:3]
	s_setprio 0
	s_add_i32 s48, s48, 2
	s_add_u32 s22, s22, 0x100
	s_addc_u32 s23, s23, 0
	s_add_u32 s46, s46, 0x100
	s_addc_u32 s47, s47, 0
	s_cmp_gt_u32 s48, 61
	s_barrier
	s_cbranch_scc0 .LBB0_1278
; __device__ __forceinline__ unsigned pk2(float lo, float hi) { const f32x2 v = (f32x2){lo, hi}; const bf16x2_t b = __builtin_convertvector(v, bf16x2_t); return __builtin_bit_cast(unsigned, b); }
; __device__ __forceinline__ void unpack8(const u32x4 v, float* f) { f[0] = bf_lo(v.x); f[1] = bf_hi(v.x); f[2] = bf_lo(v.y); f[3] = bf_hi(v.y); f[4] = bf_lo(v.z); f[5] = bf_hi(v.z); f[6] = bf_lo(v.w); f[7] = bf_hi(v.w); }
;     __device__ __forceinline__ void operator()(const f32x4 (&acc)[2][2][4][2], const Unit& u, int wr, int wc, int fr, int fq, const float (&)[8]) const {
;         const int row0 = u.pm * BM + wr * 64 + fr, col0 = u.pn * BM + wc * 32 + 8 * fq;
; #pragma unroll
;         for (int ai = 0; ai < 2; ++ai) {
;             u32x4 bv[4][2];
; #pragma unroll
;             for (int m = 0; m < 4; ++m)
; #pragma unroll
;                 for (int bj = 0; bj < 2; ++bj) bv[m][bj] = *(const u32x4*)(xb + (size_t)(row0 + ai * HALF + m * 16) * DM + col0 + bj * HALF);
; #pragma unroll
;             for (int m = 0; m < 4; ++m) { const int row = row0 + ai * HALF + m * 16; const size_t ro = (size_t)row * DM + col0; float s = 0.f;
; #pragma unroll
;                 for (int bj = 0; bj < 2; ++bj) { float b8[8]; unpack8(bv[m][bj], b8);
;                     const f32x4 v0 = (f32x4){b8[0], b8[1], b8[2], b8[3]} + acc[ai][bj][m][0], v1 = (f32x4){b8[4], b8[5], b8[6], b8[7]} + acc[ai][bj][m][1];
;                     s += v0[0] * v0[0] + v0[1] * v0[1] + v0[2] * v0[2] + v0[3] * v0[3] + v1[0] * v1[0] + v1[1] * v1[1] + v1[2] * v1[2] + v1[3] * v1[3];
;                     if (LAST) { *(f32x4*)(out + ro + bj * HALF) = v0; *(f32x4*)(out + ro + bj * HALF + 4) = v1; }
;                     else { u32x4 w; w.x = pk2(v0[0], v0[1]); w.y = pk2(v0[2], v0[3]); w.z = pk2(v1[0], v1[1]); w.w = pk2(v1[2], v1[3]); *(u32x4*)(xb + ro + bj * HALF) = w; } }
;                 s += __shfl_xor(s, 16); s += __shfl_xor(s, 32);
;                 if (fq == 0) ss[(size_t)row * 16 + u.pn * 4 + wc] = s; }
	v_lshl_or_b32 v170, s6, 8, v189
	v_lshl_add_u32 v172, s8, 8, v153
	v_ashrrev_i32_e32 v171, 31, v170
	v_lshlrev_b64 v[204:205], 1, v[170:171]
	v_ashrrev_i32_e32 v173, 31, v172
	v_lshl_add_u64 v[174:175], s[76:77], 0, v[204:205]
	v_lshlrev_b64 v[206:207], 11, v[172:173]
	v_lshl_add_u64 v[128:129], v[174:175], 0, v[206:207]
	global_load_dwordx4 v[196:199], v[128:129], off
	global_load_dwordx4 v[200:203], v[128:129], off offset:256
	v_or_b32_e32 v184, 16, v172
	v_or_b32_e32 v180, 32, v172
	v_or_b32_e32 v176, 48, v172
	v_ashrrev_i32_e32 v185, 31, v184
	v_ashrrev_i32_e32 v181, 31, v180
	v_ashrrev_i32_e32 v177, 31, v176
	v_lshlrev_b64 v[186:187], 11, v[184:185]
	v_lshlrev_b64 v[182:183], 11, v[180:181]
	v_lshlrev_b64 v[178:179], 11, v[176:177]
	v_lshl_add_u64 v[128:129], v[174:175], 0, v[186:187]
	v_lshl_add_u64 v[130:131], v[174:175], 0, v[182:183]
	v_lshl_add_u64 v[194:195], v[174:175], 0, v[178:179]
	global_load_dwordx4 v[148:151], v[128:129], off
	global_load_dwordx4 v[144:147], v[128:129], off offset:256
	global_load_dwordx4 v[140:143], v[130:131], off
	global_load_dwordx4 v[136:139], v[130:131], off offset:256
	global_load_dwordx4 v[132:135], v[194:195], off
	s_nop 0
	global_load_dwordx4 v[128:131], v[194:195], off offset:256
	v_add_u32_e32 v226, 0x80, v172
	v_ashrrev_i32_e32 v227, 31, v226
	v_lshlrev_b64 v[226:227], 11, v[226:227]
	v_lshl_add_u64 v[226:227], v[174:175], 0, v[226:227]
	global_load_dwordx4 v[216:219], v[226:227], off
	global_load_dwordx4 v[220:223], v[226:227], off offset:256
	v_add_u32_e32 v226, 0x90, v172
	v_ashrrev_i32_e32 v227, 31, v226
	v_lshlrev_b64 v[226:227], 11, v[226:227]
	v_lshl_add_u64 v[226:227], v[174:175], 0, v[226:227]
	global_load_dwordx4 v[228:231], v[226:227], off
	global_load_dwordx4 v[232:235], v[226:227], off offset:256
	v_add_u32_e32 v226, 0xa0, v172
	v_ashrrev_i32_e32 v227, 31, v226
	v_lshlrev_b64 v[226:227], 11, v[226:227]
	v_lshl_add_u64 v[226:227], v[174:175], 0, v[226:227]
	global_load_dwordx4 v[236:239], v[226:227], off
	global_load_dwordx4 v[240:243], v[226:227], off offset:256
	v_add_u32_e32 v226, 0xb0, v172
	v_ashrrev_i32_e32 v227, 31, v226
	v_lshlrev_b64 v[226:227], 11, v[226:227]
	v_lshl_add_u64 v[226:227], v[174:175], 0, v[226:227]
	global_load_dwordx4 v[244:247], v[226:227], off
	global_load_dwordx4 v[252:255], v[226:227], off offset:256
	v_and_b32_e32 v195, 64, v193
	v_xor_b32_e32 v194, 16, v193
	v_add_u32_e32 v195, 64, v195
	v_xor_b32_e32 v208, 32, v193
	v_cmp_lt_i32_e32 vcc, v194, v195
	s_waitcnt vmcnt(0)
	v_and_b32_e32 v209, 0xffff0000, v196
	v_cndmask_b32_e32 v194, v193, v194, vcc
	v_cmp_lt_i32_e32 vcc, v208, v195
	v_lshlrev_b32_e32 v195, 2, v194
	v_lshlrev_b32_e32 v212, 16, v200
	v_cndmask_b32_e32 v208, v193, v208, vcc
	v_lshlrev_b32_e32 v194, 2, v208
	v_lshlrev_b32_e32 v208, 16, v196
	v_and_b32_e32 v213, 0xffff0000, v200
	v_lshlrev_b32_e32 v210, 16, v198
	v_and_b32_e32 v211, 0xffff0000, v198
	v_lshlrev_b32_e32 v198, 16, v199
	v_and_b32_e32 v199, 0xffff0000, v199
	v_lshlrev_b32_e32 v200, 16, v201
	v_and_b32_e32 v201, 0xffff0000, v201
	v_lshlrev_b32_e32 v214, 16, v202
	v_and_b32_e32 v215, 0xffff0000, v202
	v_pk_add_f32 v[124:125], v[124:125], v[208:209]
	v_pk_add_f32 v[116:117], v[116:117], v[212:213]
	v_lshlrev_b32_e32 v196, 16, v197
	v_and_b32_e32 v197, 0xffff0000, v197
	v_pk_add_f32 v[122:123], v[122:123], v[198:199]
	v_pk_add_f32 v[118:119], v[118:119], v[200:201]
	v_pk_add_f32 v[198:199], v[112:113], v[214:215]
	v_mul_f32_e32 v200, v125, v125
	v_cvt_pk_bf16_f32 v112, v124, v125
	v_mul_f32_e32 v125, v117, v117
	v_pk_add_f32 v[126:127], v[126:127], v[196:197]
	v_fmac_f32_e32 v200, v124, v124
	v_fmac_f32_e32 v125, v116, v116
	v_fmac_f32_e32 v200, v126, v126
	v_fmac_f32_e32 v125, v118, v118
	v_pk_add_f32 v[120:121], v[120:121], v[210:211]
	v_fmac_f32_e32 v200, v127, v127
	v_fmac_f32_e32 v125, v119, v119
	v_lshlrev_b32_e32 v202, 16, v203
	v_and_b32_e32 v203, 0xffff0000, v203
	v_fmac_f32_e32 v200, v120, v120
	v_fmac_f32_e32 v125, v198, v198
	v_pk_add_f32 v[196:197], v[114:115], v[202:203]
	v_fmac_f32_e32 v200, v121, v121
	v_fmac_f32_e32 v125, v199, v199
	v_fmac_f32_e32 v200, v122, v122
	v_fmac_f32_e32 v125, v196, v196
	v_fmac_f32_e32 v200, v123, v123
	v_fmac_f32_e32 v125, v197, v197
	v_cvt_pk_bf16_f32 v115, v122, v123
	v_add_f32_e32 v122, v200, v125
	ds_bpermute_b32 v123, v195, v122
	v_cvt_pk_bf16_f32 v114, v120, v121
	v_lshl_add_u64 v[120:121], s[76:77], 0, v[206:207]
	v_cvt_pk_bf16_f32 v113, v126, v127
	v_lshl_add_u64 v[120:121], v[120:121], 0, v[204:205]
	global_store_dwordx4 v[120:121], v[112:115], off
	s_waitcnt lgkmcnt(0)
	s_nop 0
	v_add_f32_e32 v112, v122, v123
	ds_bpermute_b32 v113, v194, v112
	v_cvt_pk_bf16_f32 v114, v116, v117
	v_cvt_pk_bf16_f32 v115, v118, v119
	v_cvt_pk_bf16_f32 v116, v198, v199
	v_cvt_pk_bf16_f32 v117, v196, v197
	global_store_dwordx4 v[120:121], v[114:117], off offset:256
	s_and_saveexec_b64 s[22:23], s[0:1]
	s_cbranch_execz .LBB0_1281
	s_waitcnt lgkmcnt(0)
	v_add_f32_e32 v114, v112, v113
	s_lshl_b32 s24, s6, 2
	v_lshlrev_b64 v[112:113], 6, v[172:173]
	s_ashr_i32 s25, s24, 31
	v_lshl_add_u64 v[112:113], s[10:11], 0, v[112:113]
	v_lshl_add_u64 v[112:113], s[24:25], 2, v[112:113]
	s_lshl_b32 s8, s37, 2
	v_lshl_add_u64 v[112:113], v[112:113], 0, s[8:9]
	global_store_dword v[112:113], v114, off

; __device__ __forceinline__ unsigned pk2(float lo, float hi) { const f32x2 v = (f32x2){lo, hi}; const bf16x2_t b = __builtin_convertvector(v, bf16x2_t); return __builtin_bit_cast(unsigned, b); }
; __device__ __forceinline__ void unpack8(const u32x4 v, float* f) { f[0] = bf_lo(v.x); f[1] = bf_hi(v.x); f[2] = bf_lo(v.y); f[3] = bf_hi(v.y); f[4] = bf_lo(v.z); f[5] = bf_hi(v.z); f[6] = bf_lo(v.w); f[7] = bf_hi(v.w); }
;     __device__ __forceinline__ void operator()(const f32x4 (&acc)[2][2][4][2], const Unit& u, int wr, int wc, int fr, int fq, const float (&)[8]) const {
;     ...
;                 for (int bj = 0; bj < 2; ++bj) bv[m][bj] = *(const u32x4*)(xb + (size_t)(row0 + ai * HALF + m * 16) * DM + col0 + bj * HALF);
; #pragma unroll
;             for (int m = 0; m < 4; ++m) { const int row = row0 + ai * HALF + m * 16; const size_t ro = (size_t)row * DM + col0; float s = 0.f;
; #pragma unroll
;                 for (int bj = 0; bj < 2; ++bj) { float b8[8]; unpack8(bv[m][bj], b8);
;                     const f32x4 v0 = (f32x4){b8[0], b8[1], b8[2], b8[3]} + acc[ai][bj][m][0], v1 = (f32x4){b8[4], b8[5], b8[6], b8[7]} + acc[ai][bj][m][1];
;                     s += v0[0] * v0[0] + v0[1] * v0[1] + v0[2] * v0[2] + v0[3] * v0[3] + v1[0] * v1[0] + v1[1] * v1[1] + v1[2] * v1[2] + v1[3] * v1[3];
;                     if (LAST) { *(f32x4*)(out + ro + bj * HALF) = v0; *(f32x4*)(out + ro + bj * HALF + 4) = v1; }
;                     else { u32x4 w; w.x = pk2(v0[0], v0[1]); w.y = pk2(v0[2], v0[3]); w.z = pk2(v1[0], v1[1]); w.w = pk2(v1[2], v1[3]); *(u32x4*)(xb + ro + bj * HALF) = w; } }
;                 s += __shfl_xor(s, 16); s += __shfl_xor(s, 32);
;                 if (fq == 0) ss[(size_t)row * 16 + u.pn * 4 + wc] = s; }
.LBB0_1287:
	s_or_b64 exec, exec, s[22:23]
	v_add_u32_e32 v100, 0x80, v172
	v_ashrrev_i32_e32 v101, 31, v100
	v_lshlrev_b64 v[110:111], 11, v[100:101]
	s_waitcnt lgkmcnt(0)
	v_lshl_add_u64 v[64:65], v[174:175], 0, v[110:111]
	v_mov_b32_e32 v102, v216
	v_mov_b32_e32 v103, v217
	v_mov_b32_e32 v104, v218
	v_mov_b32_e32 v105, v219
	v_mov_b32_e32 v106, v220
	v_mov_b32_e32 v107, v221
	v_mov_b32_e32 v108, v222
	v_mov_b32_e32 v109, v223
	v_add_u32_e32 v96, 0x90, v172
	v_add_u32_e32 v92, 0xa0, v172
	v_add_u32_e32 v88, 0xb0, v172
	v_ashrrev_i32_e32 v97, 31, v96
	v_ashrrev_i32_e32 v93, 31, v92
	v_ashrrev_i32_e32 v89, 31, v88
	v_lshlrev_b64 v[98:99], 11, v[96:97]
	v_lshlrev_b64 v[94:95], 11, v[92:93]
	v_lshlrev_b64 v[90:91], 11, v[88:89]
	v_lshl_add_u64 v[64:65], v[174:175], 0, v[98:99]
	v_lshl_add_u64 v[66:67], v[174:175], 0, v[94:95]
	v_lshl_add_u64 v[112:113], v[174:175], 0, v[90:91]
	v_mov_b32_e32 v84, v228
	v_mov_b32_e32 v85, v229
	v_mov_b32_e32 v86, v230
	v_mov_b32_e32 v87, v231
	v_mov_b32_e32 v80, v232
	v_mov_b32_e32 v81, v233
	v_mov_b32_e32 v82, v234
	v_mov_b32_e32 v83, v235
	v_mov_b32_e32 v76, v236
	v_mov_b32_e32 v77, v237
	v_mov_b32_e32 v78, v238
	v_mov_b32_e32 v79, v239
	v_mov_b32_e32 v72, v240
	v_mov_b32_e32 v73, v241
	v_mov_b32_e32 v74, v242
	v_mov_b32_e32 v75, v243
	v_mov_b32_e32 v68, v244
	v_mov_b32_e32 v69, v245
	v_mov_b32_e32 v70, v246
	v_mov_b32_e32 v71, v247
	s_nop 0
	v_mov_b32_e32 v64, v252
	v_mov_b32_e32 v65, v253
	v_mov_b32_e32 v66, v254
	v_mov_b32_e32 v67, v255
	s_nop 0
	v_lshlrev_b32_e32 v112, 16, v102
	v_and_b32_e32 v113, 0xffff0000, v102
	s_nop 0
	v_lshlrev_b32_e32 v116, 16, v106
	v_and_b32_e32 v117, 0xffff0000, v106
	v_lshlrev_b32_e32 v114, 16, v104
	v_and_b32_e32 v115, 0xffff0000, v104
	v_lshlrev_b32_e32 v104, 16, v105
	v_and_b32_e32 v105, 0xffff0000, v105
	v_lshlrev_b32_e32 v106, 16, v107
	v_and_b32_e32 v107, 0xffff0000, v107
	v_lshlrev_b32_e32 v118, 16, v108
	v_and_b32_e32 v119, 0xffff0000, v108
	v_pk_add_f32 v[60:61], v[60:61], v[112:113]
	v_pk_add_f32 v[52:53], v[52:53], v[116:117]
	v_lshlrev_b32_e32 v102, 16, v103
	v_and_b32_e32 v103, 0xffff0000, v103
	v_pk_add_f32 v[58:59], v[58:59], v[104:105]
	v_pk_add_f32 v[54:55], v[54:55], v[106:107]
	v_pk_add_f32 v[104:105], v[48:49], v[118:119]
	v_mul_f32_e32 v106, v61, v61
	v_cvt_pk_bf16_f32 v48, v60, v61
	v_mul_f32_e32 v61, v53, v53
	v_pk_add_f32 v[62:63], v[62:63], v[102:103]
	v_fmac_f32_e32 v106, v60, v60
	v_fmac_f32_e32 v61, v52, v52
	v_fmac_f32_e32 v106, v62, v62
	v_fmac_f32_e32 v61, v54, v54
	v_pk_add_f32 v[56:57], v[56:57], v[114:115]
	v_fmac_f32_e32 v106, v63, v63
	v_fmac_f32_e32 v61, v55, v55
	v_lshlrev_b32_e32 v108, 16, v109
	v_and_b32_e32 v109, 0xffff0000, v109
	v_fmac_f32_e32 v106, v56, v56
	v_fmac_f32_e32 v61, v104, v104
	v_pk_add_f32 v[102:103], v[50:51], v[108:109]
	v_fmac_f32_e32 v106, v57, v57
	v_fmac_f32_e32 v61, v105, v105
	v_fmac_f32_e32 v106, v58, v58
	v_fmac_f32_e32 v61, v102, v102
	v_fmac_f32_e32 v106, v59, v59
	v_fmac_f32_e32 v61, v103, v103
	v_cvt_pk_bf16_f32 v51, v58, v59
	v_add_f32_e32 v58, v106, v61
	ds_bpermute_b32 v59, v195, v58
	v_cvt_pk_bf16_f32 v50, v56, v57
	v_lshl_add_u64 v[56:57], s[76:77], 0, v[110:111]
	v_cvt_pk_bf16_f32 v49, v62, v63
	v_lshl_add_u64 v[56:57], v[170:171], 1, v[56:57]
	global_store_dwordx4 v[56:57], v[48:51], off
	s_waitcnt lgkmcnt(0)
	s_nop 0
	v_add_f32_e32 v48, v58, v59
	ds_bpermute_b32 v49, v194, v48
	v_cvt_pk_bf16_f32 v50, v52, v53
	v_cvt_pk_bf16_f32 v51, v54, v55
	v_cvt_pk_bf16_f32 v52, v104, v105
	v_cvt_pk_bf16_f32 v53, v102, v103
	global_store_dwordx4 v[56:57], v[50:53], off offset:256
	s_and_saveexec_b64 s[22:23], s[0:1]
	s_cbranch_execz .LBB0_1289
	s_waitcnt lgkmcnt(0)
	v_add_f32_e32 v50, v48, v49
	s_lshl_b32 s24, s6, 2
	v_lshlrev_b64 v[48:49], 6, v[100:101]
	s_ashr_i32 s25, s24, 31
	v_lshl_add_u64 v[48:49], s[10:11], 0, v[48:49]
	v_lshl_add_u64 v[48:49], s[24:25], 2, v[48:49]
	s_lshl_b32 s8, s37, 2
	v_lshl_add_u64 v[48:49], v[48:49], 0, s[8:9]
	global_store_dword v[48:49], v50, off
.LBB0_1289:
	s_or_b64 exec, exec, s[22:23]
	s_nop 0
	v_lshlrev_b32_e32 v48, 16, v84
	s_waitcnt lgkmcnt(0)
	v_and_b32_e32 v49, 0xffff0000, v84
	v_lshlrev_b32_e32 v52, 16, v86
	v_and_b32_e32 v53, 0xffff0000, v86
	v_lshlrev_b32_e32 v54, 16, v87
	v_and_b32_e32 v55, 0xffff0000, v87
	v_pk_add_f32 v[44:45], v[44:45], v[48:49]
	v_lshlrev_b32_e32 v50, 16, v85
	v_and_b32_e32 v51, 0xffff0000, v85
	v_pk_add_f32 v[48:49], v[42:43], v[54:55]
	v_pk_add_f32 v[42:43], v[40:41], v[52:53]
	v_mul_f32_e32 v52, v45, v45
	v_pk_add_f32 v[46:47], v[46:47], v[50:51]
	v_fmac_f32_e32 v52, v44, v44
	v_fmac_f32_e32 v52, v46, v46
	v_fmac_f32_e32 v52, v47, v47
	v_fmac_f32_e32 v52, v42, v42
	v_fmac_f32_e32 v52, v43, v43
	v_fmac_f32_e32 v52, v48, v48
	v_cvt_pk_bf16_f32 v40, v44, v45
	s_nop 0
	v_lshlrev_b32_e32 v44, 16, v80
	v_and_b32_e32 v45, 0xffff0000, v80
	v_fmac_f32_e32 v52, v49, v49
	v_cvt_pk_bf16_f32 v41, v46, v47
	v_cvt_pk_bf16_f32 v42, v42, v43
	v_cvt_pk_bf16_f32 v43, v48, v49
	v_lshlrev_b32_e32 v46, 16, v81
	v_and_b32_e32 v47, 0xffff0000, v81
	v_lshlrev_b32_e32 v48, 16, v82
	v_and_b32_e32 v49, 0xffff0000, v82
	v_pk_add_f32 v[36:37], v[36:37], v[44:45]
	v_pk_add_f32 v[38:39], v[38:39], v[46:47]
	v_pk_add_f32 v[46:47], v[32:33], v[48:49]
	v_mul_f32_e32 v32, v37, v37
	v_fmac_f32_e32 v32, v36, v36
	v_fmac_f32_e32 v32, v38, v38
	v_fmac_f32_e32 v32, v39, v39
	v_lshlrev_b32_e32 v50, 16, v83
	v_and_b32_e32 v51, 0xffff0000, v83
	v_fmac_f32_e32 v32, v46, v46
	v_pk_add_f32 v[44:45], v[34:35], v[50:51]
	v_fmac_f32_e32 v32, v47, v47
	v_fmac_f32_e32 v32, v44, v44
	v_fmac_f32_e32 v32, v45, v45
	v_add_f32_e32 v35, v52, v32
	ds_bpermute_b32 v50, v195, v35
	v_lshl_add_u64 v[32:33], s[76:77], 0, v[98:99]
	v_lshl_add_u64 v[48:49], v[170:171], 1, v[32:33]
	v_cvt_pk_bf16_f32 v34, v36, v37
	v_cvt_pk_bf16_f32 v36, v46, v47
	s_waitcnt lgkmcnt(0)
	v_add_f32_e32 v32, v35, v50
	ds_bpermute_b32 v33, v194, v32
	v_cvt_pk_bf16_f32 v35, v38, v39
	v_cvt_pk_bf16_f32 v37, v44, v45
	global_store_dwordx4 v[48:49], v[40:43], off
	global_store_dwordx4 v[48:49], v[34:37], off offset:256
	s_and_saveexec_b64 s[22:23], s[0:1]
	s_cbranch_execz .LBB0_1291
	s_waitcnt lgkmcnt(0)
	v_add_f32_e32 v34, v32, v33
	s_lshl_b32 s24, s6, 2
	v_lshlrev_b64 v[32:33], 6, v[96:97]
	s_ashr_i32 s25, s24, 31
	v_lshl_add_u64 v[32:33], s[10:11], 0, v[32:33]
	v_lshl_add_u64 v[32:33], s[24:25], 2, v[32:33]
	s_lshl_b32 s8, s37, 2
	v_lshl_add_u64 v[32:33], v[32:33], 0, s[8:9]
	global_store_dword v[32:33], v34, off
; __device__ __forceinline__ unsigned pk2(float lo, float hi) { const f32x2 v = (f32x2){lo, hi}; const bf16x2_t b = __builtin_convertvector(v, bf16x2_t); return __builtin_bit_cast(unsigned, b); }
; __device__ __forceinline__ void unpack8(const u32x4 v, float* f) { f[0] = bf_lo(v.x); f[1] = bf_hi(v.x); f[2] = bf_lo(v.y); f[3] = bf_hi(v.y); f[4] = bf_lo(v.z); f[5] = bf_hi(v.z); f[6] = bf_lo(v.w); f[7] = bf_hi(v.w); }
;     __device__ __forceinline__ void operator()(const f32x4 (&acc)[2][2][4][2], const Unit& u, int wr, int wc, int fr, int fq, const float (&)[8]) const {
;     ...
;             for (int m = 0; m < 4; ++m) { const int row = row0 + ai * HALF + m * 16; const size_t ro = (size_t)row * DM + col0; float s = 0.f;
; #pragma unroll
;                 for (int bj = 0; bj < 2; ++bj) { float b8[8]; unpack8(bv[m][bj], b8);
;                     const f32x4 v0 = (f32x4){b8[0], b8[1], b8[2], b8[3]} + acc[ai][bj][m][0], v1 = (f32x4){b8[4], b8[5], b8[6], b8[7]} + acc[ai][bj][m][1];
;                     s += v0[0] * v0[0] + v0[1] * v0[1] + v0[2] * v0[2] + v0[3] * v0[3] + v1[0] * v1[0] + v1[1] * v1[1] + v1[2] * v1[2] + v1[3] * v1[3];
;                     if (LAST) { *(f32x4*)(out + ro + bj * HALF) = v0; *(f32x4*)(out + ro + bj * HALF + 4) = v1; }
;                     else { u32x4 w; w.x = pk2(v0[0], v0[1]); w.y = pk2(v0[2], v0[3]); w.z = pk2(v1[0], v1[1]); w.w = pk2(v1[2], v1[3]); *(u32x4*)(xb + ro + bj * HALF) = w; } }
;                 s += __shfl_xor(s, 16); s += __shfl_xor(s, 32);
;                 if (fq == 0) ss[(size_t)row * 16 + u.pn * 4 + wc] = s; }
.LBB0_1291:
	s_or_b64 exec, exec, s[22:23]
	s_nop 0
	v_lshlrev_b32_e32 v32, 16, v76
	s_waitcnt lgkmcnt(0)
	v_and_b32_e32 v33, 0xffff0000, v76
	v_lshlrev_b32_e32 v36, 16, v78
	v_and_b32_e32 v37, 0xffff0000, v78
	v_lshlrev_b32_e32 v38, 16, v79
	v_and_b32_e32 v39, 0xffff0000, v79
	v_pk_add_f32 v[28:29], v[28:29], v[32:33]
	v_lshlrev_b32_e32 v34, 16, v77
	v_and_b32_e32 v35, 0xffff0000, v77
	v_pk_add_f32 v[32:33], v[26:27], v[38:39]
	v_pk_add_f32 v[26:27], v[24:25], v[36:37]
	v_mul_f32_e32 v36, v29, v29
	v_pk_add_f32 v[30:31], v[30:31], v[34:35]
	v_fmac_f32_e32 v36, v28, v28
	v_fmac_f32_e32 v36, v30, v30
	v_fmac_f32_e32 v36, v31, v31
	v_fmac_f32_e32 v36, v26, v26
	v_fmac_f32_e32 v36, v27, v27
	v_fmac_f32_e32 v36, v32, v32
	v_cvt_pk_bf16_f32 v24, v28, v29
	s_nop 0
	v_lshlrev_b32_e32 v28, 16, v72
	v_and_b32_e32 v29, 0xffff0000, v72
	v_fmac_f32_e32 v36, v33, v33
	v_cvt_pk_bf16_f32 v25, v30, v31
	v_cvt_pk_bf16_f32 v26, v26, v27
	v_cvt_pk_bf16_f32 v27, v32, v33
	v_lshlrev_b32_e32 v30, 16, v73
	v_and_b32_e32 v31, 0xffff0000, v73
	v_lshlrev_b32_e32 v32, 16, v74
	v_and_b32_e32 v33, 0xffff0000, v74
	v_pk_add_f32 v[20:21], v[20:21], v[28:29]
	v_pk_add_f32 v[22:23], v[22:23], v[30:31]
	v_pk_add_f32 v[30:31], v[16:17], v[32:33]
	v_mul_f32_e32 v16, v21, v21
	v_fmac_f32_e32 v16, v20, v20
	v_fmac_f32_e32 v16, v22, v22
	v_fmac_f32_e32 v16, v23, v23
	v_lshlrev_b32_e32 v34, 16, v75
	v_and_b32_e32 v35, 0xffff0000, v75
	v_fmac_f32_e32 v16, v30, v30
	v_pk_add_f32 v[28:29], v[18:19], v[34:35]
	v_fmac_f32_e32 v16, v31, v31
	v_fmac_f32_e32 v16, v28, v28
	v_fmac_f32_e32 v16, v29, v29
	v_add_f32_e32 v19, v36, v16
	ds_bpermute_b32 v34, v195, v19
	v_lshl_add_u64 v[16:17], s[76:77], 0, v[94:95]
	v_lshl_add_u64 v[32:33], v[170:171], 1, v[16:17]
	v_cvt_pk_bf16_f32 v18, v20, v21
	v_cvt_pk_bf16_f32 v20, v30, v31
	s_waitcnt lgkmcnt(0)
	v_add_f32_e32 v16, v19, v34
	ds_bpermute_b32 v17, v194, v16
	v_cvt_pk_bf16_f32 v19, v22, v23
	v_cvt_pk_bf16_f32 v21, v28, v29
	global_store_dwordx4 v[32:33], v[24:27], off
	global_store_dwordx4 v[32:33], v[18:21], off offset:256
	s_and_saveexec_b64 s[22:23], s[0:1]
	s_cbranch_execz .LBB0_1293
	s_waitcnt lgkmcnt(0)
	v_add_f32_e32 v18, v16, v17
	s_lshl_b32 s24, s6, 2
	v_lshlrev_b64 v[16:17], 6, v[92:93]
	s_ashr_i32 s25, s24, 31
	v_lshl_add_u64 v[16:17], s[10:11], 0, v[16:17]
	v_lshl_add_u64 v[16:17], s[24:25], 2, v[16:17]
	s_lshl_b32 s8, s37, 2
	v_lshl_add_u64 v[16:17], v[16:17], 0, s[8:9]
	global_store_dword v[16:17], v18, off
.LBB0_1293:
	s_or_b64 exec, exec, s[22:23]
	s_nop 0
	v_lshlrev_b32_e32 v16, 16, v68
	s_waitcnt lgkmcnt(0)
	v_and_b32_e32 v17, 0xffff0000, v68
	v_lshlrev_b32_e32 v20, 16, v70
	v_and_b32_e32 v21, 0xffff0000, v70
	v_lshlrev_b32_e32 v22, 16, v71
	v_and_b32_e32 v23, 0xffff0000, v71
	v_pk_add_f32 v[12:13], v[12:13], v[16:17]
	v_lshlrev_b32_e32 v18, 16, v69
	v_and_b32_e32 v19, 0xffff0000, v69
	v_pk_add_f32 v[16:17], v[10:11], v[22:23]
	v_pk_add_f32 v[10:11], v[8:9], v[20:21]
	v_mul_f32_e32 v20, v13, v13
	v_pk_add_f32 v[14:15], v[14:15], v[18:19]
	v_fmac_f32_e32 v20, v12, v12
	v_fmac_f32_e32 v20, v14, v14
	v_fmac_f32_e32 v20, v15, v15
	v_fmac_f32_e32 v20, v10, v10
	v_fmac_f32_e32 v20, v11, v11
	v_fmac_f32_e32 v20, v16, v16
	v_cvt_pk_bf16_f32 v8, v12, v13
	s_nop 0
	v_lshlrev_b32_e32 v12, 16, v64
	v_and_b32_e32 v13, 0xffff0000, v64
	v_fmac_f32_e32 v20, v17, v17
	v_cvt_pk_bf16_f32 v9, v14, v15
	v_cvt_pk_bf16_f32 v10, v10, v11
	v_cvt_pk_bf16_f32 v11, v16, v17
	v_lshlrev_b32_e32 v14, 16, v65
	v_and_b32_e32 v15, 0xffff0000, v65
	v_lshlrev_b32_e32 v16, 16, v66
	v_and_b32_e32 v17, 0xffff0000, v66
	v_pk_add_f32 v[4:5], v[4:5], v[12:13]
	v_pk_add_f32 v[6:7], v[6:7], v[14:15]
	v_pk_add_f32 v[14:15], v[0:1], v[16:17]
	v_mul_f32_e32 v0, v5, v5
	v_fmac_f32_e32 v0, v4, v4
	v_fmac_f32_e32 v0, v6, v6
	v_fmac_f32_e32 v0, v7, v7
	v_lshlrev_b32_e32 v18, 16, v67
	v_and_b32_e32 v19, 0xffff0000, v67
	v_fmac_f32_e32 v0, v14, v14
	v_pk_add_f32 v[12:13], v[2:3], v[18:19]
	v_fmac_f32_e32 v0, v15, v15
	v_fmac_f32_e32 v0, v12, v12
	v_fmac_f32_e32 v0, v13, v13
	v_add_f32_e32 v3, v20, v0
	ds_bpermute_b32 v18, v195, v3
	v_lshl_add_u64 v[0:1], s[76:77], 0, v[90:91]
	v_lshl_add_u64 v[16:17], v[170:171], 1, v[0:1]
	v_cvt_pk_bf16_f32 v2, v4, v5
	v_cvt_pk_bf16_f32 v4, v14, v15
	s_waitcnt lgkmcnt(0)
	v_add_f32_e32 v0, v3, v18
	ds_bpermute_b32 v1, v194, v0
	v_cvt_pk_bf16_f32 v3, v6, v7
	v_cvt_pk_bf16_f32 v5, v12, v13
	global_store_dwordx4 v[16:17], v[8:11], off
	global_store_dwordx4 v[16:17], v[2:5], off offset:256
	s_and_saveexec_b64 s[22:23], s[0:1]
	s_cbranch_execz .LBB0_1270
	s_waitcnt lgkmcnt(0)
	v_add_f32_e32 v2, v0, v1
	s_lshl_b32 s24, s6, 2
	v_lshlrev_b64 v[0:1], 6, v[88:89]
	s_ashr_i32 s25, s24, 31
	v_lshl_add_u64 v[0:1], s[10:11], 0, v[0:1]
	v_lshl_add_u64 v[0:1], s[24:25], 2, v[0:1]
	s_lshl_b32 s8, s37, 2
	v_lshl_add_u64 v[0:1], v[0:1], 0, s[8:9]
	global_store_dword v[0:1], v2, off
	s_branch .LBB0_1270

; template <bool COOP>
; __global__ void __launch_bounds__(512, 2) mega(Args A) {
;     extern __shared__ __attribute__((aligned(16))) unsigned char smem[];
	.amdhsa_kernel _Z4megaILb1EEv4Args
		.amdhsa_group_segment_fixed_size 4096
		.amdhsa_private_segment_fixed_size 0
		.amdhsa_kernarg_size 472
		.amdhsa_user_sgpr_count 2
		.amdhsa_user_sgpr_dispatch_ptr 0
		.amdhsa_user_sgpr_queue_ptr 0
		.amdhsa_user_sgpr_kernarg_segment_ptr 1
		.amdhsa_user_sgpr_dispatch_id 0
		.amdhsa_user_sgpr_kernarg_preload_length 0
		.amdhsa_user_sgpr_kernarg_preload_offset 0
		.amdhsa_user_sgpr_private_segment_size 0
		.amdhsa_uses_dynamic_stack 0
		.amdhsa_enable_private_segment 0
		.amdhsa_system_sgpr_workgroup_id_x 1
		.amdhsa_system_sgpr_workgroup_id_y 0
		.amdhsa_system_sgpr_workgroup_id_z 0
		.amdhsa_system_sgpr_workgroup_info 0
		.amdhsa_system_vgpr_workitem_id 2
		.amdhsa_next_free_vgpr 256
		.amdhsa_next_free_sgpr 98
		.amdhsa_accum_offset 256
		.amdhsa_reserve_vcc 1
		.amdhsa_float_round_mode_32 0
		.amdhsa_float_round_mode_16_64 0
		.amdhsa_float_denorm_mode_32 3
		.amdhsa_float_denorm_mode_16_64 3
		.amdhsa_dx10_clamp 1
		.amdhsa_ieee_mode 1
		.amdhsa_fp16_overflow 0
		.amdhsa_tg_split 0
		.amdhsa_exception_fp_ieee_invalid_op 0
		.amdhsa_exception_fp_denorm_src 0
		.amdhsa_exception_fp_ieee_div_zero 0
		.amdhsa_exception_fp_ieee_overflow 0
		.amdhsa_exception_fp_ieee_underflow 0
		.amdhsa_exception_fp_ieee_inexact 0
		.amdhsa_exception_int_div_zero 0
	.end_amdhsa_kernel

; template <bool COOP>
; __global__ void __launch_bounds__(512, 2) mega(Args A) {
;     extern __shared__ __attribute__((aligned(16))) unsigned char smem[];
amdhsa.kernels:
  - .agpr_count:     0
    .args:
      - .offset:         0
        .size:           216
        .value_kind:     by_value
      - .offset:         216
        .size:           4
        .value_kind:     hidden_block_count_x
      - .offset:         220
        .size:           4
        .value_kind:     hidden_block_count_y
      - .offset:         224
        .size:           4
        .value_kind:     hidden_block_count_z
      - .offset:         228
        .size:           2
        .value_kind:     hidden_group_size_x
      - .offset:         230
        .size:           2
        .value_kind:     hidden_group_size_y
      - .offset:         232
        .size:           2
        .value_kind:     hidden_group_size_z
      - .offset:         234
        .size:           2
        .value_kind:     hidden_remainder_x
      - .offset:         236
        .size:           2
        .value_kind:     hidden_remainder_y
      - .offset:         238
        .size:           2
        .value_kind:     hidden_remainder_z
      - .offset:         256
        .size:           8
        .value_kind:     hidden_global_offset_x
      - .offset:         264
        .size:           8
        .value_kind:     hidden_global_offset_y
      - .offset:         272
        .size:           8
        .value_kind:     hidden_global_offset_z
      - .offset:         280
        .size:           2
        .value_kind:     hidden_grid_dims
      - .offset:         304
        .size:           8
        .value_kind:     hidden_multigrid_sync_arg
      - .offset:         336
        .size:           4
        .value_kind:     hidden_dynamic_lds_size
    .group_segment_fixed_size: 4096
    .kernarg_segment_align: 8
    .kernarg_segment_size: 472
    .language:       OpenCL C
    .language_version:
      - 2
      - 0
    .max_flat_workgroup_size: 512
    .name:           _Z4megaILb1EEv4Args
    .private_segment_fixed_size: 0
    .sgpr_count:     104
    .sgpr_spill_count: 86
    .symbol:         _Z4megaILb1EEv4Args.kd
    .uniform_work_group_size: 1
    .uses_dynamic_stack: false
    .vgpr_count:     256
    .vgpr_spill_count: 0
    .wavefront_size: 64
